# S1 load segment trimmed: 7 scalar ops moved into the following MFMA stream, 2 LDS-DMA use sgpr-base form (no 64-bit VALU add)
# speedup vs baseline: 1.0014x; 1.0014x over previous
; #define PG8_STAGE(bufoff, gbase, VO) do { _Pragma("unroll") for (int _i = 0; _i < 2; ++_i) \
;         __builtin_amdgcn_global_load_lds((const unsigned*)((const char*)(gbase) + VO[_i]), (LAS unsigned*)(lds + (bufoff) + ldsw + _i * 8192), 16, 0, 0); } while (0)
; #define PG8_LDA(dst, b, h) do { _Pragma("unroll") for (int m = 0; m < 4; ++m) _Pragma("unroll") for (int k = 0; k < 2; ++k) dst[m][k] = *(const LAS bf16x8*)(lds + PG8_SA(b, h) + aoff + m * 2048 + k * 1024); } while (0)
; #define PG8_LDB(dst, b, h) do { _Pragma("unroll") for (int n = 0; n < 2; ++n) _Pragma("unroll") for (int k = 0; k < 2; ++k) dst[n][k] = *(const LAS bf16x8*)(lds + PG8_SB(b, h) + boff + n * 2048 + k * 1024); } while (0)
; #define PG8_MMA(ai, bj, At, Bt) do { __builtin_amdgcn_s_setprio(1); _Pragma("unroll") for (int m = 0; m < 4; ++m) _Pragma("unroll") for (int n = 0; n < 2; ++n) _Pragma("unroll") for (int k = 0; k < 2; ++k) \
;         acc[ai][bj][m][n] = __builtin_amdgcn_mfma_f32_16x16x32_bf16(Bt[n][k], At[m][k], acc[ai][bj][m][n], 0, 0, 0); __builtin_amdgcn_s_setprio(0); } while (0)
; #define PG8_WAIT_V(n) asm volatile("s_waitcnt vmcnt(" #n ")" ::: "memory")
; #define PG8_WAIT_L(n) asm volatile("s_waitcnt lgkmcnt(" #n ")" ::: "memory")
; #define PG8_BAR __builtin_amdgcn_s_barrier()
; #define PG8_SCHED __builtin_amdgcn_sched_barrier(0)
; template <int NSEG, class Epi, bool ALIGN_EPI = PG8_ALIGN, bool SP2 = PG8_SP2>
; DI void gemm_phase(LAS unsigned char* lds, const Gemm g, const StaticOrder& S, const Epi& E) {
;     ...
;             PG8_LDB(B0, 0, 0); PG8_LDB(B1, 0, 1); PG8_SCHED; PG8_LDA(At, 0, 0); PG8_STAGE(PG8_SA(1, 1), a1 + hstepC, voffC);
;             PG8_WAIT_V(8); PG8_WAIT_L(0); PG8_BAR; PG8_MMA(0, 0, At, B0); PG8_MMA(0, 1, At, B1); PG8_BAR; PG8_SCHED;
;             PG8_LDA(At, 0, 1); PG8_STAGE(PG8_SB(0, 0), b2, v2); PG8_STAGE(PG8_SB(0, 1), b2 + h2, v2); PG8_STAGE(PG8_SA(0, 0), a2, v2);
.LBB0_139:
	v_add_u32_e32 v134, s62, v157
	ds_read_b128 v[144:147], v178
	ds_read_b128 v[148:151], v178 offset:1024
	ds_read_b128 v[152:155], v178 offset:2048
	ds_read_b128 v[182:185], v178 offset:3072
	ds_read_b128 v[186:189], v134
	ds_read_b128 v[190:193], v134 offset:1024
	ds_read_b128 v[194:197], v134 offset:2048
	ds_read_b128 v[198:201], v134 offset:3072
	s_add_i32 m0, s45, 0xc000
	ds_read_b128 v[202:205], v179
	ds_read_b128 v[206:209], v179 offset:1024
	ds_read_b128 v[210:213], v179 offset:2048
	ds_read_b128 v[214:217], v179 offset:3072
	ds_read_b128 v[218:221], v179 offset:4096
	ds_read_b128 v[222:225], v179 offset:5120
	ds_read_b128 v[226:229], v179 offset:6144
	ds_read_b128 v[230:233], v179 offset:7168
	global_load_lds_dwordx4 v136, s[34:35]
	s_add_i32 m0, s45, 0xe000
	s_nop 0
	global_load_lds_dwordx4 v138, s[34:35]
	s_waitcnt vmcnt(8)
	s_waitcnt lgkmcnt(0)
	s_setprio 1
	s_barrier
	v_mfma_f32_16x16x32_bf16 v[126:129], v[144:147], v[202:205], v[126:129]
	v_mfma_f32_16x16x32_bf16 v[122:125], v[152:155], v[202:205], v[122:125]
	s_add_u32 s36, s34, 0xfff80080
	s_addc_u32 s37, s35, -1
	v_mfma_f32_16x16x32_bf16 v[110:113], v[144:147], v[210:213], v[110:113]
	v_mfma_f32_16x16x32_bf16 v[106:109], v[152:155], v[210:213], v[106:109]
	s_cmp_eq_u32 s72, 28
	s_cselect_b32 s41, s3, s37
	v_mfma_f32_16x16x32_bf16 v[94:97], v[144:147], v[218:221], v[94:97]
	v_mfma_f32_16x16x32_bf16 v[90:93], v[152:155], v[218:221], v[90:93]
	s_cselect_b32 s40, s25, s36
	s_cselect_b32 s37, s27, s71
	v_mfma_f32_16x16x32_bf16 v[78:81], v[144:147], v[226:229], v[78:81]
	v_mfma_f32_16x16x32_bf16 v[74:77], v[152:155], v[226:229], v[74:77]
	s_cselect_b32 s36, s69, s70
	v_mfma_f32_16x16x32_bf16 v[126:129], v[148:151], v[206:209], v[126:129]
	v_mfma_f32_16x16x32_bf16 v[122:125], v[182:185], v[206:209], v[122:125]
	v_mfma_f32_16x16x32_bf16 v[110:113], v[148:151], v[214:217], v[110:113]
	v_mfma_f32_16x16x32_bf16 v[106:109], v[182:185], v[214:217], v[106:109]
	v_mfma_f32_16x16x32_bf16 v[94:97], v[148:151], v[222:225], v[94:97]
	v_mfma_f32_16x16x32_bf16 v[90:93], v[182:185], v[222:225], v[90:93]
	v_mfma_f32_16x16x32_bf16 v[78:81], v[148:151], v[230:233], v[78:81]
	v_mfma_f32_16x16x32_bf16 v[74:77], v[182:185], v[230:233], v[74:77]
	s_setprio 0
	s_setprio 1
	v_mfma_f32_16x16x32_bf16 v[118:121], v[186:189], v[202:205], v[118:121]
	v_mfma_f32_16x16x32_bf16 v[114:117], v[194:197], v[202:205], v[114:117]
	v_mfma_f32_16x16x32_bf16 v[102:105], v[186:189], v[210:213], v[102:105]
	v_mfma_f32_16x16x32_bf16 v[98:101], v[194:197], v[210:213], v[98:101]
	v_mfma_f32_16x16x32_bf16 v[86:89], v[186:189], v[218:221], v[86:89]
	v_mfma_f32_16x16x32_bf16 v[82:85], v[194:197], v[218:221], v[82:85]
	v_mfma_f32_16x16x32_bf16 v[70:73], v[186:189], v[226:229], v[70:73]
	v_mfma_f32_16x16x32_bf16 v[66:69], v[194:197], v[226:229], v[66:69]
	v_mfma_f32_16x16x32_bf16 v[118:121], v[190:193], v[206:209], v[118:121]
	v_mfma_f32_16x16x32_bf16 v[114:117], v[198:201], v[206:209], v[114:117]
	v_mfma_f32_16x16x32_bf16 v[102:105], v[190:193], v[214:217], v[102:105]
	v_mfma_f32_16x16x32_bf16 v[98:101], v[198:201], v[214:217], v[98:101]
	v_mfma_f32_16x16x32_bf16 v[86:89], v[190:193], v[222:225], v[86:89]
	v_mfma_f32_16x16x32_bf16 v[82:85], v[198:201], v[222:225], v[82:85]
	v_mfma_f32_16x16x32_bf16 v[70:73], v[190:193], v[230:233], v[70:73]
	v_mfma_f32_16x16x32_bf16 v[66:69], v[198:201], v[230:233], v[66:69]
	s_setprio 0
	s_barrier
	s_add_i32 s73, s61, s51
	v_lshl_add_u64 v[234:235], s[36:37], 0, v[130:131]
	s_mov_b32 m0, s73
	ds_read_b128 v[202:205], v179 offset:16384
	ds_read_b128 v[206:209], v179 offset:17408
	ds_read_b128 v[210:213], v179 offset:18432
	ds_read_b128 v[214:217], v179 offset:19456
	ds_read_b128 v[218:221], v179 offset:20480
	ds_read_b128 v[222:225], v179 offset:21504
	ds_read_b128 v[226:229], v179 offset:22528
	ds_read_b128 v[230:233], v179 offset:23552
	global_load_lds_dwordx4 v[234:235], off
	s_add_i32 m0, s73, 0x2000
	s_add_u32 s74, s36, 0x80000
	v_lshl_add_u64 v[236:237], s[36:37], 0, v[132:133]
	s_addc_u32 s75, s37, 0
	s_add_i32 s73, s62, s51
	global_load_lds_dwordx4 v[236:237], off
	v_lshl_add_u64 v[238:239], s[74:75], 0, v[130:131]
	s_mov_b32 m0, s73
	v_lshl_add_u64 v[240:241], s[40:41], 0, v[132:133]
	global_load_lds_dwordx4 v[238:239], off
	v_lshl_add_u64 v[238:239], s[74:75], 0, v[132:133]
	s_add_i32 m0, s73, 0x2000
	s_nop 0
	global_load_lds_dwordx4 v[238:239], off
	v_lshl_add_u64 v[238:239], s[40:41], 0, v[130:131]
	s_mov_b32 m0, s45
	s_nop 0
	global_load_lds_dwordx4 v[238:239], off
	s_mov_b32 m0, s54
	s_nop 0
	global_load_lds_dwordx4 v[240:241], off
	s_waitcnt vmcnt(8)
	s_waitcnt lgkmcnt(0)
	s_setprio 1
	s_barrier
; #define PG8_STAGE(bufoff, gbase, VO) do { _Pragma("unroll") for (int _i = 0; _i < 2; ++_i) \
;         __builtin_amdgcn_global_load_lds((const unsigned*)((const char*)(gbase) + VO[_i]), (LAS unsigned*)(lds + (bufoff) + ldsw + _i * 8192), 16, 0, 0); } while (0)
; #define PG8_LDA(dst, b, h) do { _Pragma("unroll") for (int m = 0; m < 4; ++m) _Pragma("unroll") for (int k = 0; k < 2; ++k) dst[m][k] = *(const LAS bf16x8*)(lds + PG8_SA(b, h) + aoff + m * 2048 + k * 1024); } while (0)
; #define PG8_LDB(dst, b, h) do { _Pragma("unroll") for (int n = 0; n < 2; ++n) _Pragma("unroll") for (int k = 0; k < 2; ++k) dst[n][k] = *(const LAS bf16x8*)(lds + PG8_SB(b, h) + boff + n * 2048 + k * 1024); } while (0)
; #define PG8_MMA(ai, bj, At, Bt) do { __builtin_amdgcn_s_setprio(1); _Pragma("unroll") for (int m = 0; m < 4; ++m) _Pragma("unroll") for (int n = 0; n < 2; ++n) _Pragma("unroll") for (int k = 0; k < 2; ++k) \
;         acc[ai][bj][m][n] = __builtin_amdgcn_mfma_f32_16x16x32_bf16(Bt[n][k], At[m][k], acc[ai][bj][m][n], 0, 0, 0); __builtin_amdgcn_s_setprio(0); } while (0)
; #define PG8_WAIT_V(n) asm volatile("s_waitcnt vmcnt(" #n ")" ::: "memory")
; #define PG8_WAIT_L(n) asm volatile("s_waitcnt lgkmcnt(" #n ")" ::: "memory")
; #define PG8_BAR __builtin_amdgcn_s_barrier()
; #define PG8_SCHED __builtin_amdgcn_sched_barrier(0)
; template <int NSEG, class Epi, bool ALIGN_EPI = PG8_ALIGN, bool SP2 = PG8_SP2>
; DI void gemm_phase(LAS unsigned char* lds, const Gemm g, const StaticOrder& S, const Epi& E) {
;     ...
;             PG8_WAIT_V(8); PG8_WAIT_L(0); PG8_BAR; PG8_MMA(1, 0, At, B0); PG8_MMA(1, 1, At, B1); PG8_BAR; PG8_SCHED;
;             PG8_LDB(B0, 1, 0); PG8_LDB(B1, 1, 1); PG8_SCHED; PG8_LDA(At, 1, 0); PG8_STAGE(PG8_SA(0, 1), a2 + h2, v2);
;             PG8_WAIT_V(8); PG8_WAIT_L(0); PG8_BAR; PG8_MMA(0, 0, At, B0); PG8_MMA(0, 1, At, B1); PG8_BAR; PG8_SCHED;
	v_mfma_f32_16x16x32_bf16 v[62:65], v[144:147], v[202:205], v[62:65]
	v_mfma_f32_16x16x32_bf16 v[58:61], v[152:155], v[202:205], v[58:61]
	v_mfma_f32_16x16x32_bf16 v[46:49], v[144:147], v[210:213], v[46:49]
	v_mfma_f32_16x16x32_bf16 v[42:45], v[152:155], v[210:213], v[42:45]
	v_mfma_f32_16x16x32_bf16 v[22:25], v[144:147], v[218:221], v[22:25]
	v_mfma_f32_16x16x32_bf16 v[18:21], v[152:155], v[218:221], v[18:21]
	v_mfma_f32_16x16x32_bf16 v[6:9], v[144:147], v[226:229], v[6:9]
	v_mfma_f32_16x16x32_bf16 v[2:5], v[152:155], v[226:229], v[2:5]
	v_mfma_f32_16x16x32_bf16 v[62:65], v[148:151], v[206:209], v[62:65]
	v_mfma_f32_16x16x32_bf16 v[58:61], v[182:185], v[206:209], v[58:61]
	v_mfma_f32_16x16x32_bf16 v[46:49], v[148:151], v[214:217], v[46:49]
	v_mfma_f32_16x16x32_bf16 v[42:45], v[182:185], v[214:217], v[42:45]
	v_mfma_f32_16x16x32_bf16 v[22:25], v[148:151], v[222:225], v[22:25]
	v_mfma_f32_16x16x32_bf16 v[18:21], v[182:185], v[222:225], v[18:21]
	v_mfma_f32_16x16x32_bf16 v[6:9], v[148:151], v[230:233], v[6:9]
	v_mfma_f32_16x16x32_bf16 v[2:5], v[182:185], v[230:233], v[2:5]
	s_setprio 0
	s_setprio 1
	v_mfma_f32_16x16x32_bf16 v[54:57], v[186:189], v[202:205], v[54:57]
	v_mfma_f32_16x16x32_bf16 v[50:53], v[194:197], v[202:205], v[50:53]
	v_mfma_f32_16x16x32_bf16 v[38:41], v[186:189], v[210:213], v[38:41]
	v_mfma_f32_16x16x32_bf16 v[26:29], v[194:197], v[210:213], v[26:29]
	v_mfma_f32_16x16x32_bf16 v[34:37], v[186:189], v[218:221], v[34:37]
	v_mfma_f32_16x16x32_bf16 v[30:33], v[194:197], v[218:221], v[30:33]
	v_mfma_f32_16x16x32_bf16 v[14:17], v[186:189], v[226:229], v[14:17]
	v_mfma_f32_16x16x32_bf16 v[10:13], v[194:197], v[226:229], v[10:13]
	v_mfma_f32_16x16x32_bf16 v[54:57], v[190:193], v[206:209], v[54:57]
	v_mfma_f32_16x16x32_bf16 v[50:53], v[198:201], v[206:209], v[50:53]
	v_mfma_f32_16x16x32_bf16 v[38:41], v[190:193], v[214:217], v[38:41]
	v_mfma_f32_16x16x32_bf16 v[26:29], v[198:201], v[214:217], v[26:29]
	v_mfma_f32_16x16x32_bf16 v[34:37], v[190:193], v[222:225], v[34:37]
	v_mfma_f32_16x16x32_bf16 v[30:33], v[198:201], v[222:225], v[30:33]
	v_mfma_f32_16x16x32_bf16 v[14:17], v[190:193], v[230:233], v[14:17]
	v_mfma_f32_16x16x32_bf16 v[10:13], v[198:201], v[230:233], v[10:13]
	s_setprio 0
	s_barrier
	s_add_i32 s73, 0, 0x18000
	v_add_u32_e32 v134, s73, v157
	s_add_i32 s74, 0, 0x1c000
	ds_read_b128 v[144:147], v134
	ds_read_b128 v[148:151], v134 offset:1024
	ds_read_b128 v[152:155], v134 offset:2048
	ds_read_b128 v[182:185], v134 offset:3072
	v_add_u32_e32 v134, s74, v157
	ds_read_b128 v[186:189], v134
	ds_read_b128 v[190:193], v134 offset:1024
	ds_read_b128 v[194:197], v134 offset:2048
	ds_read_b128 v[198:201], v134 offset:3072
	s_add_u32 s40, s40, 0x80000
	s_addc_u32 s41, s41, 0
	s_mov_b32 m0, s55
	v_lshl_add_u64 v[242:243], s[40:41], 0, v[130:131]
	ds_read_b128 v[202:205], v179 offset:32768
	ds_read_b128 v[206:209], v179 offset:33792
	ds_read_b128 v[210:213], v179 offset:34816
	ds_read_b128 v[214:217], v179 offset:35840
	ds_read_b128 v[218:221], v179 offset:36864
	ds_read_b128 v[222:225], v179 offset:37888
	ds_read_b128 v[226:229], v179 offset:38912
	ds_read_b128 v[230:233], v179 offset:39936
	global_load_lds_dwordx4 v[242:243], off
	v_lshl_add_u64 v[242:243], s[40:41], 0, v[132:133]
	s_mov_b32 m0, s56
	s_nop 0
	global_load_lds_dwordx4 v[242:243], off
	s_waitcnt vmcnt(8)
	s_waitcnt lgkmcnt(0)
	s_setprio 1
	s_barrier
	v_mfma_f32_16x16x32_bf16 v[126:129], v[144:147], v[202:205], v[126:129]
	v_mfma_f32_16x16x32_bf16 v[122:125], v[152:155], v[202:205], v[122:125]
	v_mfma_f32_16x16x32_bf16 v[110:113], v[144:147], v[210:213], v[110:113]
	v_mfma_f32_16x16x32_bf16 v[106:109], v[152:155], v[210:213], v[106:109]
	v_mfma_f32_16x16x32_bf16 v[94:97], v[144:147], v[218:221], v[94:97]
	v_mfma_f32_16x16x32_bf16 v[90:93], v[152:155], v[218:221], v[90:93]
	v_mfma_f32_16x16x32_bf16 v[78:81], v[144:147], v[226:229], v[78:81]
	v_mfma_f32_16x16x32_bf16 v[74:77], v[152:155], v[226:229], v[74:77]
	v_mfma_f32_16x16x32_bf16 v[126:129], v[148:151], v[206:209], v[126:129]
	v_mfma_f32_16x16x32_bf16 v[122:125], v[182:185], v[206:209], v[122:125]
	v_mfma_f32_16x16x32_bf16 v[110:113], v[148:151], v[214:217], v[110:113]
	v_mfma_f32_16x16x32_bf16 v[106:109], v[182:185], v[214:217], v[106:109]
	v_mfma_f32_16x16x32_bf16 v[94:97], v[148:151], v[222:225], v[94:97]
	v_mfma_f32_16x16x32_bf16 v[90:93], v[182:185], v[222:225], v[90:93]
	v_mfma_f32_16x16x32_bf16 v[78:81], v[148:151], v[230:233], v[78:81]
	v_mfma_f32_16x16x32_bf16 v[74:77], v[182:185], v[230:233], v[74:77]
	s_setprio 0
	s_setprio 1
	v_mfma_f32_16x16x32_bf16 v[118:121], v[186:189], v[202:205], v[118:121]
	v_mfma_f32_16x16x32_bf16 v[114:117], v[194:197], v[202:205], v[114:117]
	v_mfma_f32_16x16x32_bf16 v[102:105], v[186:189], v[210:213], v[102:105]
	v_mfma_f32_16x16x32_bf16 v[98:101], v[194:197], v[210:213], v[98:101]
	v_mfma_f32_16x16x32_bf16 v[86:89], v[186:189], v[218:221], v[86:89]
	v_mfma_f32_16x16x32_bf16 v[82:85], v[194:197], v[218:221], v[82:85]
	v_mfma_f32_16x16x32_bf16 v[70:73], v[186:189], v[226:229], v[70:73]
	v_mfma_f32_16x16x32_bf16 v[66:69], v[194:197], v[226:229], v[66:69]
	v_mfma_f32_16x16x32_bf16 v[118:121], v[190:193], v[206:209], v[118:121]
	v_mfma_f32_16x16x32_bf16 v[114:117], v[198:201], v[206:209], v[114:117]
	v_mfma_f32_16x16x32_bf16 v[102:105], v[190:193], v[214:217], v[102:105]
	v_mfma_f32_16x16x32_bf16 v[98:101], v[198:201], v[214:217], v[98:101]
	v_mfma_f32_16x16x32_bf16 v[86:89], v[190:193], v[222:225], v[86:89]
	v_mfma_f32_16x16x32_bf16 v[82:85], v[198:201], v[222:225], v[82:85]
	v_mfma_f32_16x16x32_bf16 v[70:73], v[190:193], v[230:233], v[70:73]
	v_mfma_f32_16x16x32_bf16 v[66:69], v[198:201], v[230:233], v[66:69]
	s_setprio 0
	s_barrier
; #define PG8_STAGE(bufoff, gbase, VO) do { _Pragma("unroll") for (int _i = 0; _i < 2; ++_i) \
;         __builtin_amdgcn_global_load_lds((const unsigned*)((const char*)(gbase) + VO[_i]), (LAS unsigned*)(lds + (bufoff) + ldsw + _i * 8192), 16, 0, 0); } while (0)
; #define PG8_LDA(dst, b, h) do { _Pragma("unroll") for (int m = 0; m < 4; ++m) _Pragma("unroll") for (int k = 0; k < 2; ++k) dst[m][k] = *(const LAS bf16x8*)(lds + PG8_SA(b, h) + aoff + m * 2048 + k * 1024); } while (0)
; #define PG8_MMA(ai, bj, At, Bt) do { __builtin_amdgcn_s_setprio(1); _Pragma("unroll") for (int m = 0; m < 4; ++m) _Pragma("unroll") for (int n = 0; n < 2; ++n) _Pragma("unroll") for (int k = 0; k < 2; ++k) \
;         acc[ai][bj][m][n] = __builtin_amdgcn_mfma_f32_16x16x32_bf16(Bt[n][k], At[m][k], acc[ai][bj][m][n], 0, 0, 0); __builtin_amdgcn_s_setprio(0); } while (0)
; #define PG8_WAIT_V(n) asm volatile("s_waitcnt vmcnt(" #n ")" ::: "memory")
; #define PG8_WAIT_L(n) asm volatile("s_waitcnt lgkmcnt(" #n ")" ::: "memory")
; #define PG8_BAR __builtin_amdgcn_s_barrier()
; #define PG8_SCHED __builtin_amdgcn_sched_barrier(0)
; template <int NSEG, class Epi, bool ALIGN_EPI = PG8_ALIGN, bool SP2 = PG8_SP2>
; DI void gemm_phase(LAS unsigned char* lds, const Gemm g, const StaticOrder& S, const Epi& E) {
;     ...
;             PG8_LDA(At, 1, 1); PG8_STAGE(PG8_SB(1, 0), b3, v2); PG8_STAGE(PG8_SB(1, 1), b3 + h2, v2); PG8_STAGE(PG8_SA(1, 0), a3, v2);
;             PG8_WAIT_V(8); PG8_WAIT_L(0); PG8_BAR; PG8_MMA(1, 0, At, B0); PG8_MMA(1, 1, At, B1); PG8_BAR; PG8_SCHED;
	s_add_i32 s40, s73, s51
	v_lshl_add_u64 v[234:235], v[234:235], 0, s[12:13]
	s_mov_b32 m0, s40
	ds_read_b128 v[202:205], v179 offset:49152
	ds_read_b128 v[206:209], v179 offset:50176
	ds_read_b128 v[210:213], v179 offset:51200
	ds_read_b128 v[214:217], v179 offset:52224
	ds_read_b128 v[218:221], v179 offset:53248
	ds_read_b128 v[222:225], v179 offset:54272
	ds_read_b128 v[226:229], v179 offset:55296
	ds_read_b128 v[230:233], v179 offset:56320
	global_load_lds_dwordx4 v[234:235], off
	s_add_i32 m0, s40, 0x2000
	s_add_u32 s36, s36, 0x80080
	v_lshl_add_u64 v[234:235], v[236:237], 0, s[12:13]
	s_addc_u32 s37, s37, 0
	s_add_i32 s40, s74, s51
	global_load_lds_dwordx4 v[234:235], off
	v_lshl_add_u64 v[234:235], s[36:37], 0, v[130:131]
	s_mov_b32 m0, s40
	s_nop 0
	global_load_lds_dwordx4 v[234:235], off
	v_lshl_add_u64 v[234:235], s[36:37], 0, v[132:133]
	s_add_i32 m0, s40, 0x2000
	s_nop 0
	global_load_lds_dwordx4 v[234:235], off
	v_lshl_add_u64 v[234:235], v[238:239], 0, s[12:13]
	s_mov_b32 m0, s57
	s_nop 0
	global_load_lds_dwordx4 v[234:235], off
	v_lshl_add_u64 v[234:235], v[240:241], 0, s[12:13]
	s_mov_b32 m0, s58
	s_nop 0
	global_load_lds_dwordx4 v[234:235], off
	s_waitcnt vmcnt(8)
	s_waitcnt lgkmcnt(0)
	s_setprio 1
	s_barrier
	v_mfma_f32_16x16x32_bf16 v[62:65], v[144:147], v[202:205], v[62:65]
	v_mfma_f32_16x16x32_bf16 v[58:61], v[152:155], v[202:205], v[58:61]
	v_mfma_f32_16x16x32_bf16 v[46:49], v[144:147], v[210:213], v[46:49]
	v_mfma_f32_16x16x32_bf16 v[42:45], v[152:155], v[210:213], v[42:45]
	v_mfma_f32_16x16x32_bf16 v[22:25], v[144:147], v[218:221], v[22:25]
	v_mfma_f32_16x16x32_bf16 v[18:21], v[152:155], v[218:221], v[18:21]
	v_mfma_f32_16x16x32_bf16 v[6:9], v[144:147], v[226:229], v[6:9]
	v_mfma_f32_16x16x32_bf16 v[2:5], v[152:155], v[226:229], v[2:5]
	v_mfma_f32_16x16x32_bf16 v[62:65], v[148:151], v[206:209], v[62:65]
	v_mfma_f32_16x16x32_bf16 v[58:61], v[182:185], v[206:209], v[58:61]
	v_mfma_f32_16x16x32_bf16 v[46:49], v[148:151], v[214:217], v[46:49]
	v_mfma_f32_16x16x32_bf16 v[42:45], v[182:185], v[214:217], v[42:45]
	v_mfma_f32_16x16x32_bf16 v[22:25], v[148:151], v[222:225], v[22:25]
	v_mfma_f32_16x16x32_bf16 v[18:21], v[182:185], v[222:225], v[18:21]
	v_mfma_f32_16x16x32_bf16 v[6:9], v[148:151], v[230:233], v[6:9]
	v_mfma_f32_16x16x32_bf16 v[2:5], v[182:185], v[230:233], v[2:5]
	s_setprio 0
	s_setprio 1
	v_mfma_f32_16x16x32_bf16 v[54:57], v[186:189], v[202:205], v[54:57]
	v_mfma_f32_16x16x32_bf16 v[50:53], v[194:197], v[202:205], v[50:53]
	v_mfma_f32_16x16x32_bf16 v[38:41], v[186:189], v[210:213], v[38:41]
	v_mfma_f32_16x16x32_bf16 v[26:29], v[194:197], v[210:213], v[26:29]
	v_mfma_f32_16x16x32_bf16 v[34:37], v[186:189], v[218:221], v[34:37]
	v_mfma_f32_16x16x32_bf16 v[30:33], v[194:197], v[218:221], v[30:33]
	v_mfma_f32_16x16x32_bf16 v[14:17], v[186:189], v[226:229], v[14:17]
	v_mfma_f32_16x16x32_bf16 v[10:13], v[194:197], v[226:229], v[10:13]
	v_mfma_f32_16x16x32_bf16 v[54:57], v[190:193], v[206:209], v[54:57]
	v_mfma_f32_16x16x32_bf16 v[50:53], v[198:201], v[206:209], v[50:53]
	v_mfma_f32_16x16x32_bf16 v[38:41], v[190:193], v[214:217], v[38:41]
	v_mfma_f32_16x16x32_bf16 v[26:29], v[198:201], v[214:217], v[26:29]
	v_mfma_f32_16x16x32_bf16 v[34:37], v[190:193], v[222:225], v[34:37]
	v_mfma_f32_16x16x32_bf16 v[30:33], v[198:201], v[222:225], v[30:33]
	v_mfma_f32_16x16x32_bf16 v[14:17], v[190:193], v[230:233], v[14:17]
	v_mfma_f32_16x16x32_bf16 v[10:13], v[198:201], v[230:233], v[10:13]
	s_setprio 0
	s_barrier
	s_add_i32 s72, s72, 2
	s_add_u32 s34, s34, 0x100
	s_addc_u32 s35, s35, 0
	s_add_u32 s70, s70, 0x100
	s_addc_u32 s71, s71, 0
	s_cmp_gt_u32 s72, 29
	s_cbranch_scc0 .LBB0_139
	s_and_b64 vcc, exec, s[14:15]
	s_cbranch_vccnz .LBB0_144
	v_lshl_add_u32 v144, s2, 8, v1
	s_cmp_gt_i32 s44, 15
	s_mov_b64 s[2:3], -1
	s_cbranch_scc1 .LBB0_145

; #define PG8_STAGE(bufoff, gbase, VO) do { _Pragma("unroll") for (int _i = 0; _i < 2; ++_i) \
;         __builtin_amdgcn_global_load_lds((const unsigned*)((const char*)(gbase) + VO[_i]), (LAS unsigned*)(lds + (bufoff) + ldsw + _i * 8192), 16, 0, 0); } while (0)
; #define PG8_LDA(dst, b, h) do { _Pragma("unroll") for (int m = 0; m < 4; ++m) _Pragma("unroll") for (int k = 0; k < 2; ++k) dst[m][k] = *(const LAS bf16x8*)(lds + PG8_SA(b, h) + aoff + m * 2048 + k * 1024); } while (0)
; #define PG8_LDB(dst, b, h) do { _Pragma("unroll") for (int n = 0; n < 2; ++n) _Pragma("unroll") for (int k = 0; k < 2; ++k) dst[n][k] = *(const LAS bf16x8*)(lds + PG8_SB(b, h) + boff + n * 2048 + k * 1024); } while (0)
; #define PG8_MMA(ai, bj, At, Bt) do { __builtin_amdgcn_s_setprio(1); _Pragma("unroll") for (int m = 0; m < 4; ++m) _Pragma("unroll") for (int n = 0; n < 2; ++n) _Pragma("unroll") for (int k = 0; k < 2; ++k) \
;         acc[ai][bj][m][n] = __builtin_amdgcn_mfma_f32_16x16x32_bf16(Bt[n][k], At[m][k], acc[ai][bj][m][n], 0, 0, 0); __builtin_amdgcn_s_setprio(0); } while (0)
; #define PG8_BAR __builtin_amdgcn_s_barrier()
; template <int NSEG, class Epi, bool ALIGN_EPI = PG8_ALIGN, bool SP2 = PG8_SP2>
; DI void gemm_phase(LAS unsigned char* lds, const Gemm g, const StaticOrder& S, const Epi& E) {
;     ...
;         for (int t = 0; t < nt; t += 2) {
;             const bool last = (t == nt - 2);
;             const char* a1 = cA + (size_t)(t + 1) * kstep;
;             const char* a2 = last ? nA : cA + (size_t)(t + 2) * kstep; const char* b2 = last ? nB : cB + (size_t)(t + 2) * kstep;
;             const char* a3 = a2 + kstep; const char* b3 = b2 + kstep;
;             unsigned v2[2]; v2[0] = (NSEG > 1 && last) ? voffN[0] : voffC[0]; v2[1] = (NSEG > 1 && last) ? voffN[1] : voffC[1];
;             const size_t h2 = (NSEG > 1 && last) ? hstepN : hstepC;
;             if constexpr (SP2) {
;             PG8_LDB(B0, 0, 0); PG8_LDB(B1, 0, 1); PG8_SCHED; PG8_LDA(At, 0, 0); PG8_STAGE(PG8_SA(1, 1), a1 + hstepC, voffC);
;             PG8_WAIT_V(8); PG8_WAIT_L(0); PG8_BAR; PG8_MMA(0, 0, At, B0); PG8_MMA(0, 1, At, B1); PG8_BAR; PG8_SCHED;
;             PG8_LDA(At, 0, 1); PG8_STAGE(PG8_SB(0, 0), b2, v2); PG8_STAGE(PG8_SB(0, 1), b2 + h2, v2); PG8_STAGE(PG8_SA(0, 0), a2, v2);
;             PG8_WAIT_V(8); PG8_WAIT_L(0); PG8_BAR; PG8_MMA(1, 0, At, B0); PG8_MMA(1, 1, At, B1); PG8_BAR; PG8_SCHED;
.LBB0_281:
	ds_read_b128 v[42:45], v250
	ds_read_b128 v[46:49], v250 offset:1024
	ds_read_b128 v[58:61], v250 offset:2048
	ds_read_b128 v[62:65], v250 offset:3072
	ds_read_b128 v[122:125], v251
	ds_read_b128 v[134:137], v251 offset:1024
	ds_read_b128 v[146:149], v251 offset:2048
	ds_read_b128 v[150:153], v251 offset:3072
	s_add_i32 m0, s37, 0xc000
	ds_read_b128 v[154:157], v252
	ds_read_b128 v[166:169], v252 offset:1024
	ds_read_b128 v[170:173], v252 offset:2048
	ds_read_b128 v[174:177], v252 offset:3072
	ds_read_b128 v[178:181], v252 offset:4096
	ds_read_b128 v[182:185], v252 offset:5120
	ds_read_b128 v[186:189], v252 offset:6144
	ds_read_b128 v[190:193], v252 offset:7168
	global_load_lds_dwordx4 v206, s[22:23]
	s_add_i32 m0, s37, 0xe000
	s_nop 0
	global_load_lds_dwordx4 v208, s[22:23]
	s_waitcnt vmcnt(8)
	s_waitcnt lgkmcnt(0)
	s_setprio 1
	s_barrier
	v_mfma_f32_16x16x32_bf16 v[162:165], v[42:45], v[154:157], v[162:165]
	v_mfma_f32_16x16x32_bf16 v[158:161], v[58:61], v[154:157], v[158:161]
	s_add_u32 s24, s22, 0xfff80080
	s_addc_u32 s25, s23, -1
	v_mfma_f32_16x16x32_bf16 v[130:133], v[42:45], v[170:173], v[130:133]
	v_mfma_f32_16x16x32_bf16 v[126:129], v[58:61], v[170:173], v[126:129]
	s_cmp_eq_u32 s56, 28
	s_cselect_b32 s27, s15, s25
	v_mfma_f32_16x16x32_bf16 v[110:113], v[42:45], v[178:181], v[110:113]
	v_mfma_f32_16x16x32_bf16 v[106:109], v[58:61], v[178:181], v[106:109]
	s_cselect_b32 s26, s17, s24
	s_cselect_b32 s25, s52, s55
	v_mfma_f32_16x16x32_bf16 v[94:97], v[42:45], v[186:189], v[94:97]
	v_mfma_f32_16x16x32_bf16 v[90:93], v[58:61], v[186:189], v[90:93]
	s_cselect_b32 s24, s53, s54
	v_mfma_f32_16x16x32_bf16 v[162:165], v[46:49], v[166:169], v[162:165]
	v_mfma_f32_16x16x32_bf16 v[158:161], v[62:65], v[166:169], v[158:161]
	v_mfma_f32_16x16x32_bf16 v[130:133], v[46:49], v[174:177], v[130:133]
	v_mfma_f32_16x16x32_bf16 v[126:129], v[62:65], v[174:177], v[126:129]
	v_mfma_f32_16x16x32_bf16 v[110:113], v[46:49], v[182:185], v[110:113]
	v_mfma_f32_16x16x32_bf16 v[106:109], v[62:65], v[182:185], v[106:109]
	v_mfma_f32_16x16x32_bf16 v[94:97], v[46:49], v[190:193], v[94:97]
	v_mfma_f32_16x16x32_bf16 v[90:93], v[62:65], v[190:193], v[90:93]
	s_setprio 0
	s_setprio 1
	v_mfma_f32_16x16x32_bf16 v[142:145], v[122:125], v[154:157], v[142:145]
	v_mfma_f32_16x16x32_bf16 v[138:141], v[146:149], v[154:157], v[138:141]
	v_mfma_f32_16x16x32_bf16 v[118:121], v[122:125], v[170:173], v[118:121]
	v_mfma_f32_16x16x32_bf16 v[114:117], v[146:149], v[170:173], v[114:117]
	v_mfma_f32_16x16x32_bf16 v[102:105], v[122:125], v[178:181], v[102:105]
	v_mfma_f32_16x16x32_bf16 v[98:101], v[146:149], v[178:181], v[98:101]
	v_mfma_f32_16x16x32_bf16 v[86:89], v[122:125], v[186:189], v[86:89]
	v_mfma_f32_16x16x32_bf16 v[82:85], v[146:149], v[186:189], v[82:85]
	v_mfma_f32_16x16x32_bf16 v[142:145], v[134:137], v[166:169], v[142:145]
	v_mfma_f32_16x16x32_bf16 v[138:141], v[150:153], v[166:169], v[138:141]
	v_mfma_f32_16x16x32_bf16 v[118:121], v[134:137], v[174:177], v[118:121]
	v_mfma_f32_16x16x32_bf16 v[114:117], v[150:153], v[174:177], v[114:117]
	v_mfma_f32_16x16x32_bf16 v[102:105], v[134:137], v[182:185], v[102:105]
	v_mfma_f32_16x16x32_bf16 v[98:101], v[150:153], v[182:185], v[98:101]
	v_mfma_f32_16x16x32_bf16 v[86:89], v[134:137], v[190:193], v[86:89]
	v_mfma_f32_16x16x32_bf16 v[82:85], v[150:153], v[190:193], v[82:85]
	s_setprio 0
	s_barrier
	s_add_i32 s57, s50, s36
	v_lshl_add_u64 v[194:195], s[24:25], 0, v[202:203]
	s_mov_b32 m0, s57
	ds_read_b128 v[154:157], v252 offset:16384
	ds_read_b128 v[166:169], v252 offset:17408
	ds_read_b128 v[170:173], v252 offset:18432
	ds_read_b128 v[174:177], v252 offset:19456
	ds_read_b128 v[178:181], v252 offset:20480
	ds_read_b128 v[182:185], v252 offset:21504
	ds_read_b128 v[186:189], v252 offset:22528
	ds_read_b128 v[190:193], v252 offset:23552
	global_load_lds_dwordx4 v[194:195], off
	s_add_i32 m0, s57, 0x2000
	s_add_u32 s58, s24, 0x80000
	v_lshl_add_u64 v[196:197], s[24:25], 0, v[204:205]
	s_addc_u32 s59, s25, 0
	s_add_i32 s57, s51, s36
	global_load_lds_dwordx4 v[196:197], off
	v_lshl_add_u64 v[198:199], s[58:59], 0, v[202:203]
	s_mov_b32 m0, s57
	v_lshl_add_u64 v[200:201], s[26:27], 0, v[204:205]
	global_load_lds_dwordx4 v[198:199], off
	v_lshl_add_u64 v[198:199], s[58:59], 0, v[204:205]
	s_add_i32 m0, s57, 0x2000
	s_nop 0
	global_load_lds_dwordx4 v[198:199], off
	v_lshl_add_u64 v[198:199], s[26:27], 0, v[202:203]
	s_mov_b32 m0, s37
	s_nop 0
	global_load_lds_dwordx4 v[198:199], off
	s_mov_b32 m0, s38
	s_nop 0
	global_load_lds_dwordx4 v[200:201], off
	s_waitcnt vmcnt(8)
	s_waitcnt lgkmcnt(0)
	s_setprio 1
	s_barrier
; #define PG8_STAGE(bufoff, gbase, VO) do { _Pragma("unroll") for (int _i = 0; _i < 2; ++_i) \
;         __builtin_amdgcn_global_load_lds((const unsigned*)((const char*)(gbase) + VO[_i]), (LAS unsigned*)(lds + (bufoff) + ldsw + _i * 8192), 16, 0, 0); } while (0)
; #define PG8_LDA(dst, b, h) do { _Pragma("unroll") for (int m = 0; m < 4; ++m) _Pragma("unroll") for (int k = 0; k < 2; ++k) dst[m][k] = *(const LAS bf16x8*)(lds + PG8_SA(b, h) + aoff + m * 2048 + k * 1024); } while (0)
; #define PG8_LDB(dst, b, h) do { _Pragma("unroll") for (int n = 0; n < 2; ++n) _Pragma("unroll") for (int k = 0; k < 2; ++k) dst[n][k] = *(const LAS bf16x8*)(lds + PG8_SB(b, h) + boff + n * 2048 + k * 1024); } while (0)
; #define PG8_MMA(ai, bj, At, Bt) do { __builtin_amdgcn_s_setprio(1); _Pragma("unroll") for (int m = 0; m < 4; ++m) _Pragma("unroll") for (int n = 0; n < 2; ++n) _Pragma("unroll") for (int k = 0; k < 2; ++k) \
;         acc[ai][bj][m][n] = __builtin_amdgcn_mfma_f32_16x16x32_bf16(Bt[n][k], At[m][k], acc[ai][bj][m][n], 0, 0, 0); __builtin_amdgcn_s_setprio(0); } while (0)
; #define PG8_WAIT_V(n) asm volatile("s_waitcnt vmcnt(" #n ")" ::: "memory")
; #define PG8_WAIT_L(n) asm volatile("s_waitcnt lgkmcnt(" #n ")" ::: "memory")
; #define PG8_BAR __builtin_amdgcn_s_barrier()
; #define PG8_SCHED __builtin_amdgcn_sched_barrier(0)
; template <int NSEG, class Epi, bool ALIGN_EPI = PG8_ALIGN, bool SP2 = PG8_SP2>
; DI void gemm_phase(LAS unsigned char* lds, const Gemm g, const StaticOrder& S, const Epi& E) {
;     ...
;             PG8_WAIT_V(8); PG8_WAIT_L(0); PG8_BAR; PG8_MMA(1, 0, At, B0); PG8_MMA(1, 1, At, B1); PG8_BAR; PG8_SCHED;
;             PG8_LDB(B0, 1, 0); PG8_LDB(B1, 1, 1); PG8_SCHED; PG8_LDA(At, 1, 0); PG8_STAGE(PG8_SA(0, 1), a2 + h2, v2);
;             PG8_WAIT_V(8); PG8_WAIT_L(0); PG8_BAR; PG8_MMA(0, 0, At, B0); PG8_MMA(0, 1, At, B1); PG8_BAR; PG8_SCHED;
	v_mfma_f32_16x16x32_bf16 v[78:81], v[42:45], v[154:157], v[78:81]
	v_mfma_f32_16x16x32_bf16 v[74:77], v[58:61], v[154:157], v[74:77]
	v_mfma_f32_16x16x32_bf16 v[54:57], v[42:45], v[170:173], v[54:57]
	v_mfma_f32_16x16x32_bf16 v[50:53], v[58:61], v[170:173], v[50:53]
	v_mfma_f32_16x16x32_bf16 v[30:33], v[42:45], v[178:181], v[30:33]
	v_mfma_f32_16x16x32_bf16 v[26:29], v[58:61], v[178:181], v[26:29]
	v_mfma_f32_16x16x32_bf16 v[14:17], v[42:45], v[186:189], v[14:17]
	v_mfma_f32_16x16x32_bf16 v[10:13], v[58:61], v[186:189], v[10:13]
	v_mfma_f32_16x16x32_bf16 v[78:81], v[46:49], v[166:169], v[78:81]
	v_mfma_f32_16x16x32_bf16 v[74:77], v[62:65], v[166:169], v[74:77]
	v_mfma_f32_16x16x32_bf16 v[54:57], v[46:49], v[174:177], v[54:57]
	v_mfma_f32_16x16x32_bf16 v[50:53], v[62:65], v[174:177], v[50:53]
	v_mfma_f32_16x16x32_bf16 v[30:33], v[46:49], v[182:185], v[30:33]
	v_mfma_f32_16x16x32_bf16 v[26:29], v[62:65], v[182:185], v[26:29]
	v_mfma_f32_16x16x32_bf16 v[14:17], v[46:49], v[190:193], v[14:17]
	v_mfma_f32_16x16x32_bf16 v[10:13], v[62:65], v[190:193], v[10:13]
	s_setprio 0
	s_setprio 1
	v_mfma_f32_16x16x32_bf16 v[38:41], v[122:125], v[170:173], v[38:41]
	v_mfma_f32_16x16x32_bf16 v[34:37], v[146:149], v[170:173], v[34:37]
	v_mfma_f32_16x16x32_bf16 v[22:25], v[122:125], v[178:181], v[22:25]
	v_mfma_f32_16x16x32_bf16 v[18:21], v[146:149], v[178:181], v[18:21]
	v_mfma_f32_16x16x32_bf16 v[6:9], v[122:125], v[186:189], v[6:9]
	v_mfma_f32_16x16x32_bf16 v[2:5], v[146:149], v[186:189], v[2:5]
	v_mfma_f32_16x16x32_bf16 v[42:45], v[122:125], v[154:157], v[70:73]
	v_mfma_f32_16x16x32_bf16 v[46:49], v[146:149], v[154:157], v[66:69]
	v_mfma_f32_16x16x32_bf16 v[38:41], v[134:137], v[174:177], v[38:41]
	v_mfma_f32_16x16x32_bf16 v[34:37], v[150:153], v[174:177], v[34:37]
	v_mfma_f32_16x16x32_bf16 v[22:25], v[134:137], v[182:185], v[22:25]
	v_mfma_f32_16x16x32_bf16 v[18:21], v[150:153], v[182:185], v[18:21]
	v_mfma_f32_16x16x32_bf16 v[6:9], v[134:137], v[190:193], v[6:9]
	v_mfma_f32_16x16x32_bf16 v[2:5], v[150:153], v[190:193], v[2:5]
	v_mfma_f32_16x16x32_bf16 v[42:45], v[134:137], v[166:169], v[42:45]
	v_mfma_f32_16x16x32_bf16 v[46:49], v[150:153], v[166:169], v[46:49]
	s_setprio 0
	s_barrier
	s_add_i32 s57, 0, 0x18000
	s_add_i32 s58, 0, 0x1c000
	v_add_u32_e32 v70, s57, v248
	v_add_u32_e32 v150, s58, v248
	ds_read_b128 v[58:61], v70
	ds_read_b128 v[62:65], v70 offset:1024
	ds_read_b128 v[66:69], v70 offset:2048
	ds_read_b128 v[70:73], v70 offset:3072
	ds_read_b128 v[122:125], v150
	ds_read_b128 v[134:137], v150 offset:1024
	ds_read_b128 v[146:149], v150 offset:2048
	ds_read_b128 v[150:153], v150 offset:3072
	s_add_u32 s26, s26, 0x80000
	s_addc_u32 s27, s27, 0
	s_mov_b32 m0, s39
	v_lshl_add_u64 v[212:213], s[26:27], 0, v[202:203]
	ds_read_b128 v[154:157], v252 offset:32768
	ds_read_b128 v[166:169], v252 offset:33792
	ds_read_b128 v[170:173], v252 offset:34816
	ds_read_b128 v[174:177], v252 offset:35840
	ds_read_b128 v[178:181], v252 offset:36864
	ds_read_b128 v[182:185], v252 offset:37888
	ds_read_b128 v[186:189], v252 offset:38912
	ds_read_b128 v[190:193], v252 offset:39936
	global_load_lds_dwordx4 v[212:213], off
	v_lshl_add_u64 v[212:213], s[26:27], 0, v[204:205]
	s_mov_b32 m0, s40
	s_nop 0
	global_load_lds_dwordx4 v[212:213], off
	s_waitcnt vmcnt(8)
	s_waitcnt lgkmcnt(0)
	s_setprio 1
	s_barrier
	v_mfma_f32_16x16x32_bf16 v[162:165], v[58:61], v[154:157], v[162:165]
	v_mfma_f32_16x16x32_bf16 v[158:161], v[66:69], v[154:157], v[158:161]
	v_mfma_f32_16x16x32_bf16 v[130:133], v[58:61], v[170:173], v[130:133]
	v_mfma_f32_16x16x32_bf16 v[126:129], v[66:69], v[170:173], v[126:129]
	v_mfma_f32_16x16x32_bf16 v[110:113], v[58:61], v[178:181], v[110:113]
	v_mfma_f32_16x16x32_bf16 v[106:109], v[66:69], v[178:181], v[106:109]
	v_mfma_f32_16x16x32_bf16 v[94:97], v[58:61], v[186:189], v[94:97]
	v_mfma_f32_16x16x32_bf16 v[90:93], v[66:69], v[186:189], v[90:93]
	v_mfma_f32_16x16x32_bf16 v[162:165], v[62:65], v[166:169], v[162:165]
	v_mfma_f32_16x16x32_bf16 v[158:161], v[70:73], v[166:169], v[158:161]
	v_mfma_f32_16x16x32_bf16 v[130:133], v[62:65], v[174:177], v[130:133]
	v_mfma_f32_16x16x32_bf16 v[126:129], v[70:73], v[174:177], v[126:129]
	v_mfma_f32_16x16x32_bf16 v[110:113], v[62:65], v[182:185], v[110:113]
	v_mfma_f32_16x16x32_bf16 v[106:109], v[70:73], v[182:185], v[106:109]
	v_mfma_f32_16x16x32_bf16 v[94:97], v[62:65], v[190:193], v[94:97]
	v_mfma_f32_16x16x32_bf16 v[90:93], v[70:73], v[190:193], v[90:93]
	s_setprio 0
	s_setprio 1
	v_mfma_f32_16x16x32_bf16 v[142:145], v[122:125], v[154:157], v[142:145]
	v_mfma_f32_16x16x32_bf16 v[138:141], v[146:149], v[154:157], v[138:141]
	v_mfma_f32_16x16x32_bf16 v[118:121], v[122:125], v[170:173], v[118:121]
	v_mfma_f32_16x16x32_bf16 v[114:117], v[146:149], v[170:173], v[114:117]
	v_mfma_f32_16x16x32_bf16 v[102:105], v[122:125], v[178:181], v[102:105]
	v_mfma_f32_16x16x32_bf16 v[98:101], v[146:149], v[178:181], v[98:101]
	v_mfma_f32_16x16x32_bf16 v[86:89], v[122:125], v[186:189], v[86:89]
	v_mfma_f32_16x16x32_bf16 v[82:85], v[146:149], v[186:189], v[82:85]
	v_mfma_f32_16x16x32_bf16 v[142:145], v[134:137], v[166:169], v[142:145]
	v_mfma_f32_16x16x32_bf16 v[138:141], v[150:153], v[166:169], v[138:141]
	v_mfma_f32_16x16x32_bf16 v[118:121], v[134:137], v[174:177], v[118:121]
	v_mfma_f32_16x16x32_bf16 v[114:117], v[150:153], v[174:177], v[114:117]
	v_mfma_f32_16x16x32_bf16 v[102:105], v[134:137], v[182:185], v[102:105]
	v_mfma_f32_16x16x32_bf16 v[98:101], v[150:153], v[182:185], v[98:101]
	v_mfma_f32_16x16x32_bf16 v[86:89], v[134:137], v[190:193], v[86:89]
	v_mfma_f32_16x16x32_bf16 v[82:85], v[150:153], v[190:193], v[82:85]
	s_setprio 0
	s_barrier
; #define PG8_STAGE(bufoff, gbase, VO) do { _Pragma("unroll") for (int _i = 0; _i < 2; ++_i) \
;         __builtin_amdgcn_global_load_lds((const unsigned*)((const char*)(gbase) + VO[_i]), (LAS unsigned*)(lds + (bufoff) + ldsw + _i * 8192), 16, 0, 0); } while (0)
; #define PG8_LDA(dst, b, h) do { _Pragma("unroll") for (int m = 0; m < 4; ++m) _Pragma("unroll") for (int k = 0; k < 2; ++k) dst[m][k] = *(const LAS bf16x8*)(lds + PG8_SA(b, h) + aoff + m * 2048 + k * 1024); } while (0)
; #define PG8_MMA(ai, bj, At, Bt) do { __builtin_amdgcn_s_setprio(1); _Pragma("unroll") for (int m = 0; m < 4; ++m) _Pragma("unroll") for (int n = 0; n < 2; ++n) _Pragma("unroll") for (int k = 0; k < 2; ++k) \
;         acc[ai][bj][m][n] = __builtin_amdgcn_mfma_f32_16x16x32_bf16(Bt[n][k], At[m][k], acc[ai][bj][m][n], 0, 0, 0); __builtin_amdgcn_s_setprio(0); } while (0)
; #define PG8_WAIT_V(n) asm volatile("s_waitcnt vmcnt(" #n ")" ::: "memory")
; #define PG8_WAIT_L(n) asm volatile("s_waitcnt lgkmcnt(" #n ")" ::: "memory")
; #define PG8_BAR __builtin_amdgcn_s_barrier()
; #define PG8_SCHED __builtin_amdgcn_sched_barrier(0)
; template <int NSEG, class Epi, bool ALIGN_EPI = PG8_ALIGN, bool SP2 = PG8_SP2>
; DI void gemm_phase(LAS unsigned char* lds, const Gemm g, const StaticOrder& S, const Epi& E) {
;     ...
;             PG8_LDA(At, 1, 1); PG8_STAGE(PG8_SB(1, 0), b3, v2); PG8_STAGE(PG8_SB(1, 1), b3 + h2, v2); PG8_STAGE(PG8_SA(1, 0), a3, v2);
;             PG8_WAIT_V(8); PG8_WAIT_L(0); PG8_BAR; PG8_MMA(1, 0, At, B0); PG8_MMA(1, 1, At, B1); PG8_BAR; PG8_SCHED;
;     ...
;         if constexpr (ALIGN_EPI) { if (wr == 0) PG8_BAR; }
	s_add_i32 s26, s57, s36
	v_lshl_add_u64 v[194:195], v[194:195], 0, s[10:11]
	s_mov_b32 m0, s26
	ds_read_b128 v[154:157], v252 offset:49152
	ds_read_b128 v[166:169], v252 offset:50176
	ds_read_b128 v[170:173], v252 offset:51200
	ds_read_b128 v[174:177], v252 offset:52224
	ds_read_b128 v[178:181], v252 offset:53248
	ds_read_b128 v[182:185], v252 offset:54272
	ds_read_b128 v[186:189], v252 offset:55296
	ds_read_b128 v[190:193], v252 offset:56320
	global_load_lds_dwordx4 v[194:195], off
	s_add_i32 m0, s26, 0x2000
	s_add_u32 s24, s24, 0x80080
	v_lshl_add_u64 v[194:195], v[196:197], 0, s[10:11]
	s_addc_u32 s25, s25, 0
	s_add_i32 s26, s58, s36
	global_load_lds_dwordx4 v[194:195], off
	v_lshl_add_u64 v[194:195], s[24:25], 0, v[202:203]
	s_mov_b32 m0, s26
	s_nop 0
	global_load_lds_dwordx4 v[194:195], off
	v_lshl_add_u64 v[194:195], s[24:25], 0, v[204:205]
	s_add_i32 m0, s26, 0x2000
	s_nop 0
	global_load_lds_dwordx4 v[194:195], off
	v_lshl_add_u64 v[194:195], v[198:199], 0, s[10:11]
	s_mov_b32 m0, s48
	s_nop 0
	global_load_lds_dwordx4 v[194:195], off
	v_lshl_add_u64 v[194:195], v[200:201], 0, s[10:11]
	s_mov_b32 m0, s49
	s_nop 0
	global_load_lds_dwordx4 v[194:195], off
	s_waitcnt vmcnt(8)
	s_waitcnt lgkmcnt(0)
	s_setprio 1
	s_barrier
	v_mfma_f32_16x16x32_bf16 v[78:81], v[58:61], v[154:157], v[78:81]
	v_mfma_f32_16x16x32_bf16 v[74:77], v[66:69], v[154:157], v[74:77]
	v_mfma_f32_16x16x32_bf16 v[54:57], v[58:61], v[170:173], v[54:57]
	v_mfma_f32_16x16x32_bf16 v[50:53], v[66:69], v[170:173], v[50:53]
	v_mfma_f32_16x16x32_bf16 v[30:33], v[58:61], v[178:181], v[30:33]
	v_mfma_f32_16x16x32_bf16 v[26:29], v[66:69], v[178:181], v[26:29]
	v_mfma_f32_16x16x32_bf16 v[14:17], v[58:61], v[186:189], v[14:17]
	v_mfma_f32_16x16x32_bf16 v[10:13], v[66:69], v[186:189], v[10:13]
	v_mfma_f32_16x16x32_bf16 v[78:81], v[62:65], v[166:169], v[78:81]
	v_mfma_f32_16x16x32_bf16 v[74:77], v[70:73], v[166:169], v[74:77]
	v_mfma_f32_16x16x32_bf16 v[54:57], v[62:65], v[174:177], v[54:57]
	v_mfma_f32_16x16x32_bf16 v[50:53], v[70:73], v[174:177], v[50:53]
	v_mfma_f32_16x16x32_bf16 v[30:33], v[62:65], v[182:185], v[30:33]
	v_mfma_f32_16x16x32_bf16 v[26:29], v[70:73], v[182:185], v[26:29]
	v_mfma_f32_16x16x32_bf16 v[14:17], v[62:65], v[190:193], v[14:17]
	v_mfma_f32_16x16x32_bf16 v[10:13], v[70:73], v[190:193], v[10:13]
	s_setprio 0
	s_setprio 1
	v_mfma_f32_16x16x32_bf16 v[42:45], v[122:125], v[154:157], v[42:45]
	v_mfma_f32_16x16x32_bf16 v[70:73], v[134:137], v[166:169], v[42:45]
	v_mfma_f32_16x16x32_bf16 v[42:45], v[146:149], v[154:157], v[46:49]
	v_mfma_f32_16x16x32_bf16 v[38:41], v[122:125], v[170:173], v[38:41]
	v_mfma_f32_16x16x32_bf16 v[34:37], v[146:149], v[170:173], v[34:37]
	v_mfma_f32_16x16x32_bf16 v[22:25], v[122:125], v[178:181], v[22:25]
	v_mfma_f32_16x16x32_bf16 v[18:21], v[146:149], v[178:181], v[18:21]
	v_mfma_f32_16x16x32_bf16 v[6:9], v[122:125], v[186:189], v[6:9]
	v_mfma_f32_16x16x32_bf16 v[2:5], v[146:149], v[186:189], v[2:5]
	v_mfma_f32_16x16x32_bf16 v[66:69], v[150:153], v[166:169], v[42:45]
	v_mfma_f32_16x16x32_bf16 v[38:41], v[134:137], v[174:177], v[38:41]
	v_mfma_f32_16x16x32_bf16 v[34:37], v[150:153], v[174:177], v[34:37]
	v_mfma_f32_16x16x32_bf16 v[22:25], v[134:137], v[182:185], v[22:25]
	v_mfma_f32_16x16x32_bf16 v[18:21], v[150:153], v[182:185], v[18:21]
	v_mfma_f32_16x16x32_bf16 v[6:9], v[134:137], v[190:193], v[6:9]
	v_mfma_f32_16x16x32_bf16 v[2:5], v[150:153], v[190:193], v[2:5]
	s_setprio 0
	s_barrier
	s_add_i32 s56, s56, 2
	s_add_u32 s22, s22, 0x100
	s_addc_u32 s23, s23, 0
	s_add_u32 s54, s54, 0x100
	s_addc_u32 s55, s55, 0
	s_cmp_gt_u32 s56, 29
	s_cbranch_scc0 .LBB0_281
	s_and_b64 vcc, exec, s[12:13]
	s_cbranch_vccz .LBB0_284
	s_barrier

; #define PG8_STAGE(bufoff, gbase, VO) do { _Pragma("unroll") for (int _i = 0; _i < 2; ++_i) \
;         __builtin_amdgcn_global_load_lds((const unsigned*)((const char*)(gbase) + VO[_i]), (LAS unsigned*)(lds + (bufoff) + ldsw + _i * 8192), 16, 0, 0); } while (0)
; #define PG8_LDA(dst, b, h) do { _Pragma("unroll") for (int m = 0; m < 4; ++m) _Pragma("unroll") for (int k = 0; k < 2; ++k) dst[m][k] = *(const LAS bf16x8*)(lds + PG8_SA(b, h) + aoff + m * 2048 + k * 1024); } while (0)
; #define PG8_LDB(dst, b, h) do { _Pragma("unroll") for (int n = 0; n < 2; ++n) _Pragma("unroll") for (int k = 0; k < 2; ++k) dst[n][k] = *(const LAS bf16x8*)(lds + PG8_SB(b, h) + boff + n * 2048 + k * 1024); } while (0)
; #define PG8_MMA(ai, bj, At, Bt) do { __builtin_amdgcn_s_setprio(1); _Pragma("unroll") for (int m = 0; m < 4; ++m) _Pragma("unroll") for (int n = 0; n < 2; ++n) _Pragma("unroll") for (int k = 0; k < 2; ++k) \
;         acc[ai][bj][m][n] = __builtin_amdgcn_mfma_f32_16x16x32_bf16(Bt[n][k], At[m][k], acc[ai][bj][m][n], 0, 0, 0); __builtin_amdgcn_s_setprio(0); } while (0)
; #define PG8_BAR __builtin_amdgcn_s_barrier()
; template <int NSEG, class Epi, bool ALIGN_EPI = PG8_ALIGN, bool SP2 = PG8_SP2>
; DI void gemm_phase(LAS unsigned char* lds, const Gemm g, const StaticOrder& S, const Epi& E) {
;     ...
;         for (int t = 0; t < nt; t += 2) {
;             const bool last = (t == nt - 2);
;             const char* a1 = cA + (size_t)(t + 1) * kstep;
;             const char* a2 = last ? nA : cA + (size_t)(t + 2) * kstep; const char* b2 = last ? nB : cB + (size_t)(t + 2) * kstep;
;             const char* a3 = a2 + kstep; const char* b3 = b2 + kstep;
;             unsigned v2[2]; v2[0] = (NSEG > 1 && last) ? voffN[0] : voffC[0]; v2[1] = (NSEG > 1 && last) ? voffN[1] : voffC[1];
;             const size_t h2 = (NSEG > 1 && last) ? hstepN : hstepC;
;             if constexpr (SP2) {
;             PG8_LDB(B0, 0, 0); PG8_LDB(B1, 0, 1); PG8_SCHED; PG8_LDA(At, 0, 0); PG8_STAGE(PG8_SA(1, 1), a1 + hstepC, voffC);
;             PG8_WAIT_V(8); PG8_WAIT_L(0); PG8_BAR; PG8_MMA(0, 0, At, B0); PG8_MMA(0, 1, At, B1); PG8_BAR; PG8_SCHED;
;             PG8_LDA(At, 0, 1); PG8_STAGE(PG8_SB(0, 0), b2, v2); PG8_STAGE(PG8_SB(0, 1), b2 + h2, v2); PG8_STAGE(PG8_SA(0, 0), a2, v2);
;             PG8_WAIT_V(8); PG8_WAIT_L(0); PG8_BAR; PG8_MMA(1, 0, At, B0); PG8_MMA(1, 1, At, B1); PG8_BAR; PG8_SCHED;
.LBB0_305:
	ds_read_b128 v[130:133], v161
	ds_read_b128 v[134:137], v161 offset:1024
	ds_read_b128 v[150:153], v161 offset:2048
	ds_read_b128 v[154:157], v161 offset:3072
	ds_read_b128 v[164:167], v162
	ds_read_b128 v[168:171], v162 offset:1024
	ds_read_b128 v[172:175], v162 offset:2048
	ds_read_b128 v[176:179], v162 offset:3072
	s_add_i32 m0, s35, 0xc000
	ds_read_b128 v[180:183], v163
	ds_read_b128 v[184:187], v163 offset:1024
	ds_read_b128 v[188:191], v163 offset:2048
	ds_read_b128 v[192:195], v163 offset:3072
	ds_read_b128 v[196:199], v163 offset:4096
	ds_read_b128 v[200:203], v163 offset:5120
	ds_read_b128 v[204:207], v163 offset:6144
	ds_read_b128 v[208:211], v163 offset:7168
	global_load_lds_dwordx4 v142, s[36:37]
	s_add_i32 m0, s35, 0xe000
	s_nop 0
	global_load_lds_dwordx4 v144, s[36:37]
	s_waitcnt vmcnt(8)
	s_waitcnt lgkmcnt(0)
	s_setprio 1
	s_barrier
	v_mfma_f32_16x16x32_bf16 v[126:129], v[130:133], v[180:183], v[126:129]
	v_mfma_f32_16x16x32_bf16 v[122:125], v[150:153], v[180:183], v[122:125]
	s_add_u32 s38, s36, 0xfff80080
	s_addc_u32 s39, s37, -1
	v_mfma_f32_16x16x32_bf16 v[118:121], v[130:133], v[188:191], v[118:121]
	v_mfma_f32_16x16x32_bf16 v[114:117], v[150:153], v[188:191], v[114:117]
	s_cmp_eq_u32 s66, 28
	s_cselect_b32 s41, s21, s39
	v_mfma_f32_16x16x32_bf16 v[110:113], v[130:133], v[196:199], v[110:113]
	v_mfma_f32_16x16x32_bf16 v[106:109], v[150:153], v[196:199], v[106:109]
	s_cselect_b32 s40, s23, s38
	s_cselect_b32 s39, s62, s65
	v_mfma_f32_16x16x32_bf16 v[102:105], v[130:133], v[204:207], v[102:105]
	v_mfma_f32_16x16x32_bf16 v[98:101], v[150:153], v[204:207], v[98:101]
	s_cselect_b32 s38, s63, s64
	v_mfma_f32_16x16x32_bf16 v[126:129], v[134:137], v[184:187], v[126:129]
	v_mfma_f32_16x16x32_bf16 v[122:125], v[154:157], v[184:187], v[122:125]
	v_mfma_f32_16x16x32_bf16 v[118:121], v[134:137], v[192:195], v[118:121]
	v_mfma_f32_16x16x32_bf16 v[114:117], v[154:157], v[192:195], v[114:117]
	v_mfma_f32_16x16x32_bf16 v[110:113], v[134:137], v[200:203], v[110:113]
	v_mfma_f32_16x16x32_bf16 v[106:109], v[154:157], v[200:203], v[106:109]
	v_mfma_f32_16x16x32_bf16 v[102:105], v[134:137], v[208:211], v[102:105]
	v_mfma_f32_16x16x32_bf16 v[98:101], v[154:157], v[208:211], v[98:101]
	s_setprio 0
	s_setprio 1
	v_mfma_f32_16x16x32_bf16 v[62:65], v[164:167], v[180:183], v[62:65]
	v_mfma_f32_16x16x32_bf16 v[58:61], v[172:175], v[180:183], v[58:61]
	v_mfma_f32_16x16x32_bf16 v[54:57], v[164:167], v[188:191], v[54:57]
	v_mfma_f32_16x16x32_bf16 v[50:53], v[172:175], v[188:191], v[50:53]
	v_mfma_f32_16x16x32_bf16 v[46:49], v[164:167], v[196:199], v[46:49]
	v_mfma_f32_16x16x32_bf16 v[42:45], v[172:175], v[196:199], v[42:45]
	v_mfma_f32_16x16x32_bf16 v[38:41], v[164:167], v[204:207], v[38:41]
	v_mfma_f32_16x16x32_bf16 v[34:37], v[172:175], v[204:207], v[34:37]
	v_mfma_f32_16x16x32_bf16 v[62:65], v[168:171], v[184:187], v[62:65]
	v_mfma_f32_16x16x32_bf16 v[58:61], v[176:179], v[184:187], v[58:61]
	v_mfma_f32_16x16x32_bf16 v[54:57], v[168:171], v[192:195], v[54:57]
	v_mfma_f32_16x16x32_bf16 v[50:53], v[176:179], v[192:195], v[50:53]
	v_mfma_f32_16x16x32_bf16 v[46:49], v[168:171], v[200:203], v[46:49]
	v_mfma_f32_16x16x32_bf16 v[42:45], v[176:179], v[200:203], v[42:45]
	v_mfma_f32_16x16x32_bf16 v[38:41], v[168:171], v[208:211], v[38:41]
	v_mfma_f32_16x16x32_bf16 v[34:37], v[176:179], v[208:211], v[34:37]
	s_setprio 0
	s_barrier
	s_add_i32 s67, s55, s48
	v_lshl_add_u64 v[212:213], s[38:39], 0, v[138:139]
	s_mov_b32 m0, s67
	ds_read_b128 v[180:183], v163 offset:16384
	ds_read_b128 v[184:187], v163 offset:17408
	ds_read_b128 v[188:191], v163 offset:18432
	ds_read_b128 v[192:195], v163 offset:19456
	ds_read_b128 v[196:199], v163 offset:20480
	ds_read_b128 v[200:203], v163 offset:21504
	ds_read_b128 v[204:207], v163 offset:22528
	ds_read_b128 v[208:211], v163 offset:23552
	global_load_lds_dwordx4 v[212:213], off
	s_add_i32 m0, s67, 0x2000
	s_add_u32 s68, s38, 0x80000
	v_lshl_add_u64 v[214:215], s[38:39], 0, v[140:141]
	s_addc_u32 s69, s39, 0
	s_add_i32 s67, s56, s48
	global_load_lds_dwordx4 v[214:215], off
	v_lshl_add_u64 v[216:217], s[68:69], 0, v[138:139]
	s_mov_b32 m0, s67
	v_lshl_add_u64 v[218:219], s[40:41], 0, v[140:141]
	global_load_lds_dwordx4 v[216:217], off
	v_lshl_add_u64 v[216:217], s[68:69], 0, v[140:141]
	s_add_i32 m0, s67, 0x2000
	s_nop 0
	global_load_lds_dwordx4 v[216:217], off
	v_lshl_add_u64 v[216:217], s[40:41], 0, v[138:139]
	s_mov_b32 m0, s35
	s_nop 0
	global_load_lds_dwordx4 v[216:217], off
	s_mov_b32 m0, s49
	s_nop 0
	global_load_lds_dwordx4 v[218:219], off
	s_waitcnt vmcnt(8)
	s_waitcnt lgkmcnt(0)
	s_setprio 1
	s_barrier
; #define PG8_STAGE(bufoff, gbase, VO) do { _Pragma("unroll") for (int _i = 0; _i < 2; ++_i) \
;         __builtin_amdgcn_global_load_lds((const unsigned*)((const char*)(gbase) + VO[_i]), (LAS unsigned*)(lds + (bufoff) + ldsw + _i * 8192), 16, 0, 0); } while (0)
; #define PG8_LDA(dst, b, h) do { _Pragma("unroll") for (int m = 0; m < 4; ++m) _Pragma("unroll") for (int k = 0; k < 2; ++k) dst[m][k] = *(const LAS bf16x8*)(lds + PG8_SA(b, h) + aoff + m * 2048 + k * 1024); } while (0)
; #define PG8_LDB(dst, b, h) do { _Pragma("unroll") for (int n = 0; n < 2; ++n) _Pragma("unroll") for (int k = 0; k < 2; ++k) dst[n][k] = *(const LAS bf16x8*)(lds + PG8_SB(b, h) + boff + n * 2048 + k * 1024); } while (0)
; #define PG8_MMA(ai, bj, At, Bt) do { __builtin_amdgcn_s_setprio(1); _Pragma("unroll") for (int m = 0; m < 4; ++m) _Pragma("unroll") for (int n = 0; n < 2; ++n) _Pragma("unroll") for (int k = 0; k < 2; ++k) \
;         acc[ai][bj][m][n] = __builtin_amdgcn_mfma_f32_16x16x32_bf16(Bt[n][k], At[m][k], acc[ai][bj][m][n], 0, 0, 0); __builtin_amdgcn_s_setprio(0); } while (0)
; #define PG8_WAIT_V(n) asm volatile("s_waitcnt vmcnt(" #n ")" ::: "memory")
; #define PG8_WAIT_L(n) asm volatile("s_waitcnt lgkmcnt(" #n ")" ::: "memory")
; #define PG8_BAR __builtin_amdgcn_s_barrier()
; #define PG8_SCHED __builtin_amdgcn_sched_barrier(0)
; template <int NSEG, class Epi, bool ALIGN_EPI = PG8_ALIGN, bool SP2 = PG8_SP2>
; DI void gemm_phase(LAS unsigned char* lds, const Gemm g, const StaticOrder& S, const Epi& E) {
;     ...
;             PG8_WAIT_V(8); PG8_WAIT_L(0); PG8_BAR; PG8_MMA(1, 0, At, B0); PG8_MMA(1, 1, At, B1); PG8_BAR; PG8_SCHED;
;             PG8_LDB(B0, 1, 0); PG8_LDB(B1, 1, 1); PG8_SCHED; PG8_LDA(At, 1, 0); PG8_STAGE(PG8_SA(0, 1), a2 + h2, v2);
;             PG8_WAIT_V(8); PG8_WAIT_L(0); PG8_BAR; PG8_MMA(0, 0, At, B0); PG8_MMA(0, 1, At, B1); PG8_BAR; PG8_SCHED;
	v_mfma_f32_16x16x32_bf16 v[94:97], v[130:133], v[180:183], v[94:97]
	v_mfma_f32_16x16x32_bf16 v[90:93], v[150:153], v[180:183], v[90:93]
	v_mfma_f32_16x16x32_bf16 v[86:89], v[130:133], v[188:191], v[86:89]
	v_mfma_f32_16x16x32_bf16 v[82:85], v[150:153], v[188:191], v[82:85]
	v_mfma_f32_16x16x32_bf16 v[78:81], v[130:133], v[196:199], v[78:81]
	v_mfma_f32_16x16x32_bf16 v[74:77], v[150:153], v[196:199], v[74:77]
	v_mfma_f32_16x16x32_bf16 v[70:73], v[130:133], v[204:207], v[70:73]
	v_mfma_f32_16x16x32_bf16 v[66:69], v[150:153], v[204:207], v[66:69]
	v_mfma_f32_16x16x32_bf16 v[94:97], v[134:137], v[184:187], v[94:97]
	v_mfma_f32_16x16x32_bf16 v[90:93], v[154:157], v[184:187], v[90:93]
	v_mfma_f32_16x16x32_bf16 v[86:89], v[134:137], v[192:195], v[86:89]
	v_mfma_f32_16x16x32_bf16 v[82:85], v[154:157], v[192:195], v[82:85]
	v_mfma_f32_16x16x32_bf16 v[78:81], v[134:137], v[200:203], v[78:81]
	v_mfma_f32_16x16x32_bf16 v[74:77], v[154:157], v[200:203], v[74:77]
	v_mfma_f32_16x16x32_bf16 v[70:73], v[134:137], v[208:211], v[70:73]
	v_mfma_f32_16x16x32_bf16 v[66:69], v[154:157], v[208:211], v[66:69]
	s_setprio 0
	s_setprio 1
	v_mfma_f32_16x16x32_bf16 v[30:33], v[164:167], v[180:183], v[30:33]
	v_mfma_f32_16x16x32_bf16 v[26:29], v[172:175], v[180:183], v[26:29]
	v_mfma_f32_16x16x32_bf16 v[14:17], v[164:167], v[188:191], v[14:17]
	v_mfma_f32_16x16x32_bf16 v[2:5], v[172:175], v[188:191], v[2:5]
	v_mfma_f32_16x16x32_bf16 v[22:25], v[164:167], v[196:199], v[22:25]
	v_mfma_f32_16x16x32_bf16 v[18:21], v[172:175], v[196:199], v[18:21]
	v_mfma_f32_16x16x32_bf16 v[10:13], v[164:167], v[204:207], v[10:13]
	v_mfma_f32_16x16x32_bf16 v[6:9], v[172:175], v[204:207], v[6:9]
	v_mfma_f32_16x16x32_bf16 v[30:33], v[168:171], v[184:187], v[30:33]
	v_mfma_f32_16x16x32_bf16 v[26:29], v[176:179], v[184:187], v[26:29]
	v_mfma_f32_16x16x32_bf16 v[14:17], v[168:171], v[192:195], v[14:17]
	v_mfma_f32_16x16x32_bf16 v[2:5], v[176:179], v[192:195], v[2:5]
	v_mfma_f32_16x16x32_bf16 v[22:25], v[168:171], v[200:203], v[22:25]
	v_mfma_f32_16x16x32_bf16 v[18:21], v[176:179], v[200:203], v[18:21]
	v_mfma_f32_16x16x32_bf16 v[10:13], v[168:171], v[208:211], v[10:13]
	v_mfma_f32_16x16x32_bf16 v[6:9], v[176:179], v[208:211], v[6:9]
	s_setprio 0
	s_barrier
	s_add_i32 s67, 0, 0x18000
	s_add_i32 s68, 0, 0x1c000
	v_add_u32_e32 v154, s67, v159
	v_add_u32_e32 v176, s68, v159
	ds_read_b128 v[130:133], v154
	ds_read_b128 v[134:137], v154 offset:1024
	ds_read_b128 v[150:153], v154 offset:2048
	ds_read_b128 v[154:157], v154 offset:3072
	ds_read_b128 v[164:167], v176
	ds_read_b128 v[168:171], v176 offset:1024
	ds_read_b128 v[172:175], v176 offset:2048
	ds_read_b128 v[176:179], v176 offset:3072
	s_add_u32 s40, s40, 0x80000
	s_addc_u32 s41, s41, 0
	s_mov_b32 m0, s50
	v_lshl_add_u64 v[220:221], s[40:41], 0, v[138:139]
	ds_read_b128 v[180:183], v163 offset:32768
	ds_read_b128 v[184:187], v163 offset:33792
	ds_read_b128 v[188:191], v163 offset:34816
	ds_read_b128 v[192:195], v163 offset:35840
	ds_read_b128 v[196:199], v163 offset:36864
	ds_read_b128 v[200:203], v163 offset:37888
	ds_read_b128 v[204:207], v163 offset:38912
	ds_read_b128 v[208:211], v163 offset:39936
	global_load_lds_dwordx4 v[220:221], off
	v_lshl_add_u64 v[220:221], s[40:41], 0, v[140:141]
	s_mov_b32 m0, s51
	s_nop 0
	global_load_lds_dwordx4 v[220:221], off
	s_waitcnt vmcnt(8)
	s_waitcnt lgkmcnt(0)
	s_setprio 1
	s_barrier
	v_mfma_f32_16x16x32_bf16 v[126:129], v[130:133], v[180:183], v[126:129]
	v_mfma_f32_16x16x32_bf16 v[122:125], v[150:153], v[180:183], v[122:125]
	v_mfma_f32_16x16x32_bf16 v[118:121], v[130:133], v[188:191], v[118:121]
	v_mfma_f32_16x16x32_bf16 v[114:117], v[150:153], v[188:191], v[114:117]
	v_mfma_f32_16x16x32_bf16 v[110:113], v[130:133], v[196:199], v[110:113]
	v_mfma_f32_16x16x32_bf16 v[106:109], v[150:153], v[196:199], v[106:109]
	v_mfma_f32_16x16x32_bf16 v[102:105], v[130:133], v[204:207], v[102:105]
	v_mfma_f32_16x16x32_bf16 v[98:101], v[150:153], v[204:207], v[98:101]
	v_mfma_f32_16x16x32_bf16 v[126:129], v[134:137], v[184:187], v[126:129]
	v_mfma_f32_16x16x32_bf16 v[122:125], v[154:157], v[184:187], v[122:125]
	v_mfma_f32_16x16x32_bf16 v[118:121], v[134:137], v[192:195], v[118:121]
	v_mfma_f32_16x16x32_bf16 v[114:117], v[154:157], v[192:195], v[114:117]
	v_mfma_f32_16x16x32_bf16 v[110:113], v[134:137], v[200:203], v[110:113]
	v_mfma_f32_16x16x32_bf16 v[106:109], v[154:157], v[200:203], v[106:109]
	v_mfma_f32_16x16x32_bf16 v[102:105], v[134:137], v[208:211], v[102:105]
	v_mfma_f32_16x16x32_bf16 v[98:101], v[154:157], v[208:211], v[98:101]
	s_setprio 0
	s_setprio 1
	v_mfma_f32_16x16x32_bf16 v[62:65], v[164:167], v[180:183], v[62:65]
	v_mfma_f32_16x16x32_bf16 v[58:61], v[172:175], v[180:183], v[58:61]
	v_mfma_f32_16x16x32_bf16 v[54:57], v[164:167], v[188:191], v[54:57]
	v_mfma_f32_16x16x32_bf16 v[50:53], v[172:175], v[188:191], v[50:53]
	v_mfma_f32_16x16x32_bf16 v[46:49], v[164:167], v[196:199], v[46:49]
	v_mfma_f32_16x16x32_bf16 v[42:45], v[172:175], v[196:199], v[42:45]
	v_mfma_f32_16x16x32_bf16 v[38:41], v[164:167], v[204:207], v[38:41]
	v_mfma_f32_16x16x32_bf16 v[34:37], v[172:175], v[204:207], v[34:37]
	v_mfma_f32_16x16x32_bf16 v[62:65], v[168:171], v[184:187], v[62:65]
	v_mfma_f32_16x16x32_bf16 v[58:61], v[176:179], v[184:187], v[58:61]
	v_mfma_f32_16x16x32_bf16 v[54:57], v[168:171], v[192:195], v[54:57]
	v_mfma_f32_16x16x32_bf16 v[50:53], v[176:179], v[192:195], v[50:53]
	v_mfma_f32_16x16x32_bf16 v[46:49], v[168:171], v[200:203], v[46:49]
	v_mfma_f32_16x16x32_bf16 v[42:45], v[176:179], v[200:203], v[42:45]
	v_mfma_f32_16x16x32_bf16 v[38:41], v[168:171], v[208:211], v[38:41]
	v_mfma_f32_16x16x32_bf16 v[34:37], v[176:179], v[208:211], v[34:37]
	s_setprio 0
	s_barrier
; #define PG8_STAGE(bufoff, gbase, VO) do { _Pragma("unroll") for (int _i = 0; _i < 2; ++_i) \
;         __builtin_amdgcn_global_load_lds((const unsigned*)((const char*)(gbase) + VO[_i]), (LAS unsigned*)(lds + (bufoff) + ldsw + _i * 8192), 16, 0, 0); } while (0)
; #define PG8_LDA(dst, b, h) do { _Pragma("unroll") for (int m = 0; m < 4; ++m) _Pragma("unroll") for (int k = 0; k < 2; ++k) dst[m][k] = *(const LAS bf16x8*)(lds + PG8_SA(b, h) + aoff + m * 2048 + k * 1024); } while (0)
; #define PG8_MMA(ai, bj, At, Bt) do { __builtin_amdgcn_s_setprio(1); _Pragma("unroll") for (int m = 0; m < 4; ++m) _Pragma("unroll") for (int n = 0; n < 2; ++n) _Pragma("unroll") for (int k = 0; k < 2; ++k) \
;         acc[ai][bj][m][n] = __builtin_amdgcn_mfma_f32_16x16x32_bf16(Bt[n][k], At[m][k], acc[ai][bj][m][n], 0, 0, 0); __builtin_amdgcn_s_setprio(0); } while (0)
; #define PG8_WAIT_V(n) asm volatile("s_waitcnt vmcnt(" #n ")" ::: "memory")
; #define PG8_WAIT_L(n) asm volatile("s_waitcnt lgkmcnt(" #n ")" ::: "memory")
; #define PG8_BAR __builtin_amdgcn_s_barrier()
; #define PG8_SCHED __builtin_amdgcn_sched_barrier(0)
; template <int NSEG, class Epi, bool ALIGN_EPI = PG8_ALIGN, bool SP2 = PG8_SP2>
; DI void gemm_phase(LAS unsigned char* lds, const Gemm g, const StaticOrder& S, const Epi& E) {
;     ...
;             PG8_LDA(At, 1, 1); PG8_STAGE(PG8_SB(1, 0), b3, v2); PG8_STAGE(PG8_SB(1, 1), b3 + h2, v2); PG8_STAGE(PG8_SA(1, 0), a3, v2);
;             PG8_WAIT_V(8); PG8_WAIT_L(0); PG8_BAR; PG8_MMA(1, 0, At, B0); PG8_MMA(1, 1, At, B1); PG8_BAR; PG8_SCHED;
;     ...
;         if constexpr (ALIGN_EPI) { if (wr == 0) PG8_BAR; }
	s_add_i32 s40, s67, s48
	v_lshl_add_u64 v[212:213], v[212:213], 0, s[8:9]
	s_mov_b32 m0, s40
	ds_read_b128 v[180:183], v163 offset:49152
	ds_read_b128 v[184:187], v163 offset:50176
	ds_read_b128 v[188:191], v163 offset:51200
	ds_read_b128 v[192:195], v163 offset:52224
	ds_read_b128 v[196:199], v163 offset:53248
	ds_read_b128 v[200:203], v163 offset:54272
	ds_read_b128 v[204:207], v163 offset:55296
	ds_read_b128 v[208:211], v163 offset:56320
	global_load_lds_dwordx4 v[212:213], off
	s_add_i32 m0, s40, 0x2000
	s_add_u32 s38, s38, 0x80080
	v_lshl_add_u64 v[212:213], v[214:215], 0, s[8:9]
	s_addc_u32 s39, s39, 0
	s_add_i32 s40, s68, s48
	global_load_lds_dwordx4 v[212:213], off
	v_lshl_add_u64 v[212:213], s[38:39], 0, v[138:139]
	s_mov_b32 m0, s40
	s_nop 0
	global_load_lds_dwordx4 v[212:213], off
	v_lshl_add_u64 v[212:213], s[38:39], 0, v[140:141]
	s_add_i32 m0, s40, 0x2000
	s_nop 0
	global_load_lds_dwordx4 v[212:213], off
	v_lshl_add_u64 v[212:213], v[216:217], 0, s[8:9]
	s_mov_b32 m0, s53
	s_nop 0
	global_load_lds_dwordx4 v[212:213], off
	v_lshl_add_u64 v[212:213], v[218:219], 0, s[8:9]
	s_mov_b32 m0, s54
	s_nop 0
	global_load_lds_dwordx4 v[212:213], off
	s_waitcnt vmcnt(8)
	s_waitcnt lgkmcnt(0)
	s_setprio 1
	s_barrier
	v_mfma_f32_16x16x32_bf16 v[94:97], v[130:133], v[180:183], v[94:97]
	v_mfma_f32_16x16x32_bf16 v[90:93], v[150:153], v[180:183], v[90:93]
	v_mfma_f32_16x16x32_bf16 v[86:89], v[130:133], v[188:191], v[86:89]
	v_mfma_f32_16x16x32_bf16 v[82:85], v[150:153], v[188:191], v[82:85]
	v_mfma_f32_16x16x32_bf16 v[78:81], v[130:133], v[196:199], v[78:81]
	v_mfma_f32_16x16x32_bf16 v[74:77], v[150:153], v[196:199], v[74:77]
	v_mfma_f32_16x16x32_bf16 v[70:73], v[130:133], v[204:207], v[70:73]
	v_mfma_f32_16x16x32_bf16 v[66:69], v[150:153], v[204:207], v[66:69]
	v_mfma_f32_16x16x32_bf16 v[94:97], v[134:137], v[184:187], v[94:97]
	v_mfma_f32_16x16x32_bf16 v[90:93], v[154:157], v[184:187], v[90:93]
	v_mfma_f32_16x16x32_bf16 v[86:89], v[134:137], v[192:195], v[86:89]
	v_mfma_f32_16x16x32_bf16 v[82:85], v[154:157], v[192:195], v[82:85]
	v_mfma_f32_16x16x32_bf16 v[78:81], v[134:137], v[200:203], v[78:81]
	v_mfma_f32_16x16x32_bf16 v[74:77], v[154:157], v[200:203], v[74:77]
	v_mfma_f32_16x16x32_bf16 v[70:73], v[134:137], v[208:211], v[70:73]
	v_mfma_f32_16x16x32_bf16 v[66:69], v[154:157], v[208:211], v[66:69]
	s_setprio 0
	s_setprio 1
	v_mfma_f32_16x16x32_bf16 v[30:33], v[164:167], v[180:183], v[30:33]
	v_mfma_f32_16x16x32_bf16 v[26:29], v[172:175], v[180:183], v[26:29]
	v_mfma_f32_16x16x32_bf16 v[14:17], v[164:167], v[188:191], v[14:17]
	v_mfma_f32_16x16x32_bf16 v[2:5], v[172:175], v[188:191], v[2:5]
	v_mfma_f32_16x16x32_bf16 v[22:25], v[164:167], v[196:199], v[22:25]
	v_mfma_f32_16x16x32_bf16 v[18:21], v[172:175], v[196:199], v[18:21]
	v_mfma_f32_16x16x32_bf16 v[10:13], v[164:167], v[204:207], v[10:13]
	v_mfma_f32_16x16x32_bf16 v[6:9], v[172:175], v[204:207], v[6:9]
	v_mfma_f32_16x16x32_bf16 v[30:33], v[168:171], v[184:187], v[30:33]
	v_mfma_f32_16x16x32_bf16 v[26:29], v[176:179], v[184:187], v[26:29]
	v_mfma_f32_16x16x32_bf16 v[14:17], v[168:171], v[192:195], v[14:17]
	v_mfma_f32_16x16x32_bf16 v[2:5], v[176:179], v[192:195], v[2:5]
	v_mfma_f32_16x16x32_bf16 v[22:25], v[168:171], v[200:203], v[22:25]
	v_mfma_f32_16x16x32_bf16 v[18:21], v[176:179], v[200:203], v[18:21]
	v_mfma_f32_16x16x32_bf16 v[10:13], v[168:171], v[208:211], v[10:13]
	v_mfma_f32_16x16x32_bf16 v[6:9], v[176:179], v[208:211], v[6:9]
	s_setprio 0
	s_barrier
	s_add_i32 s66, s66, 2
	s_add_u32 s36, s36, 0x100
	s_addc_u32 s37, s37, 0
	s_add_u32 s64, s64, 0x100
	s_addc_u32 s65, s65, 0
	s_cmp_gt_u32 s66, 29
	s_cbranch_scc0 .LBB0_305
	s_and_b64 vcc, exec, s[10:11]
	s_cbranch_vccz .LBB0_308
	s_barrier

; #define PG8_STAGE(bufoff, gbase, VO) do { _Pragma("unroll") for (int _i = 0; _i < 2; ++_i) \
;         __builtin_amdgcn_global_load_lds((const unsigned*)((const char*)(gbase) + VO[_i]), (LAS unsigned*)(lds + (bufoff) + ldsw + _i * 8192), 16, 0, 0); } while (0)
; #define PG8_LDA(dst, b, h) do { _Pragma("unroll") for (int m = 0; m < 4; ++m) _Pragma("unroll") for (int k = 0; k < 2; ++k) dst[m][k] = *(const LAS bf16x8*)(lds + PG8_SA(b, h) + aoff + m * 2048 + k * 1024); } while (0)
; #define PG8_LDB(dst, b, h) do { _Pragma("unroll") for (int n = 0; n < 2; ++n) _Pragma("unroll") for (int k = 0; k < 2; ++k) dst[n][k] = *(const LAS bf16x8*)(lds + PG8_SB(b, h) + boff + n * 2048 + k * 1024); } while (0)
; #define PG8_MMA(ai, bj, At, Bt) do { __builtin_amdgcn_s_setprio(1); _Pragma("unroll") for (int m = 0; m < 4; ++m) _Pragma("unroll") for (int n = 0; n < 2; ++n) _Pragma("unroll") for (int k = 0; k < 2; ++k) \
;         acc[ai][bj][m][n] = __builtin_amdgcn_mfma_f32_16x16x32_bf16(Bt[n][k], At[m][k], acc[ai][bj][m][n], 0, 0, 0); __builtin_amdgcn_s_setprio(0); } while (0)
; #define PG8_BAR __builtin_amdgcn_s_barrier()
; template <int NSEG, class Epi, bool ALIGN_EPI = PG8_ALIGN, bool SP2 = PG8_SP2>
; DI void gemm_phase(LAS unsigned char* lds, const Gemm g, const StaticOrder& S, const Epi& E) {
;     ...
;         for (int t = 0; t < nt; t += 2) {
;             const bool last = (t == nt - 2);
;             const char* a1 = cA + (size_t)(t + 1) * kstep;
;             const char* a2 = last ? nA : cA + (size_t)(t + 2) * kstep; const char* b2 = last ? nB : cB + (size_t)(t + 2) * kstep;
;             const char* a3 = a2 + kstep; const char* b3 = b2 + kstep;
;             unsigned v2[2]; v2[0] = (NSEG > 1 && last) ? voffN[0] : voffC[0]; v2[1] = (NSEG > 1 && last) ? voffN[1] : voffC[1];
;             const size_t h2 = (NSEG > 1 && last) ? hstepN : hstepC;
;             if constexpr (SP2) {
;             PG8_LDB(B0, 0, 0); PG8_LDB(B1, 0, 1); PG8_SCHED; PG8_LDA(At, 0, 0); PG8_STAGE(PG8_SA(1, 1), a1 + hstepC, voffC);
;             PG8_WAIT_V(8); PG8_WAIT_L(0); PG8_BAR; PG8_MMA(0, 0, At, B0); PG8_MMA(0, 1, At, B1); PG8_BAR; PG8_SCHED;
;             PG8_LDA(At, 0, 1); PG8_STAGE(PG8_SB(0, 0), b2, v2); PG8_STAGE(PG8_SB(0, 1), b2 + h2, v2); PG8_STAGE(PG8_SA(0, 0), a2, v2);
;             PG8_WAIT_V(8); PG8_WAIT_L(0); PG8_BAR; PG8_MMA(1, 0, At, B0); PG8_MMA(1, 1, At, B1); PG8_BAR; PG8_SCHED;
.LBB0_427:
	ds_read_b128 v[148:151], v145
	ds_read_b128 v[152:155], v145 offset:1024
	ds_read_b128 v[156:159], v145 offset:2048
	ds_read_b128 v[160:163], v145 offset:3072
	ds_read_b128 v[164:167], v146
	ds_read_b128 v[168:171], v146 offset:1024
	ds_read_b128 v[172:175], v146 offset:2048
	ds_read_b128 v[176:179], v146 offset:3072
	s_add_i32 m0, s23, 0xc000
	ds_read_b128 v[180:183], v147
	ds_read_b128 v[184:187], v147 offset:1024
	ds_read_b128 v[188:191], v147 offset:2048
	ds_read_b128 v[192:195], v147 offset:3072
	ds_read_b128 v[196:199], v147 offset:4096
	ds_read_b128 v[200:203], v147 offset:5120
	ds_read_b128 v[204:207], v147 offset:6144
	ds_read_b128 v[208:211], v147 offset:7168
	global_load_lds_dwordx4 v134, s[36:37]
	s_add_i32 m0, s23, 0xe000
	s_nop 0
	global_load_lds_dwordx4 v136, s[36:37]
	s_waitcnt vmcnt(8)
	s_waitcnt lgkmcnt(0)
	s_setprio 1
	s_barrier
	v_mfma_f32_16x16x32_bf16 v[126:129], v[148:151], v[180:183], v[126:129]
	v_mfma_f32_16x16x32_bf16 v[122:125], v[156:159], v[180:183], v[122:125]
	s_add_u32 s38, s36, 0xfff80080
	s_addc_u32 s39, s37, -1
	v_mfma_f32_16x16x32_bf16 v[118:121], v[148:151], v[188:191], v[118:121]
	v_mfma_f32_16x16x32_bf16 v[114:117], v[156:159], v[188:191], v[114:117]
	s_cmp_eq_u32 s61, 28
	s_cselect_b32 s41, s5, s39
	v_mfma_f32_16x16x32_bf16 v[102:105], v[148:151], v[196:199], v[102:105]
	v_mfma_f32_16x16x32_bf16 v[98:101], v[156:159], v[196:199], v[98:101]
	s_cselect_b32 s40, s4, s38
	s_cselect_b32 s39, s35, s27
	v_mfma_f32_16x16x32_bf16 v[86:89], v[148:151], v[204:207], v[86:89]
	v_mfma_f32_16x16x32_bf16 v[82:85], v[156:159], v[204:207], v[82:85]
	s_cselect_b32 s38, s34, s25
	v_mfma_f32_16x16x32_bf16 v[126:129], v[152:155], v[184:187], v[126:129]
	v_mfma_f32_16x16x32_bf16 v[122:125], v[160:163], v[184:187], v[122:125]
	v_mfma_f32_16x16x32_bf16 v[118:121], v[152:155], v[192:195], v[118:121]
	v_mfma_f32_16x16x32_bf16 v[114:117], v[160:163], v[192:195], v[114:117]
	v_mfma_f32_16x16x32_bf16 v[102:105], v[152:155], v[200:203], v[102:105]
	v_mfma_f32_16x16x32_bf16 v[98:101], v[160:163], v[200:203], v[98:101]
	v_mfma_f32_16x16x32_bf16 v[86:89], v[152:155], v[208:211], v[86:89]
	v_mfma_f32_16x16x32_bf16 v[82:85], v[160:163], v[208:211], v[82:85]
	s_setprio 0
	s_setprio 1
	v_mfma_f32_16x16x32_bf16 v[110:113], v[164:167], v[180:183], v[110:113]
	v_mfma_f32_16x16x32_bf16 v[106:109], v[172:175], v[180:183], v[106:109]
	v_mfma_f32_16x16x32_bf16 v[94:97], v[164:167], v[188:191], v[94:97]
	v_mfma_f32_16x16x32_bf16 v[90:93], v[172:175], v[188:191], v[90:93]
	v_mfma_f32_16x16x32_bf16 v[78:81], v[164:167], v[196:199], v[78:81]
	v_mfma_f32_16x16x32_bf16 v[74:77], v[172:175], v[196:199], v[74:77]
	v_mfma_f32_16x16x32_bf16 v[70:73], v[164:167], v[204:207], v[70:73]
	v_mfma_f32_16x16x32_bf16 v[66:69], v[172:175], v[204:207], v[66:69]
	v_mfma_f32_16x16x32_bf16 v[110:113], v[168:171], v[184:187], v[110:113]
	v_mfma_f32_16x16x32_bf16 v[106:109], v[176:179], v[184:187], v[106:109]
	v_mfma_f32_16x16x32_bf16 v[94:97], v[168:171], v[192:195], v[94:97]
	v_mfma_f32_16x16x32_bf16 v[90:93], v[176:179], v[192:195], v[90:93]
	v_mfma_f32_16x16x32_bf16 v[78:81], v[168:171], v[200:203], v[78:81]
	v_mfma_f32_16x16x32_bf16 v[74:77], v[176:179], v[200:203], v[74:77]
	v_mfma_f32_16x16x32_bf16 v[70:73], v[168:171], v[208:211], v[70:73]
	v_mfma_f32_16x16x32_bf16 v[66:69], v[176:179], v[208:211], v[66:69]
	s_setprio 0
	s_barrier
	s_add_i32 s62, s55, s47
	v_lshl_add_u64 v[212:213], s[38:39], 0, v[130:131]
	s_mov_b32 m0, s62
	ds_read_b128 v[180:183], v147 offset:16384
	ds_read_b128 v[184:187], v147 offset:17408
	ds_read_b128 v[188:191], v147 offset:18432
	ds_read_b128 v[192:195], v147 offset:19456
	ds_read_b128 v[196:199], v147 offset:20480
	ds_read_b128 v[200:203], v147 offset:21504
	ds_read_b128 v[204:207], v147 offset:22528
	ds_read_b128 v[208:211], v147 offset:23552
	global_load_lds_dwordx4 v[212:213], off
	s_add_i32 m0, s62, 0x2000
	s_add_u32 s62, s38, 0x80000
	v_lshl_add_u64 v[214:215], s[38:39], 0, v[132:133]
	s_addc_u32 s63, s39, 0
	s_add_i32 s64, s56, s47
	global_load_lds_dwordx4 v[214:215], off
	v_lshl_add_u64 v[216:217], s[62:63], 0, v[130:131]
	s_mov_b32 m0, s64
	v_lshl_add_u64 v[218:219], s[40:41], 0, v[132:133]
	global_load_lds_dwordx4 v[216:217], off
	v_lshl_add_u64 v[216:217], s[62:63], 0, v[132:133]
	s_add_i32 m0, s64, 0x2000
	s_nop 0
	global_load_lds_dwordx4 v[216:217], off
	v_lshl_add_u64 v[216:217], s[40:41], 0, v[130:131]
	s_mov_b32 m0, s23
	s_nop 0
	global_load_lds_dwordx4 v[216:217], off
	s_mov_b32 m0, s48
	s_nop 0
	global_load_lds_dwordx4 v[218:219], off
	s_waitcnt vmcnt(8)
	s_waitcnt lgkmcnt(0)
	s_setprio 1
	s_barrier
; #define PG8_STAGE(bufoff, gbase, VO) do { _Pragma("unroll") for (int _i = 0; _i < 2; ++_i) \
;         __builtin_amdgcn_global_load_lds((const unsigned*)((const char*)(gbase) + VO[_i]), (LAS unsigned*)(lds + (bufoff) + ldsw + _i * 8192), 16, 0, 0); } while (0)
; #define PG8_LDA(dst, b, h) do { _Pragma("unroll") for (int m = 0; m < 4; ++m) _Pragma("unroll") for (int k = 0; k < 2; ++k) dst[m][k] = *(const LAS bf16x8*)(lds + PG8_SA(b, h) + aoff + m * 2048 + k * 1024); } while (0)
; #define PG8_LDB(dst, b, h) do { _Pragma("unroll") for (int n = 0; n < 2; ++n) _Pragma("unroll") for (int k = 0; k < 2; ++k) dst[n][k] = *(const LAS bf16x8*)(lds + PG8_SB(b, h) + boff + n * 2048 + k * 1024); } while (0)
; #define PG8_MMA(ai, bj, At, Bt) do { __builtin_amdgcn_s_setprio(1); _Pragma("unroll") for (int m = 0; m < 4; ++m) _Pragma("unroll") for (int n = 0; n < 2; ++n) _Pragma("unroll") for (int k = 0; k < 2; ++k) \
;         acc[ai][bj][m][n] = __builtin_amdgcn_mfma_f32_16x16x32_bf16(Bt[n][k], At[m][k], acc[ai][bj][m][n], 0, 0, 0); __builtin_amdgcn_s_setprio(0); } while (0)
; #define PG8_WAIT_V(n) asm volatile("s_waitcnt vmcnt(" #n ")" ::: "memory")
; #define PG8_WAIT_L(n) asm volatile("s_waitcnt lgkmcnt(" #n ")" ::: "memory")
; #define PG8_BAR __builtin_amdgcn_s_barrier()
; #define PG8_SCHED __builtin_amdgcn_sched_barrier(0)
; template <int NSEG, class Epi, bool ALIGN_EPI = PG8_ALIGN, bool SP2 = PG8_SP2>
; DI void gemm_phase(LAS unsigned char* lds, const Gemm g, const StaticOrder& S, const Epi& E) {
;     ...
;             PG8_WAIT_V(8); PG8_WAIT_L(0); PG8_BAR; PG8_MMA(1, 0, At, B0); PG8_MMA(1, 1, At, B1); PG8_BAR; PG8_SCHED;
;             PG8_LDB(B0, 1, 0); PG8_LDB(B1, 1, 1); PG8_SCHED; PG8_LDA(At, 1, 0); PG8_STAGE(PG8_SA(0, 1), a2 + h2, v2);
;             PG8_WAIT_V(8); PG8_WAIT_L(0); PG8_BAR; PG8_MMA(0, 0, At, B0); PG8_MMA(0, 1, At, B1); PG8_BAR; PG8_SCHED;
	v_mfma_f32_16x16x32_bf16 v[54:57], v[148:151], v[180:183], v[54:57]
	v_mfma_f32_16x16x32_bf16 v[46:49], v[156:159], v[180:183], v[46:49]
	v_mfma_f32_16x16x32_bf16 v[38:41], v[148:151], v[188:191], v[38:41]
	v_mfma_f32_16x16x32_bf16 v[34:37], v[156:159], v[188:191], v[34:37]
	v_mfma_f32_16x16x32_bf16 v[22:25], v[148:151], v[196:199], v[22:25]
	v_mfma_f32_16x16x32_bf16 v[18:21], v[156:159], v[196:199], v[18:21]
	v_mfma_f32_16x16x32_bf16 v[6:9], v[148:151], v[204:207], v[6:9]
	v_mfma_f32_16x16x32_bf16 v[2:5], v[156:159], v[204:207], v[2:5]
	v_mfma_f32_16x16x32_bf16 v[54:57], v[152:155], v[184:187], v[54:57]
	v_mfma_f32_16x16x32_bf16 v[46:49], v[160:163], v[184:187], v[46:49]
	v_mfma_f32_16x16x32_bf16 v[38:41], v[152:155], v[192:195], v[38:41]
	v_mfma_f32_16x16x32_bf16 v[34:37], v[160:163], v[192:195], v[34:37]
	v_mfma_f32_16x16x32_bf16 v[22:25], v[152:155], v[200:203], v[22:25]
	v_mfma_f32_16x16x32_bf16 v[18:21], v[160:163], v[200:203], v[18:21]
	v_mfma_f32_16x16x32_bf16 v[6:9], v[152:155], v[208:211], v[6:9]
	v_mfma_f32_16x16x32_bf16 v[2:5], v[160:163], v[208:211], v[2:5]
	s_setprio 0
	s_setprio 1
	v_mfma_f32_16x16x32_bf16 v[30:33], v[164:167], v[180:183], v[30:33]
	v_mfma_f32_16x16x32_bf16 v[26:29], v[172:175], v[180:183], v[26:29]
	v_mfma_f32_16x16x32_bf16 v[14:17], v[164:167], v[188:191], v[14:17]
	v_mfma_f32_16x16x32_bf16 v[10:13], v[172:175], v[188:191], v[10:13]
	v_mfma_f32_16x16x32_bf16 v[58:61], v[164:167], v[196:199], v[58:61]
	v_mfma_f32_16x16x32_bf16 v[62:65], v[172:175], v[196:199], v[62:65]
	v_mfma_f32_16x16x32_bf16 v[42:45], v[164:167], v[204:207], v[42:45]
	v_mfma_f32_16x16x32_bf16 v[50:53], v[172:175], v[204:207], v[50:53]
	v_mfma_f32_16x16x32_bf16 v[30:33], v[168:171], v[184:187], v[30:33]
	v_mfma_f32_16x16x32_bf16 v[26:29], v[176:179], v[184:187], v[26:29]
	v_mfma_f32_16x16x32_bf16 v[14:17], v[168:171], v[192:195], v[14:17]
	v_mfma_f32_16x16x32_bf16 v[10:13], v[176:179], v[192:195], v[10:13]
	v_mfma_f32_16x16x32_bf16 v[58:61], v[168:171], v[200:203], v[58:61]
	v_mfma_f32_16x16x32_bf16 v[62:65], v[176:179], v[200:203], v[62:65]
	v_mfma_f32_16x16x32_bf16 v[42:45], v[168:171], v[208:211], v[42:45]
	v_mfma_f32_16x16x32_bf16 v[50:53], v[176:179], v[208:211], v[50:53]
	s_setprio 0
	s_barrier
	s_add_i32 s62, 0, 0x18000
	s_add_i32 s63, 0, 0x1c000
	v_add_u32_e32 v160, s62, v143
	v_add_u32_e32 v176, s63, v143
	ds_read_b128 v[148:151], v160
	ds_read_b128 v[152:155], v160 offset:1024
	ds_read_b128 v[156:159], v160 offset:2048
	ds_read_b128 v[160:163], v160 offset:3072
	ds_read_b128 v[164:167], v176
	ds_read_b128 v[168:171], v176 offset:1024
	ds_read_b128 v[172:175], v176 offset:2048
	ds_read_b128 v[176:179], v176 offset:3072
	s_add_u32 s40, s40, 0x80000
	s_addc_u32 s41, s41, 0
	s_mov_b32 m0, s49
	v_lshl_add_u64 v[220:221], s[40:41], 0, v[130:131]
	ds_read_b128 v[180:183], v147 offset:32768
	ds_read_b128 v[184:187], v147 offset:33792
	ds_read_b128 v[188:191], v147 offset:34816
	ds_read_b128 v[192:195], v147 offset:35840
	ds_read_b128 v[196:199], v147 offset:36864
	ds_read_b128 v[200:203], v147 offset:37888
	ds_read_b128 v[204:207], v147 offset:38912
	ds_read_b128 v[208:211], v147 offset:39936
	global_load_lds_dwordx4 v[220:221], off
	v_lshl_add_u64 v[220:221], s[40:41], 0, v[132:133]
	s_mov_b32 m0, s50
	s_nop 0
	global_load_lds_dwordx4 v[220:221], off
	s_waitcnt vmcnt(8)
	s_waitcnt lgkmcnt(0)
	s_setprio 1
	s_barrier
	v_mfma_f32_16x16x32_bf16 v[126:129], v[148:151], v[180:183], v[126:129]
	v_mfma_f32_16x16x32_bf16 v[122:125], v[156:159], v[180:183], v[122:125]
	v_mfma_f32_16x16x32_bf16 v[118:121], v[148:151], v[188:191], v[118:121]
	v_mfma_f32_16x16x32_bf16 v[114:117], v[156:159], v[188:191], v[114:117]
	v_mfma_f32_16x16x32_bf16 v[102:105], v[148:151], v[196:199], v[102:105]
	v_mfma_f32_16x16x32_bf16 v[98:101], v[156:159], v[196:199], v[98:101]
	v_mfma_f32_16x16x32_bf16 v[86:89], v[148:151], v[204:207], v[86:89]
	v_mfma_f32_16x16x32_bf16 v[82:85], v[156:159], v[204:207], v[82:85]
	v_mfma_f32_16x16x32_bf16 v[126:129], v[152:155], v[184:187], v[126:129]
	v_mfma_f32_16x16x32_bf16 v[122:125], v[160:163], v[184:187], v[122:125]
	v_mfma_f32_16x16x32_bf16 v[118:121], v[152:155], v[192:195], v[118:121]
	v_mfma_f32_16x16x32_bf16 v[114:117], v[160:163], v[192:195], v[114:117]
	v_mfma_f32_16x16x32_bf16 v[102:105], v[152:155], v[200:203], v[102:105]
	v_mfma_f32_16x16x32_bf16 v[98:101], v[160:163], v[200:203], v[98:101]
	v_mfma_f32_16x16x32_bf16 v[86:89], v[152:155], v[208:211], v[86:89]
	v_mfma_f32_16x16x32_bf16 v[82:85], v[160:163], v[208:211], v[82:85]
	s_setprio 0
	s_setprio 1
	v_mfma_f32_16x16x32_bf16 v[110:113], v[164:167], v[180:183], v[110:113]
	v_mfma_f32_16x16x32_bf16 v[106:109], v[172:175], v[180:183], v[106:109]
	v_mfma_f32_16x16x32_bf16 v[94:97], v[164:167], v[188:191], v[94:97]
	v_mfma_f32_16x16x32_bf16 v[90:93], v[172:175], v[188:191], v[90:93]
	v_mfma_f32_16x16x32_bf16 v[78:81], v[164:167], v[196:199], v[78:81]
	v_mfma_f32_16x16x32_bf16 v[74:77], v[172:175], v[196:199], v[74:77]
	v_mfma_f32_16x16x32_bf16 v[70:73], v[164:167], v[204:207], v[70:73]
	v_mfma_f32_16x16x32_bf16 v[66:69], v[172:175], v[204:207], v[66:69]
	v_mfma_f32_16x16x32_bf16 v[110:113], v[168:171], v[184:187], v[110:113]
	v_mfma_f32_16x16x32_bf16 v[106:109], v[176:179], v[184:187], v[106:109]
	v_mfma_f32_16x16x32_bf16 v[94:97], v[168:171], v[192:195], v[94:97]
	v_mfma_f32_16x16x32_bf16 v[90:93], v[176:179], v[192:195], v[90:93]
	v_mfma_f32_16x16x32_bf16 v[78:81], v[168:171], v[200:203], v[78:81]
	v_mfma_f32_16x16x32_bf16 v[74:77], v[176:179], v[200:203], v[74:77]
	v_mfma_f32_16x16x32_bf16 v[70:73], v[168:171], v[208:211], v[70:73]
	v_mfma_f32_16x16x32_bf16 v[66:69], v[176:179], v[208:211], v[66:69]
	s_setprio 0
	s_barrier
; #define PG8_STAGE(bufoff, gbase, VO) do { _Pragma("unroll") for (int _i = 0; _i < 2; ++_i) \
;         __builtin_amdgcn_global_load_lds((const unsigned*)((const char*)(gbase) + VO[_i]), (LAS unsigned*)(lds + (bufoff) + ldsw + _i * 8192), 16, 0, 0); } while (0)
; #define PG8_LDA(dst, b, h) do { _Pragma("unroll") for (int m = 0; m < 4; ++m) _Pragma("unroll") for (int k = 0; k < 2; ++k) dst[m][k] = *(const LAS bf16x8*)(lds + PG8_SA(b, h) + aoff + m * 2048 + k * 1024); } while (0)
; #define PG8_MMA(ai, bj, At, Bt) do { __builtin_amdgcn_s_setprio(1); _Pragma("unroll") for (int m = 0; m < 4; ++m) _Pragma("unroll") for (int n = 0; n < 2; ++n) _Pragma("unroll") for (int k = 0; k < 2; ++k) \
;         acc[ai][bj][m][n] = __builtin_amdgcn_mfma_f32_16x16x32_bf16(Bt[n][k], At[m][k], acc[ai][bj][m][n], 0, 0, 0); __builtin_amdgcn_s_setprio(0); } while (0)
; #define PG8_WAIT_V(n) asm volatile("s_waitcnt vmcnt(" #n ")" ::: "memory")
; #define PG8_WAIT_L(n) asm volatile("s_waitcnt lgkmcnt(" #n ")" ::: "memory")
; #define PG8_BAR __builtin_amdgcn_s_barrier()
; #define PG8_SCHED __builtin_amdgcn_sched_barrier(0)
; template <int NSEG, class Epi, bool ALIGN_EPI = PG8_ALIGN, bool SP2 = PG8_SP2>
; DI void gemm_phase(LAS unsigned char* lds, const Gemm g, const StaticOrder& S, const Epi& E) {
;     ...
;             PG8_LDA(At, 1, 1); PG8_STAGE(PG8_SB(1, 0), b3, v2); PG8_STAGE(PG8_SB(1, 1), b3 + h2, v2); PG8_STAGE(PG8_SA(1, 0), a3, v2);
;             PG8_WAIT_V(8); PG8_WAIT_L(0); PG8_BAR; PG8_MMA(1, 0, At, B0); PG8_MMA(1, 1, At, B1); PG8_BAR; PG8_SCHED;
;     ...
;         if constexpr (ALIGN_EPI) { if (wr == 0) PG8_BAR; }
	s_add_i32 s40, s62, s47
	v_lshl_add_u64 v[212:213], v[212:213], 0, s[12:13]
	s_mov_b32 m0, s40
	ds_read_b128 v[180:183], v147 offset:49152
	ds_read_b128 v[184:187], v147 offset:50176
	ds_read_b128 v[188:191], v147 offset:51200
	ds_read_b128 v[192:195], v147 offset:52224
	ds_read_b128 v[196:199], v147 offset:53248
	ds_read_b128 v[200:203], v147 offset:54272
	ds_read_b128 v[204:207], v147 offset:55296
	ds_read_b128 v[208:211], v147 offset:56320
	global_load_lds_dwordx4 v[212:213], off
	s_add_i32 m0, s40, 0x2000
	s_add_u32 s38, s38, 0x80080
	v_lshl_add_u64 v[212:213], v[214:215], 0, s[12:13]
	s_addc_u32 s39, s39, 0
	s_add_i32 s40, s63, s47
	global_load_lds_dwordx4 v[212:213], off
	v_lshl_add_u64 v[212:213], s[38:39], 0, v[130:131]
	s_mov_b32 m0, s40
	s_nop 0
	global_load_lds_dwordx4 v[212:213], off
	v_lshl_add_u64 v[212:213], s[38:39], 0, v[132:133]
	s_add_i32 m0, s40, 0x2000
	s_nop 0
	global_load_lds_dwordx4 v[212:213], off
	v_lshl_add_u64 v[212:213], v[216:217], 0, s[12:13]
	s_mov_b32 m0, s53
	s_nop 0
	global_load_lds_dwordx4 v[212:213], off
	v_lshl_add_u64 v[212:213], v[218:219], 0, s[12:13]
	s_mov_b32 m0, s54
	s_nop 0
	global_load_lds_dwordx4 v[212:213], off
	s_waitcnt vmcnt(8)
	s_waitcnt lgkmcnt(0)
	s_setprio 1
	s_barrier
	v_mfma_f32_16x16x32_bf16 v[54:57], v[148:151], v[180:183], v[54:57]
	v_mfma_f32_16x16x32_bf16 v[46:49], v[156:159], v[180:183], v[46:49]
	v_mfma_f32_16x16x32_bf16 v[38:41], v[148:151], v[188:191], v[38:41]
	v_mfma_f32_16x16x32_bf16 v[34:37], v[156:159], v[188:191], v[34:37]
	v_mfma_f32_16x16x32_bf16 v[22:25], v[148:151], v[196:199], v[22:25]
	v_mfma_f32_16x16x32_bf16 v[18:21], v[156:159], v[196:199], v[18:21]
	v_mfma_f32_16x16x32_bf16 v[6:9], v[148:151], v[204:207], v[6:9]
	v_mfma_f32_16x16x32_bf16 v[2:5], v[156:159], v[204:207], v[2:5]
	v_mfma_f32_16x16x32_bf16 v[54:57], v[152:155], v[184:187], v[54:57]
	v_mfma_f32_16x16x32_bf16 v[46:49], v[160:163], v[184:187], v[46:49]
	v_mfma_f32_16x16x32_bf16 v[38:41], v[152:155], v[192:195], v[38:41]
	v_mfma_f32_16x16x32_bf16 v[34:37], v[160:163], v[192:195], v[34:37]
	v_mfma_f32_16x16x32_bf16 v[22:25], v[152:155], v[200:203], v[22:25]
	v_mfma_f32_16x16x32_bf16 v[18:21], v[160:163], v[200:203], v[18:21]
	v_mfma_f32_16x16x32_bf16 v[6:9], v[152:155], v[208:211], v[6:9]
	v_mfma_f32_16x16x32_bf16 v[2:5], v[160:163], v[208:211], v[2:5]
	s_setprio 0
	s_setprio 1
	v_mfma_f32_16x16x32_bf16 v[30:33], v[164:167], v[180:183], v[30:33]
	v_mfma_f32_16x16x32_bf16 v[26:29], v[172:175], v[180:183], v[26:29]
	v_mfma_f32_16x16x32_bf16 v[14:17], v[164:167], v[188:191], v[14:17]
	v_mfma_f32_16x16x32_bf16 v[10:13], v[172:175], v[188:191], v[10:13]
	v_mfma_f32_16x16x32_bf16 v[58:61], v[164:167], v[196:199], v[58:61]
	v_mfma_f32_16x16x32_bf16 v[62:65], v[172:175], v[196:199], v[62:65]
	v_mfma_f32_16x16x32_bf16 v[42:45], v[164:167], v[204:207], v[42:45]
	v_mfma_f32_16x16x32_bf16 v[50:53], v[172:175], v[204:207], v[50:53]
	v_mfma_f32_16x16x32_bf16 v[30:33], v[168:171], v[184:187], v[30:33]
	v_mfma_f32_16x16x32_bf16 v[26:29], v[176:179], v[184:187], v[26:29]
	v_mfma_f32_16x16x32_bf16 v[14:17], v[168:171], v[192:195], v[14:17]
	v_mfma_f32_16x16x32_bf16 v[10:13], v[176:179], v[192:195], v[10:13]
	v_mfma_f32_16x16x32_bf16 v[58:61], v[168:171], v[200:203], v[58:61]
	v_mfma_f32_16x16x32_bf16 v[62:65], v[176:179], v[200:203], v[62:65]
	v_mfma_f32_16x16x32_bf16 v[42:45], v[168:171], v[208:211], v[42:45]
	v_mfma_f32_16x16x32_bf16 v[50:53], v[176:179], v[208:211], v[50:53]
	s_setprio 0
	s_barrier
	s_add_i32 s61, s61, 2
	s_add_u32 s36, s36, 0x100
	s_addc_u32 s37, s37, 0
	s_add_u32 s25, s25, 0x100
	s_addc_u32 s27, s27, 0
	s_cmp_gt_u32 s61, 29
	s_cbranch_scc0 .LBB0_427
	s_and_b64 vcc, exec, s[14:15]
	s_cbranch_vccz .LBB0_430
	s_barrier

; #define PG8_STAGE(bufoff, gbase, VO) do { _Pragma("unroll") for (int _i = 0; _i < 2; ++_i) \
;         __builtin_amdgcn_global_load_lds((const unsigned*)((const char*)(gbase) + VO[_i]), (LAS unsigned*)(lds + (bufoff) + ldsw + _i * 8192), 16, 0, 0); } while (0)
; #define PG8_LDA(dst, b, h) do { _Pragma("unroll") for (int m = 0; m < 4; ++m) _Pragma("unroll") for (int k = 0; k < 2; ++k) dst[m][k] = *(const LAS bf16x8*)(lds + PG8_SA(b, h) + aoff + m * 2048 + k * 1024); } while (0)
; #define PG8_LDB(dst, b, h) do { _Pragma("unroll") for (int n = 0; n < 2; ++n) _Pragma("unroll") for (int k = 0; k < 2; ++k) dst[n][k] = *(const LAS bf16x8*)(lds + PG8_SB(b, h) + boff + n * 2048 + k * 1024); } while (0)
; #define PG8_MMA(ai, bj, At, Bt) do { __builtin_amdgcn_s_setprio(1); _Pragma("unroll") for (int m = 0; m < 4; ++m) _Pragma("unroll") for (int n = 0; n < 2; ++n) _Pragma("unroll") for (int k = 0; k < 2; ++k) \
;         acc[ai][bj][m][n] = __builtin_amdgcn_mfma_f32_16x16x32_bf16(Bt[n][k], At[m][k], acc[ai][bj][m][n], 0, 0, 0); __builtin_amdgcn_s_setprio(0); } while (0)
; #define PG8_BAR __builtin_amdgcn_s_barrier()
; template <int NSEG, class Epi, bool ALIGN_EPI = PG8_ALIGN, bool SP2 = PG8_SP2>
; DI void gemm_phase(LAS unsigned char* lds, const Gemm g, const StaticOrder& S, const Epi& E) {
;     ...
;         for (int t = 0; t < nt; t += 2) {
;             const bool last = (t == nt - 2);
;             const char* a1 = cA + (size_t)(t + 1) * kstep;
;             const char* a2 = last ? nA : cA + (size_t)(t + 2) * kstep; const char* b2 = last ? nB : cB + (size_t)(t + 2) * kstep;
;             const char* a3 = a2 + kstep; const char* b3 = b2 + kstep;
;             unsigned v2[2]; v2[0] = (NSEG > 1 && last) ? voffN[0] : voffC[0]; v2[1] = (NSEG > 1 && last) ? voffN[1] : voffC[1];
;             const size_t h2 = (NSEG > 1 && last) ? hstepN : hstepC;
;             if constexpr (SP2) {
;             PG8_LDB(B0, 0, 0); PG8_LDB(B1, 0, 1); PG8_SCHED; PG8_LDA(At, 0, 0); PG8_STAGE(PG8_SA(1, 1), a1 + hstepC, voffC);
;             PG8_WAIT_V(8); PG8_WAIT_L(0); PG8_BAR; PG8_MMA(0, 0, At, B0); PG8_MMA(0, 1, At, B1); PG8_BAR; PG8_SCHED;
;             PG8_LDA(At, 0, 1); PG8_STAGE(PG8_SB(0, 0), b2, v2); PG8_STAGE(PG8_SB(0, 1), b2 + h2, v2); PG8_STAGE(PG8_SA(0, 0), a2, v2);
;             PG8_WAIT_V(8); PG8_WAIT_L(0); PG8_BAR; PG8_MMA(1, 0, At, B0); PG8_MMA(1, 1, At, B1); PG8_BAR; PG8_SCHED;
.LBB0_501:
	ds_read_b128 v[148:151], v145
	ds_read_b128 v[152:155], v145 offset:1024
	ds_read_b128 v[156:159], v145 offset:2048
	ds_read_b128 v[160:163], v145 offset:3072
	ds_read_b128 v[164:167], v146
	ds_read_b128 v[168:171], v146 offset:1024
	ds_read_b128 v[172:175], v146 offset:2048
	ds_read_b128 v[176:179], v146 offset:3072
	s_add_i32 m0, s15, 0xc000
	ds_read_b128 v[180:183], v147
	ds_read_b128 v[184:187], v147 offset:1024
	ds_read_b128 v[188:191], v147 offset:2048
	ds_read_b128 v[192:195], v147 offset:3072
	ds_read_b128 v[196:199], v147 offset:4096
	ds_read_b128 v[200:203], v147 offset:5120
	ds_read_b128 v[204:207], v147 offset:6144
	ds_read_b128 v[208:211], v147 offset:7168
	global_load_lds_dwordx4 v134, s[22:23]
	s_add_i32 m0, s15, 0xe000
	s_nop 0
	global_load_lds_dwordx4 v136, s[22:23]
	s_waitcnt vmcnt(8)
	s_waitcnt lgkmcnt(0)
	s_setprio 1
	s_barrier
	v_mfma_f32_16x16x32_bf16 v[126:129], v[148:151], v[180:183], v[126:129]
	v_mfma_f32_16x16x32_bf16 v[122:125], v[156:159], v[180:183], v[122:125]
	s_add_u32 s24, s22, 0xfff80080
	s_addc_u32 s25, s23, -1
	v_mfma_f32_16x16x32_bf16 v[118:121], v[148:151], v[188:191], v[118:121]
	v_mfma_f32_16x16x32_bf16 v[114:117], v[156:159], v[188:191], v[114:117]
	s_cmp_eq_u32 s52, 28
	s_cselect_b32 s27, s5, s25
	v_mfma_f32_16x16x32_bf16 v[102:105], v[148:151], v[196:199], v[102:105]
	v_mfma_f32_16x16x32_bf16 v[98:101], v[156:159], v[196:199], v[98:101]
	s_cselect_b32 s26, s4, s24
	s_cselect_b32 s25, s21, s19
	v_mfma_f32_16x16x32_bf16 v[86:89], v[148:151], v[204:207], v[86:89]
	v_mfma_f32_16x16x32_bf16 v[82:85], v[156:159], v[204:207], v[82:85]
	s_cselect_b32 s24, s20, s17
	v_mfma_f32_16x16x32_bf16 v[126:129], v[152:155], v[184:187], v[126:129]
	v_mfma_f32_16x16x32_bf16 v[122:125], v[160:163], v[184:187], v[122:125]
	v_mfma_f32_16x16x32_bf16 v[118:121], v[152:155], v[192:195], v[118:121]
	v_mfma_f32_16x16x32_bf16 v[114:117], v[160:163], v[192:195], v[114:117]
	v_mfma_f32_16x16x32_bf16 v[102:105], v[152:155], v[200:203], v[102:105]
	v_mfma_f32_16x16x32_bf16 v[98:101], v[160:163], v[200:203], v[98:101]
	v_mfma_f32_16x16x32_bf16 v[86:89], v[152:155], v[208:211], v[86:89]
	v_mfma_f32_16x16x32_bf16 v[82:85], v[160:163], v[208:211], v[82:85]
	s_setprio 0
	s_setprio 1
	v_mfma_f32_16x16x32_bf16 v[110:113], v[164:167], v[180:183], v[110:113]
	v_mfma_f32_16x16x32_bf16 v[106:109], v[172:175], v[180:183], v[106:109]
	v_mfma_f32_16x16x32_bf16 v[94:97], v[164:167], v[188:191], v[94:97]
	v_mfma_f32_16x16x32_bf16 v[90:93], v[172:175], v[188:191], v[90:93]
	v_mfma_f32_16x16x32_bf16 v[78:81], v[164:167], v[196:199], v[78:81]
	v_mfma_f32_16x16x32_bf16 v[74:77], v[172:175], v[196:199], v[74:77]
	v_mfma_f32_16x16x32_bf16 v[70:73], v[164:167], v[204:207], v[70:73]
	v_mfma_f32_16x16x32_bf16 v[58:61], v[172:175], v[204:207], v[58:61]
	v_mfma_f32_16x16x32_bf16 v[110:113], v[168:171], v[184:187], v[110:113]
	v_mfma_f32_16x16x32_bf16 v[106:109], v[176:179], v[184:187], v[106:109]
	v_mfma_f32_16x16x32_bf16 v[94:97], v[168:171], v[192:195], v[94:97]
	v_mfma_f32_16x16x32_bf16 v[90:93], v[176:179], v[192:195], v[90:93]
	v_mfma_f32_16x16x32_bf16 v[78:81], v[168:171], v[200:203], v[78:81]
	v_mfma_f32_16x16x32_bf16 v[74:77], v[176:179], v[200:203], v[74:77]
	v_mfma_f32_16x16x32_bf16 v[70:73], v[168:171], v[208:211], v[70:73]
	v_mfma_f32_16x16x32_bf16 v[58:61], v[176:179], v[208:211], v[58:61]
	s_setprio 0
	s_barrier
	s_add_i32 s53, s48, s38
	v_lshl_add_u64 v[212:213], s[24:25], 0, v[130:131]
	s_mov_b32 m0, s53
	ds_read_b128 v[180:183], v147 offset:16384
	ds_read_b128 v[184:187], v147 offset:17408
	ds_read_b128 v[188:191], v147 offset:18432
	ds_read_b128 v[192:195], v147 offset:19456
	ds_read_b128 v[196:199], v147 offset:20480
	ds_read_b128 v[200:203], v147 offset:21504
	ds_read_b128 v[204:207], v147 offset:22528
	ds_read_b128 v[208:211], v147 offset:23552
	global_load_lds_dwordx4 v[212:213], off
	s_add_i32 m0, s53, 0x2000
	s_add_u32 s54, s24, 0x80000
	v_lshl_add_u64 v[214:215], s[24:25], 0, v[132:133]
	s_addc_u32 s55, s25, 0
	s_add_i32 s53, s49, s38
	global_load_lds_dwordx4 v[214:215], off
	v_lshl_add_u64 v[216:217], s[54:55], 0, v[130:131]
	s_mov_b32 m0, s53
	v_lshl_add_u64 v[218:219], s[26:27], 0, v[132:133]
	global_load_lds_dwordx4 v[216:217], off
	v_lshl_add_u64 v[216:217], s[54:55], 0, v[132:133]
	s_add_i32 m0, s53, 0x2000
	s_nop 0
	global_load_lds_dwordx4 v[216:217], off
	v_lshl_add_u64 v[216:217], s[26:27], 0, v[130:131]
	s_mov_b32 m0, s15
	s_nop 0
	global_load_lds_dwordx4 v[216:217], off
	s_mov_b32 m0, s41
	s_nop 0
	global_load_lds_dwordx4 v[218:219], off
	s_waitcnt vmcnt(8)
	s_waitcnt lgkmcnt(0)
	s_setprio 1
	s_barrier
; #define PG8_STAGE(bufoff, gbase, VO) do { _Pragma("unroll") for (int _i = 0; _i < 2; ++_i) \
;         __builtin_amdgcn_global_load_lds((const unsigned*)((const char*)(gbase) + VO[_i]), (LAS unsigned*)(lds + (bufoff) + ldsw + _i * 8192), 16, 0, 0); } while (0)
; #define PG8_LDA(dst, b, h) do { _Pragma("unroll") for (int m = 0; m < 4; ++m) _Pragma("unroll") for (int k = 0; k < 2; ++k) dst[m][k] = *(const LAS bf16x8*)(lds + PG8_SA(b, h) + aoff + m * 2048 + k * 1024); } while (0)
; #define PG8_LDB(dst, b, h) do { _Pragma("unroll") for (int n = 0; n < 2; ++n) _Pragma("unroll") for (int k = 0; k < 2; ++k) dst[n][k] = *(const LAS bf16x8*)(lds + PG8_SB(b, h) + boff + n * 2048 + k * 1024); } while (0)
; #define PG8_MMA(ai, bj, At, Bt) do { __builtin_amdgcn_s_setprio(1); _Pragma("unroll") for (int m = 0; m < 4; ++m) _Pragma("unroll") for (int n = 0; n < 2; ++n) _Pragma("unroll") for (int k = 0; k < 2; ++k) \
;         acc[ai][bj][m][n] = __builtin_amdgcn_mfma_f32_16x16x32_bf16(Bt[n][k], At[m][k], acc[ai][bj][m][n], 0, 0, 0); __builtin_amdgcn_s_setprio(0); } while (0)
; #define PG8_WAIT_V(n) asm volatile("s_waitcnt vmcnt(" #n ")" ::: "memory")
; #define PG8_WAIT_L(n) asm volatile("s_waitcnt lgkmcnt(" #n ")" ::: "memory")
; #define PG8_BAR __builtin_amdgcn_s_barrier()
; #define PG8_SCHED __builtin_amdgcn_sched_barrier(0)
; template <int NSEG, class Epi, bool ALIGN_EPI = PG8_ALIGN, bool SP2 = PG8_SP2>
; DI void gemm_phase(LAS unsigned char* lds, const Gemm g, const StaticOrder& S, const Epi& E) {
;     ...
;             PG8_WAIT_V(8); PG8_WAIT_L(0); PG8_BAR; PG8_MMA(1, 0, At, B0); PG8_MMA(1, 1, At, B1); PG8_BAR; PG8_SCHED;
;             PG8_LDB(B0, 1, 0); PG8_LDB(B1, 1, 1); PG8_SCHED; PG8_LDA(At, 1, 0); PG8_STAGE(PG8_SA(0, 1), a2 + h2, v2);
;             PG8_WAIT_V(8); PG8_WAIT_L(0); PG8_BAR; PG8_MMA(0, 0, At, B0); PG8_MMA(0, 1, At, B1); PG8_BAR; PG8_SCHED;
	v_mfma_f32_16x16x32_bf16 v[46:49], v[148:151], v[180:183], v[46:49]
	v_mfma_f32_16x16x32_bf16 v[42:45], v[156:159], v[180:183], v[42:45]
	v_mfma_f32_16x16x32_bf16 v[38:41], v[148:151], v[188:191], v[38:41]
	v_mfma_f32_16x16x32_bf16 v[34:37], v[156:159], v[188:191], v[34:37]
	v_mfma_f32_16x16x32_bf16 v[22:25], v[148:151], v[196:199], v[22:25]
	v_mfma_f32_16x16x32_bf16 v[18:21], v[156:159], v[196:199], v[18:21]
	v_mfma_f32_16x16x32_bf16 v[6:9], v[148:151], v[204:207], v[6:9]
	v_mfma_f32_16x16x32_bf16 v[2:5], v[156:159], v[204:207], v[2:5]
	v_mfma_f32_16x16x32_bf16 v[46:49], v[152:155], v[184:187], v[46:49]
	v_mfma_f32_16x16x32_bf16 v[42:45], v[160:163], v[184:187], v[42:45]
	v_mfma_f32_16x16x32_bf16 v[38:41], v[152:155], v[192:195], v[38:41]
	v_mfma_f32_16x16x32_bf16 v[34:37], v[160:163], v[192:195], v[34:37]
	v_mfma_f32_16x16x32_bf16 v[22:25], v[152:155], v[200:203], v[22:25]
	v_mfma_f32_16x16x32_bf16 v[18:21], v[160:163], v[200:203], v[18:21]
	v_mfma_f32_16x16x32_bf16 v[6:9], v[152:155], v[208:211], v[6:9]
	v_mfma_f32_16x16x32_bf16 v[2:5], v[160:163], v[208:211], v[2:5]
	s_setprio 0
	s_setprio 1
	v_mfma_f32_16x16x32_bf16 v[30:33], v[164:167], v[180:183], v[30:33]
	v_mfma_f32_16x16x32_bf16 v[26:29], v[172:175], v[180:183], v[26:29]
	v_mfma_f32_16x16x32_bf16 v[14:17], v[164:167], v[188:191], v[14:17]
	v_mfma_f32_16x16x32_bf16 v[10:13], v[172:175], v[188:191], v[10:13]
	v_mfma_f32_16x16x32_bf16 v[62:65], v[164:167], v[196:199], v[62:65]
	v_mfma_f32_16x16x32_bf16 v[66:69], v[172:175], v[196:199], v[66:69]
	v_mfma_f32_16x16x32_bf16 v[50:53], v[164:167], v[204:207], v[50:53]
	v_mfma_f32_16x16x32_bf16 v[54:57], v[172:175], v[204:207], v[54:57]
	v_mfma_f32_16x16x32_bf16 v[30:33], v[168:171], v[184:187], v[30:33]
	v_mfma_f32_16x16x32_bf16 v[26:29], v[176:179], v[184:187], v[26:29]
	v_mfma_f32_16x16x32_bf16 v[14:17], v[168:171], v[192:195], v[14:17]
	v_mfma_f32_16x16x32_bf16 v[10:13], v[176:179], v[192:195], v[10:13]
	v_mfma_f32_16x16x32_bf16 v[62:65], v[168:171], v[200:203], v[62:65]
	v_mfma_f32_16x16x32_bf16 v[66:69], v[176:179], v[200:203], v[66:69]
	v_mfma_f32_16x16x32_bf16 v[50:53], v[168:171], v[208:211], v[50:53]
	v_mfma_f32_16x16x32_bf16 v[54:57], v[176:179], v[208:211], v[54:57]
	s_setprio 0
	s_barrier
	s_add_i32 s53, 0, 0x18000
	s_add_i32 s54, 0, 0x1c000
	v_add_u32_e32 v160, s53, v143
	v_add_u32_e32 v176, s54, v143
	ds_read_b128 v[148:151], v160
	ds_read_b128 v[152:155], v160 offset:1024
	ds_read_b128 v[156:159], v160 offset:2048
	ds_read_b128 v[160:163], v160 offset:3072
	ds_read_b128 v[164:167], v176
	ds_read_b128 v[168:171], v176 offset:1024
	ds_read_b128 v[172:175], v176 offset:2048
	ds_read_b128 v[176:179], v176 offset:3072
	s_add_u32 s26, s26, 0x80000
	s_addc_u32 s27, s27, 0
	s_mov_b32 m0, s42
	v_lshl_add_u64 v[220:221], s[26:27], 0, v[130:131]
	ds_read_b128 v[180:183], v147 offset:32768
	ds_read_b128 v[184:187], v147 offset:33792
	ds_read_b128 v[188:191], v147 offset:34816
	ds_read_b128 v[192:195], v147 offset:35840
	ds_read_b128 v[196:199], v147 offset:36864
	ds_read_b128 v[200:203], v147 offset:37888
	ds_read_b128 v[204:207], v147 offset:38912
	ds_read_b128 v[208:211], v147 offset:39936
	global_load_lds_dwordx4 v[220:221], off
	v_lshl_add_u64 v[220:221], s[26:27], 0, v[132:133]
	s_mov_b32 m0, s43
	s_nop 0
	global_load_lds_dwordx4 v[220:221], off
	s_waitcnt vmcnt(8)
	s_waitcnt lgkmcnt(0)
	s_setprio 1
	s_barrier
	v_mfma_f32_16x16x32_bf16 v[126:129], v[148:151], v[180:183], v[126:129]
	v_mfma_f32_16x16x32_bf16 v[122:125], v[156:159], v[180:183], v[122:125]
	v_mfma_f32_16x16x32_bf16 v[118:121], v[148:151], v[188:191], v[118:121]
	v_mfma_f32_16x16x32_bf16 v[114:117], v[156:159], v[188:191], v[114:117]
	v_mfma_f32_16x16x32_bf16 v[102:105], v[148:151], v[196:199], v[102:105]
	v_mfma_f32_16x16x32_bf16 v[98:101], v[156:159], v[196:199], v[98:101]
	v_mfma_f32_16x16x32_bf16 v[86:89], v[148:151], v[204:207], v[86:89]
	v_mfma_f32_16x16x32_bf16 v[82:85], v[156:159], v[204:207], v[82:85]
	v_mfma_f32_16x16x32_bf16 v[126:129], v[152:155], v[184:187], v[126:129]
	v_mfma_f32_16x16x32_bf16 v[122:125], v[160:163], v[184:187], v[122:125]
	v_mfma_f32_16x16x32_bf16 v[118:121], v[152:155], v[192:195], v[118:121]
	v_mfma_f32_16x16x32_bf16 v[114:117], v[160:163], v[192:195], v[114:117]
	v_mfma_f32_16x16x32_bf16 v[102:105], v[152:155], v[200:203], v[102:105]
	v_mfma_f32_16x16x32_bf16 v[98:101], v[160:163], v[200:203], v[98:101]
	v_mfma_f32_16x16x32_bf16 v[86:89], v[152:155], v[208:211], v[86:89]
	v_mfma_f32_16x16x32_bf16 v[82:85], v[160:163], v[208:211], v[82:85]
	s_setprio 0
	s_setprio 1
	v_mfma_f32_16x16x32_bf16 v[110:113], v[164:167], v[180:183], v[110:113]
	v_mfma_f32_16x16x32_bf16 v[106:109], v[172:175], v[180:183], v[106:109]
	v_mfma_f32_16x16x32_bf16 v[94:97], v[164:167], v[188:191], v[94:97]
	v_mfma_f32_16x16x32_bf16 v[90:93], v[172:175], v[188:191], v[90:93]
	v_mfma_f32_16x16x32_bf16 v[78:81], v[164:167], v[196:199], v[78:81]
	v_mfma_f32_16x16x32_bf16 v[74:77], v[172:175], v[196:199], v[74:77]
	v_mfma_f32_16x16x32_bf16 v[70:73], v[164:167], v[204:207], v[70:73]
	v_mfma_f32_16x16x32_bf16 v[58:61], v[172:175], v[204:207], v[58:61]
	v_mfma_f32_16x16x32_bf16 v[110:113], v[168:171], v[184:187], v[110:113]
	v_mfma_f32_16x16x32_bf16 v[106:109], v[176:179], v[184:187], v[106:109]
	v_mfma_f32_16x16x32_bf16 v[94:97], v[168:171], v[192:195], v[94:97]
	v_mfma_f32_16x16x32_bf16 v[90:93], v[176:179], v[192:195], v[90:93]
	v_mfma_f32_16x16x32_bf16 v[78:81], v[168:171], v[200:203], v[78:81]
	v_mfma_f32_16x16x32_bf16 v[74:77], v[176:179], v[200:203], v[74:77]
	v_mfma_f32_16x16x32_bf16 v[70:73], v[168:171], v[208:211], v[70:73]
	v_mfma_f32_16x16x32_bf16 v[58:61], v[176:179], v[208:211], v[58:61]
	s_setprio 0
	s_barrier
; #define PG8_STAGE(bufoff, gbase, VO) do { _Pragma("unroll") for (int _i = 0; _i < 2; ++_i) \
;         __builtin_amdgcn_global_load_lds((const unsigned*)((const char*)(gbase) + VO[_i]), (LAS unsigned*)(lds + (bufoff) + ldsw + _i * 8192), 16, 0, 0); } while (0)
; #define PG8_LDA(dst, b, h) do { _Pragma("unroll") for (int m = 0; m < 4; ++m) _Pragma("unroll") for (int k = 0; k < 2; ++k) dst[m][k] = *(const LAS bf16x8*)(lds + PG8_SA(b, h) + aoff + m * 2048 + k * 1024); } while (0)
; #define PG8_MMA(ai, bj, At, Bt) do { __builtin_amdgcn_s_setprio(1); _Pragma("unroll") for (int m = 0; m < 4; ++m) _Pragma("unroll") for (int n = 0; n < 2; ++n) _Pragma("unroll") for (int k = 0; k < 2; ++k) \
;         acc[ai][bj][m][n] = __builtin_amdgcn_mfma_f32_16x16x32_bf16(Bt[n][k], At[m][k], acc[ai][bj][m][n], 0, 0, 0); __builtin_amdgcn_s_setprio(0); } while (0)
; #define PG8_WAIT_V(n) asm volatile("s_waitcnt vmcnt(" #n ")" ::: "memory")
; #define PG8_WAIT_L(n) asm volatile("s_waitcnt lgkmcnt(" #n ")" ::: "memory")
; #define PG8_BAR __builtin_amdgcn_s_barrier()
; #define PG8_SCHED __builtin_amdgcn_sched_barrier(0)
; template <int NSEG, class Epi, bool ALIGN_EPI = PG8_ALIGN, bool SP2 = PG8_SP2>
; DI void gemm_phase(LAS unsigned char* lds, const Gemm g, const StaticOrder& S, const Epi& E) {
;     ...
;             PG8_LDA(At, 1, 1); PG8_STAGE(PG8_SB(1, 0), b3, v2); PG8_STAGE(PG8_SB(1, 1), b3 + h2, v2); PG8_STAGE(PG8_SA(1, 0), a3, v2);
;             PG8_WAIT_V(8); PG8_WAIT_L(0); PG8_BAR; PG8_MMA(1, 0, At, B0); PG8_MMA(1, 1, At, B1); PG8_BAR; PG8_SCHED;
;     ...
;         if constexpr (ALIGN_EPI) { if (wr == 0) PG8_BAR; }
	s_add_i32 s26, s53, s38
	v_lshl_add_u64 v[212:213], v[212:213], 0, s[10:11]
	s_mov_b32 m0, s26
	ds_read_b128 v[180:183], v147 offset:49152
	ds_read_b128 v[184:187], v147 offset:50176
	ds_read_b128 v[188:191], v147 offset:51200
	ds_read_b128 v[192:195], v147 offset:52224
	ds_read_b128 v[196:199], v147 offset:53248
	ds_read_b128 v[200:203], v147 offset:54272
	ds_read_b128 v[204:207], v147 offset:55296
	ds_read_b128 v[208:211], v147 offset:56320
	global_load_lds_dwordx4 v[212:213], off
	s_add_i32 m0, s26, 0x2000
	s_add_u32 s24, s24, 0x80080
	v_lshl_add_u64 v[212:213], v[214:215], 0, s[10:11]
	s_addc_u32 s25, s25, 0
	s_add_i32 s26, s54, s38
	global_load_lds_dwordx4 v[212:213], off
	v_lshl_add_u64 v[212:213], s[24:25], 0, v[130:131]
	s_mov_b32 m0, s26
	s_nop 0
	global_load_lds_dwordx4 v[212:213], off
	v_lshl_add_u64 v[212:213], s[24:25], 0, v[132:133]
	s_add_i32 m0, s26, 0x2000
	s_nop 0
	global_load_lds_dwordx4 v[212:213], off
	v_lshl_add_u64 v[212:213], v[216:217], 0, s[10:11]
	s_mov_b32 m0, s46
	s_nop 0
	global_load_lds_dwordx4 v[212:213], off
	v_lshl_add_u64 v[212:213], v[218:219], 0, s[10:11]
	s_mov_b32 m0, s47
	s_nop 0
	global_load_lds_dwordx4 v[212:213], off
	s_waitcnt vmcnt(8)
	s_waitcnt lgkmcnt(0)
	s_setprio 1
	s_barrier
	v_mfma_f32_16x16x32_bf16 v[46:49], v[148:151], v[180:183], v[46:49]
	v_mfma_f32_16x16x32_bf16 v[42:45], v[156:159], v[180:183], v[42:45]
	v_mfma_f32_16x16x32_bf16 v[38:41], v[148:151], v[188:191], v[38:41]
	v_mfma_f32_16x16x32_bf16 v[34:37], v[156:159], v[188:191], v[34:37]
	v_mfma_f32_16x16x32_bf16 v[22:25], v[148:151], v[196:199], v[22:25]
	v_mfma_f32_16x16x32_bf16 v[18:21], v[156:159], v[196:199], v[18:21]
	v_mfma_f32_16x16x32_bf16 v[6:9], v[148:151], v[204:207], v[6:9]
	v_mfma_f32_16x16x32_bf16 v[2:5], v[156:159], v[204:207], v[2:5]
	v_mfma_f32_16x16x32_bf16 v[46:49], v[152:155], v[184:187], v[46:49]
	v_mfma_f32_16x16x32_bf16 v[42:45], v[160:163], v[184:187], v[42:45]
	v_mfma_f32_16x16x32_bf16 v[38:41], v[152:155], v[192:195], v[38:41]
	v_mfma_f32_16x16x32_bf16 v[34:37], v[160:163], v[192:195], v[34:37]
	v_mfma_f32_16x16x32_bf16 v[22:25], v[152:155], v[200:203], v[22:25]
	v_mfma_f32_16x16x32_bf16 v[18:21], v[160:163], v[200:203], v[18:21]
	v_mfma_f32_16x16x32_bf16 v[6:9], v[152:155], v[208:211], v[6:9]
	v_mfma_f32_16x16x32_bf16 v[2:5], v[160:163], v[208:211], v[2:5]
	s_setprio 0
	s_setprio 1
	v_mfma_f32_16x16x32_bf16 v[30:33], v[164:167], v[180:183], v[30:33]
	v_mfma_f32_16x16x32_bf16 v[26:29], v[172:175], v[180:183], v[26:29]
	v_mfma_f32_16x16x32_bf16 v[14:17], v[164:167], v[188:191], v[14:17]
	v_mfma_f32_16x16x32_bf16 v[10:13], v[172:175], v[188:191], v[10:13]
	v_mfma_f32_16x16x32_bf16 v[62:65], v[164:167], v[196:199], v[62:65]
	v_mfma_f32_16x16x32_bf16 v[66:69], v[172:175], v[196:199], v[66:69]
	v_mfma_f32_16x16x32_bf16 v[50:53], v[164:167], v[204:207], v[50:53]
	v_mfma_f32_16x16x32_bf16 v[54:57], v[172:175], v[204:207], v[54:57]
	v_mfma_f32_16x16x32_bf16 v[30:33], v[168:171], v[184:187], v[30:33]
	v_mfma_f32_16x16x32_bf16 v[26:29], v[176:179], v[184:187], v[26:29]
	v_mfma_f32_16x16x32_bf16 v[14:17], v[168:171], v[192:195], v[14:17]
	v_mfma_f32_16x16x32_bf16 v[10:13], v[176:179], v[192:195], v[10:13]
	v_mfma_f32_16x16x32_bf16 v[62:65], v[168:171], v[200:203], v[62:65]
	v_mfma_f32_16x16x32_bf16 v[66:69], v[176:179], v[200:203], v[66:69]
	v_mfma_f32_16x16x32_bf16 v[50:53], v[168:171], v[208:211], v[50:53]
	v_mfma_f32_16x16x32_bf16 v[54:57], v[176:179], v[208:211], v[54:57]
	s_setprio 0
	s_barrier
	s_add_i32 s52, s52, 2
	s_add_u32 s22, s22, 0x100
	s_addc_u32 s23, s23, 0
	s_add_u32 s17, s17, 0x100
	s_addc_u32 s19, s19, 0
	s_cmp_gt_u32 s52, 29
	s_cbranch_scc0 .LBB0_501
	s_and_b64 vcc, exec, s[12:13]
	s_cbranch_vccz .LBB0_504
	s_barrier

; #define PG8_STAGE(bufoff, gbase, VO) do { _Pragma("unroll") for (int _i = 0; _i < 2; ++_i) \
;         __builtin_amdgcn_global_load_lds((const unsigned*)((const char*)(gbase) + VO[_i]), (LAS unsigned*)(lds + (bufoff) + ldsw + _i * 8192), 16, 0, 0); } while (0)
; #define PG8_LDA(dst, b, h) do { _Pragma("unroll") for (int m = 0; m < 4; ++m) _Pragma("unroll") for (int k = 0; k < 2; ++k) dst[m][k] = *(const LAS bf16x8*)(lds + PG8_SA(b, h) + aoff + m * 2048 + k * 1024); } while (0)
; #define PG8_LDB(dst, b, h) do { _Pragma("unroll") for (int n = 0; n < 2; ++n) _Pragma("unroll") for (int k = 0; k < 2; ++k) dst[n][k] = *(const LAS bf16x8*)(lds + PG8_SB(b, h) + boff + n * 2048 + k * 1024); } while (0)
; #define PG8_MMA(ai, bj, At, Bt) do { __builtin_amdgcn_s_setprio(1); _Pragma("unroll") for (int m = 0; m < 4; ++m) _Pragma("unroll") for (int n = 0; n < 2; ++n) _Pragma("unroll") for (int k = 0; k < 2; ++k) \
;         acc[ai][bj][m][n] = __builtin_amdgcn_mfma_f32_16x16x32_bf16(Bt[n][k], At[m][k], acc[ai][bj][m][n], 0, 0, 0); __builtin_amdgcn_s_setprio(0); } while (0)
; #define PG8_BAR __builtin_amdgcn_s_barrier()
; template <int NSEG, class Epi, bool ALIGN_EPI = PG8_ALIGN, bool SP2 = PG8_SP2>
; DI void gemm_phase(LAS unsigned char* lds, const Gemm g, const StaticOrder& S, const Epi& E) {
;     ...
;         for (int t = 0; t < nt; t += 2) {
;             const bool last = (t == nt - 2);
;             const char* a1 = cA + (size_t)(t + 1) * kstep;
;             const char* a2 = last ? nA : cA + (size_t)(t + 2) * kstep; const char* b2 = last ? nB : cB + (size_t)(t + 2) * kstep;
;             const char* a3 = a2 + kstep; const char* b3 = b2 + kstep;
;             unsigned v2[2]; v2[0] = (NSEG > 1 && last) ? voffN[0] : voffC[0]; v2[1] = (NSEG > 1 && last) ? voffN[1] : voffC[1];
;             const size_t h2 = (NSEG > 1 && last) ? hstepN : hstepC;
;             if constexpr (SP2) {
;             PG8_LDB(B0, 0, 0); PG8_LDB(B1, 0, 1); PG8_SCHED; PG8_LDA(At, 0, 0); PG8_STAGE(PG8_SA(1, 1), a1 + hstepC, voffC);
;             PG8_WAIT_V(8); PG8_WAIT_L(0); PG8_BAR; PG8_MMA(0, 0, At, B0); PG8_MMA(0, 1, At, B1); PG8_BAR; PG8_SCHED;
;             PG8_LDA(At, 0, 1); PG8_STAGE(PG8_SB(0, 0), b2, v2); PG8_STAGE(PG8_SB(0, 1), b2 + h2, v2); PG8_STAGE(PG8_SA(0, 0), a2, v2);
;             PG8_WAIT_V(8); PG8_WAIT_L(0); PG8_BAR; PG8_MMA(1, 0, At, B0); PG8_MMA(1, 1, At, B1); PG8_BAR; PG8_SCHED;
.LBB0_545:
	ds_read_b128 v[102:105], v207
	ds_read_b128 v[106:109], v207 offset:1024
	ds_read_b128 v[110:113], v207 offset:2048
	ds_read_b128 v[114:117], v207 offset:3072
	ds_read_b128 v[118:121], v208
	ds_read_b128 v[122:125], v208 offset:1024
	ds_read_b128 v[126:129], v208 offset:2048
	ds_read_b128 v[130:133], v208 offset:3072
	s_add_i32 m0, s3, 0xc000
	ds_read_b128 v[162:165], v209
	ds_read_b128 v[166:169], v209 offset:1024
	ds_read_b128 v[170:173], v209 offset:2048
	ds_read_b128 v[188:191], v209 offset:3072
	ds_read_b128 v[192:195], v209 offset:4096
	ds_read_b128 v[196:199], v209 offset:5120
	ds_read_b128 v[200:203], v209 offset:6144
	ds_read_b128 v[212:215], v209 offset:7168
	global_load_lds_dwordx4 v178, s[4:5]
	s_add_i32 m0, s3, 0xe000
	s_nop 0
	global_load_lds_dwordx4 v180, s[4:5]
	s_waitcnt vmcnt(8)
	s_waitcnt lgkmcnt(0)
	s_setprio 1
	s_barrier
	v_mfma_f32_16x16x32_bf16 v[158:161], v[102:105], v[162:165], v[158:161]
	v_mfma_f32_16x16x32_bf16 v[154:157], v[110:113], v[162:165], v[154:157]
	s_add_u32 s34, s4, 0xfff80080
	s_addc_u32 s35, s5, -1
	v_mfma_f32_16x16x32_bf16 v[150:153], v[102:105], v[170:173], v[150:153]
	v_mfma_f32_16x16x32_bf16 v[146:149], v[110:113], v[170:173], v[146:149]
	s_cmp_eq_u32 s67, 28
	s_cselect_b32 s39, s1, s35
	v_mfma_f32_16x16x32_bf16 v[142:145], v[102:105], v[192:195], v[142:145]
	v_mfma_f32_16x16x32_bf16 v[138:141], v[110:113], v[192:195], v[138:141]
	s_cselect_b32 s38, s25, s34
	s_cselect_b32 s35, s27, s66
	v_mfma_f32_16x16x32_bf16 v[134:137], v[102:105], v[200:203], v[134:137]
	v_mfma_f32_16x16x32_bf16 v[98:101], v[110:113], v[200:203], v[98:101]
	s_cselect_b32 s34, s64, s65
	v_mfma_f32_16x16x32_bf16 v[158:161], v[106:109], v[166:169], v[158:161]
	v_mfma_f32_16x16x32_bf16 v[154:157], v[114:117], v[166:169], v[154:157]
	v_mfma_f32_16x16x32_bf16 v[150:153], v[106:109], v[188:191], v[150:153]
	v_mfma_f32_16x16x32_bf16 v[146:149], v[114:117], v[188:191], v[146:149]
	v_mfma_f32_16x16x32_bf16 v[142:145], v[106:109], v[196:199], v[142:145]
	v_mfma_f32_16x16x32_bf16 v[138:141], v[114:117], v[196:199], v[138:141]
	v_mfma_f32_16x16x32_bf16 v[134:137], v[106:109], v[212:215], v[134:137]
	v_mfma_f32_16x16x32_bf16 v[98:101], v[114:117], v[212:215], v[98:101]
	s_setprio 0
	s_setprio 1
	v_mfma_f32_16x16x32_bf16 v[62:65], v[118:121], v[162:165], v[62:65]
	v_mfma_f32_16x16x32_bf16 v[58:61], v[126:129], v[162:165], v[58:61]
	v_mfma_f32_16x16x32_bf16 v[54:57], v[118:121], v[170:173], v[54:57]
	v_mfma_f32_16x16x32_bf16 v[50:53], v[126:129], v[170:173], v[50:53]
	v_mfma_f32_16x16x32_bf16 v[46:49], v[118:121], v[192:195], v[46:49]
	v_mfma_f32_16x16x32_bf16 v[42:45], v[126:129], v[192:195], v[42:45]
	v_mfma_f32_16x16x32_bf16 v[38:41], v[118:121], v[200:203], v[38:41]
	v_mfma_f32_16x16x32_bf16 v[34:37], v[126:129], v[200:203], v[34:37]
	v_mfma_f32_16x16x32_bf16 v[62:65], v[122:125], v[166:169], v[62:65]
	v_mfma_f32_16x16x32_bf16 v[58:61], v[130:133], v[166:169], v[58:61]
	v_mfma_f32_16x16x32_bf16 v[54:57], v[122:125], v[188:191], v[54:57]
	v_mfma_f32_16x16x32_bf16 v[50:53], v[130:133], v[188:191], v[50:53]
	v_mfma_f32_16x16x32_bf16 v[46:49], v[122:125], v[196:199], v[46:49]
	v_mfma_f32_16x16x32_bf16 v[42:45], v[130:133], v[196:199], v[42:45]
	v_mfma_f32_16x16x32_bf16 v[38:41], v[122:125], v[212:215], v[38:41]
	v_mfma_f32_16x16x32_bf16 v[34:37], v[130:133], v[212:215], v[34:37]
	s_setprio 0
	s_barrier
	s_add_i32 s68, s58, s50
	v_lshl_add_u64 v[204:205], s[34:35], 0, v[174:175]
	s_mov_b32 m0, s68
	ds_read_b128 v[162:165], v209 offset:16384
	ds_read_b128 v[166:169], v209 offset:17408
	ds_read_b128 v[170:173], v209 offset:18432
	ds_read_b128 v[188:191], v209 offset:19456
	ds_read_b128 v[192:195], v209 offset:20480
	ds_read_b128 v[196:199], v209 offset:21504
	ds_read_b128 v[200:203], v209 offset:22528
	ds_read_b128 v[212:215], v209 offset:23552
	global_load_lds_dwordx4 v[204:205], off
	s_add_i32 m0, s68, 0x2000
	s_add_u32 s68, s34, 0x80000
	v_lshl_add_u64 v[216:217], s[34:35], 0, v[176:177]
	s_addc_u32 s69, s35, 0
	s_add_i32 s70, s59, s50
	global_load_lds_dwordx4 v[216:217], off
	v_lshl_add_u64 v[218:219], s[68:69], 0, v[174:175]
	s_mov_b32 m0, s70
	v_lshl_add_u64 v[220:221], s[38:39], 0, v[176:177]
	global_load_lds_dwordx4 v[218:219], off
	v_lshl_add_u64 v[218:219], s[68:69], 0, v[176:177]
	s_add_i32 m0, s70, 0x2000
	s_nop 0
	global_load_lds_dwordx4 v[218:219], off
	v_lshl_add_u64 v[218:219], s[38:39], 0, v[174:175]
	s_mov_b32 m0, s3
	s_nop 0
	global_load_lds_dwordx4 v[218:219], off
	s_mov_b32 m0, s52
	s_nop 0
	global_load_lds_dwordx4 v[220:221], off
	s_waitcnt vmcnt(8)
	s_waitcnt lgkmcnt(0)
	s_setprio 1
	s_barrier
; #define PG8_STAGE(bufoff, gbase, VO) do { _Pragma("unroll") for (int _i = 0; _i < 2; ++_i) \
;         __builtin_amdgcn_global_load_lds((const unsigned*)((const char*)(gbase) + VO[_i]), (LAS unsigned*)(lds + (bufoff) + ldsw + _i * 8192), 16, 0, 0); } while (0)
; #define PG8_LDA(dst, b, h) do { _Pragma("unroll") for (int m = 0; m < 4; ++m) _Pragma("unroll") for (int k = 0; k < 2; ++k) dst[m][k] = *(const LAS bf16x8*)(lds + PG8_SA(b, h) + aoff + m * 2048 + k * 1024); } while (0)
; #define PG8_LDB(dst, b, h) do { _Pragma("unroll") for (int n = 0; n < 2; ++n) _Pragma("unroll") for (int k = 0; k < 2; ++k) dst[n][k] = *(const LAS bf16x8*)(lds + PG8_SB(b, h) + boff + n * 2048 + k * 1024); } while (0)
; #define PG8_MMA(ai, bj, At, Bt) do { __builtin_amdgcn_s_setprio(1); _Pragma("unroll") for (int m = 0; m < 4; ++m) _Pragma("unroll") for (int n = 0; n < 2; ++n) _Pragma("unroll") for (int k = 0; k < 2; ++k) \
;         acc[ai][bj][m][n] = __builtin_amdgcn_mfma_f32_16x16x32_bf16(Bt[n][k], At[m][k], acc[ai][bj][m][n], 0, 0, 0); __builtin_amdgcn_s_setprio(0); } while (0)
; #define PG8_WAIT_V(n) asm volatile("s_waitcnt vmcnt(" #n ")" ::: "memory")
; #define PG8_WAIT_L(n) asm volatile("s_waitcnt lgkmcnt(" #n ")" ::: "memory")
; #define PG8_BAR __builtin_amdgcn_s_barrier()
; #define PG8_SCHED __builtin_amdgcn_sched_barrier(0)
; template <int NSEG, class Epi, bool ALIGN_EPI = PG8_ALIGN, bool SP2 = PG8_SP2>
; DI void gemm_phase(LAS unsigned char* lds, const Gemm g, const StaticOrder& S, const Epi& E) {
;     ...
;             PG8_WAIT_V(8); PG8_WAIT_L(0); PG8_BAR; PG8_MMA(1, 0, At, B0); PG8_MMA(1, 1, At, B1); PG8_BAR; PG8_SCHED;
;             PG8_LDB(B0, 1, 0); PG8_LDB(B1, 1, 1); PG8_SCHED; PG8_LDA(At, 1, 0); PG8_STAGE(PG8_SA(0, 1), a2 + h2, v2);
;             PG8_WAIT_V(8); PG8_WAIT_L(0); PG8_BAR; PG8_MMA(0, 0, At, B0); PG8_MMA(0, 1, At, B1); PG8_BAR; PG8_SCHED;
	v_mfma_f32_16x16x32_bf16 v[94:97], v[102:105], v[162:165], v[94:97]
	v_mfma_f32_16x16x32_bf16 v[90:93], v[110:113], v[162:165], v[90:93]
	v_mfma_f32_16x16x32_bf16 v[86:89], v[102:105], v[170:173], v[86:89]
	v_mfma_f32_16x16x32_bf16 v[82:85], v[110:113], v[170:173], v[82:85]
	v_mfma_f32_16x16x32_bf16 v[78:81], v[102:105], v[192:195], v[78:81]
	v_mfma_f32_16x16x32_bf16 v[74:77], v[110:113], v[192:195], v[74:77]
	v_mfma_f32_16x16x32_bf16 v[70:73], v[102:105], v[200:203], v[70:73]
	v_mfma_f32_16x16x32_bf16 v[66:69], v[110:113], v[200:203], v[66:69]
	v_mfma_f32_16x16x32_bf16 v[94:97], v[106:109], v[166:169], v[94:97]
	v_mfma_f32_16x16x32_bf16 v[90:93], v[114:117], v[166:169], v[90:93]
	v_mfma_f32_16x16x32_bf16 v[86:89], v[106:109], v[188:191], v[86:89]
	v_mfma_f32_16x16x32_bf16 v[82:85], v[114:117], v[188:191], v[82:85]
	v_mfma_f32_16x16x32_bf16 v[78:81], v[106:109], v[196:199], v[78:81]
	v_mfma_f32_16x16x32_bf16 v[74:77], v[114:117], v[196:199], v[74:77]
	v_mfma_f32_16x16x32_bf16 v[70:73], v[106:109], v[212:215], v[70:73]
	v_mfma_f32_16x16x32_bf16 v[66:69], v[114:117], v[212:215], v[66:69]
	s_setprio 0
	s_setprio 1
	v_mfma_f32_16x16x32_bf16 v[30:33], v[118:121], v[162:165], v[30:33]
	v_mfma_f32_16x16x32_bf16 v[26:29], v[126:129], v[162:165], v[26:29]
	v_mfma_f32_16x16x32_bf16 v[22:25], v[118:121], v[170:173], v[22:25]
	v_mfma_f32_16x16x32_bf16 v[14:17], v[126:129], v[170:173], v[14:17]
	v_mfma_f32_16x16x32_bf16 v[18:21], v[118:121], v[192:195], v[18:21]
	v_mfma_f32_16x16x32_bf16 v[10:13], v[126:129], v[192:195], v[10:13]
	v_mfma_f32_16x16x32_bf16 v[6:9], v[118:121], v[200:203], v[6:9]
	v_mfma_f32_16x16x32_bf16 v[2:5], v[126:129], v[200:203], v[2:5]
	v_mfma_f32_16x16x32_bf16 v[30:33], v[122:125], v[166:169], v[30:33]
	v_mfma_f32_16x16x32_bf16 v[26:29], v[130:133], v[166:169], v[26:29]
	v_mfma_f32_16x16x32_bf16 v[22:25], v[122:125], v[188:191], v[22:25]
	v_mfma_f32_16x16x32_bf16 v[14:17], v[130:133], v[188:191], v[14:17]
	v_mfma_f32_16x16x32_bf16 v[18:21], v[122:125], v[196:199], v[18:21]
	v_mfma_f32_16x16x32_bf16 v[10:13], v[130:133], v[196:199], v[10:13]
	v_mfma_f32_16x16x32_bf16 v[6:9], v[122:125], v[212:215], v[6:9]
	v_mfma_f32_16x16x32_bf16 v[2:5], v[130:133], v[212:215], v[2:5]
	s_setprio 0
	s_barrier
	s_add_i32 s68, 0, 0x18000
	s_add_i32 s69, 0, 0x1c000
	v_add_u32_e32 v114, s68, v187
	v_add_u32_e32 v130, s69, v187
	ds_read_b128 v[102:105], v114
	ds_read_b128 v[106:109], v114 offset:1024
	ds_read_b128 v[110:113], v114 offset:2048
	ds_read_b128 v[114:117], v114 offset:3072
	ds_read_b128 v[118:121], v130
	ds_read_b128 v[122:125], v130 offset:1024
	ds_read_b128 v[126:129], v130 offset:2048
	ds_read_b128 v[130:133], v130 offset:3072
	s_add_u32 s38, s38, 0x80000
	s_addc_u32 s39, s39, 0
	s_mov_b32 m0, s53
	v_lshl_add_u64 v[222:223], s[38:39], 0, v[174:175]
	ds_read_b128 v[162:165], v209 offset:32768
	ds_read_b128 v[166:169], v209 offset:33792
	ds_read_b128 v[170:173], v209 offset:34816
	ds_read_b128 v[188:191], v209 offset:35840
	ds_read_b128 v[192:195], v209 offset:36864
	ds_read_b128 v[196:199], v209 offset:37888
	ds_read_b128 v[200:203], v209 offset:38912
	ds_read_b128 v[212:215], v209 offset:39936
	global_load_lds_dwordx4 v[222:223], off
	v_lshl_add_u64 v[222:223], s[38:39], 0, v[176:177]
	s_mov_b32 m0, s54
	s_nop 0
	global_load_lds_dwordx4 v[222:223], off
	s_waitcnt vmcnt(8)
	s_waitcnt lgkmcnt(0)
	s_setprio 1
	s_barrier
	v_mfma_f32_16x16x32_bf16 v[158:161], v[102:105], v[162:165], v[158:161]
	v_mfma_f32_16x16x32_bf16 v[154:157], v[110:113], v[162:165], v[154:157]
	v_mfma_f32_16x16x32_bf16 v[150:153], v[102:105], v[170:173], v[150:153]
	v_mfma_f32_16x16x32_bf16 v[146:149], v[110:113], v[170:173], v[146:149]
	v_mfma_f32_16x16x32_bf16 v[142:145], v[102:105], v[192:195], v[142:145]
	v_mfma_f32_16x16x32_bf16 v[138:141], v[110:113], v[192:195], v[138:141]
	v_mfma_f32_16x16x32_bf16 v[134:137], v[102:105], v[200:203], v[134:137]
	v_mfma_f32_16x16x32_bf16 v[98:101], v[110:113], v[200:203], v[98:101]
	v_mfma_f32_16x16x32_bf16 v[158:161], v[106:109], v[166:169], v[158:161]
	v_mfma_f32_16x16x32_bf16 v[154:157], v[114:117], v[166:169], v[154:157]
	v_mfma_f32_16x16x32_bf16 v[150:153], v[106:109], v[188:191], v[150:153]
	v_mfma_f32_16x16x32_bf16 v[146:149], v[114:117], v[188:191], v[146:149]
	v_mfma_f32_16x16x32_bf16 v[142:145], v[106:109], v[196:199], v[142:145]
	v_mfma_f32_16x16x32_bf16 v[138:141], v[114:117], v[196:199], v[138:141]
	v_mfma_f32_16x16x32_bf16 v[134:137], v[106:109], v[212:215], v[134:137]
	v_mfma_f32_16x16x32_bf16 v[98:101], v[114:117], v[212:215], v[98:101]
	s_setprio 0
	s_setprio 1
	v_mfma_f32_16x16x32_bf16 v[62:65], v[118:121], v[162:165], v[62:65]
	v_mfma_f32_16x16x32_bf16 v[58:61], v[126:129], v[162:165], v[58:61]
	v_mfma_f32_16x16x32_bf16 v[54:57], v[118:121], v[170:173], v[54:57]
	v_mfma_f32_16x16x32_bf16 v[50:53], v[126:129], v[170:173], v[50:53]
	v_mfma_f32_16x16x32_bf16 v[46:49], v[118:121], v[192:195], v[46:49]
	v_mfma_f32_16x16x32_bf16 v[42:45], v[126:129], v[192:195], v[42:45]
	v_mfma_f32_16x16x32_bf16 v[38:41], v[118:121], v[200:203], v[38:41]
	v_mfma_f32_16x16x32_bf16 v[34:37], v[126:129], v[200:203], v[34:37]
	v_mfma_f32_16x16x32_bf16 v[62:65], v[122:125], v[166:169], v[62:65]
	v_mfma_f32_16x16x32_bf16 v[58:61], v[130:133], v[166:169], v[58:61]
	v_mfma_f32_16x16x32_bf16 v[54:57], v[122:125], v[188:191], v[54:57]
	v_mfma_f32_16x16x32_bf16 v[50:53], v[130:133], v[188:191], v[50:53]
	v_mfma_f32_16x16x32_bf16 v[46:49], v[122:125], v[196:199], v[46:49]
	v_mfma_f32_16x16x32_bf16 v[42:45], v[130:133], v[196:199], v[42:45]
	v_mfma_f32_16x16x32_bf16 v[38:41], v[122:125], v[212:215], v[38:41]
	v_mfma_f32_16x16x32_bf16 v[34:37], v[130:133], v[212:215], v[34:37]
	s_setprio 0
	s_barrier
; #define PG8_STAGE(bufoff, gbase, VO) do { _Pragma("unroll") for (int _i = 0; _i < 2; ++_i) \
;         __builtin_amdgcn_global_load_lds((const unsigned*)((const char*)(gbase) + VO[_i]), (LAS unsigned*)(lds + (bufoff) + ldsw + _i * 8192), 16, 0, 0); } while (0)
; #define PG8_LDA(dst, b, h) do { _Pragma("unroll") for (int m = 0; m < 4; ++m) _Pragma("unroll") for (int k = 0; k < 2; ++k) dst[m][k] = *(const LAS bf16x8*)(lds + PG8_SA(b, h) + aoff + m * 2048 + k * 1024); } while (0)
; #define PG8_MMA(ai, bj, At, Bt) do { __builtin_amdgcn_s_setprio(1); _Pragma("unroll") for (int m = 0; m < 4; ++m) _Pragma("unroll") for (int n = 0; n < 2; ++n) _Pragma("unroll") for (int k = 0; k < 2; ++k) \
;         acc[ai][bj][m][n] = __builtin_amdgcn_mfma_f32_16x16x32_bf16(Bt[n][k], At[m][k], acc[ai][bj][m][n], 0, 0, 0); __builtin_amdgcn_s_setprio(0); } while (0)
; #define PG8_WAIT_V(n) asm volatile("s_waitcnt vmcnt(" #n ")" ::: "memory")
; #define PG8_WAIT_L(n) asm volatile("s_waitcnt lgkmcnt(" #n ")" ::: "memory")
; #define PG8_BAR __builtin_amdgcn_s_barrier()
; #define PG8_SCHED __builtin_amdgcn_sched_barrier(0)
; template <int NSEG, class Epi, bool ALIGN_EPI = PG8_ALIGN, bool SP2 = PG8_SP2>
; DI void gemm_phase(LAS unsigned char* lds, const Gemm g, const StaticOrder& S, const Epi& E) {
;     ...
;             PG8_LDA(At, 1, 1); PG8_STAGE(PG8_SB(1, 0), b3, v2); PG8_STAGE(PG8_SB(1, 1), b3 + h2, v2); PG8_STAGE(PG8_SA(1, 0), a3, v2);
;             PG8_WAIT_V(8); PG8_WAIT_L(0); PG8_BAR; PG8_MMA(1, 0, At, B0); PG8_MMA(1, 1, At, B1); PG8_BAR; PG8_SCHED;
;     ...
;         if constexpr (ALIGN_EPI) { if (wr == 0) PG8_BAR; }
	s_add_i32 s38, s68, s50
	v_lshl_add_u64 v[204:205], v[204:205], 0, s[16:17]
	s_mov_b32 m0, s38
	ds_read_b128 v[162:165], v209 offset:49152
	ds_read_b128 v[166:169], v209 offset:50176
	ds_read_b128 v[170:173], v209 offset:51200
	ds_read_b128 v[188:191], v209 offset:52224
	ds_read_b128 v[192:195], v209 offset:53248
	ds_read_b128 v[196:199], v209 offset:54272
	ds_read_b128 v[200:203], v209 offset:55296
	ds_read_b128 v[212:215], v209 offset:56320
	global_load_lds_dwordx4 v[204:205], off
	s_add_i32 m0, s38, 0x2000
	s_add_u32 s34, s34, 0x80080
	v_lshl_add_u64 v[204:205], v[216:217], 0, s[16:17]
	s_addc_u32 s35, s35, 0
	s_add_i32 s38, s69, s50
	global_load_lds_dwordx4 v[204:205], off
	v_lshl_add_u64 v[204:205], s[34:35], 0, v[174:175]
	s_mov_b32 m0, s38
	s_nop 0
	global_load_lds_dwordx4 v[204:205], off
	v_lshl_add_u64 v[204:205], s[34:35], 0, v[176:177]
	s_add_i32 m0, s38, 0x2000
	s_nop 0
	global_load_lds_dwordx4 v[204:205], off
	v_lshl_add_u64 v[204:205], v[218:219], 0, s[16:17]
	s_mov_b32 m0, s55
	s_nop 0
	global_load_lds_dwordx4 v[204:205], off
	v_lshl_add_u64 v[204:205], v[220:221], 0, s[16:17]
	s_mov_b32 m0, s56
	s_nop 0
	global_load_lds_dwordx4 v[204:205], off
	s_waitcnt vmcnt(8)
	s_waitcnt lgkmcnt(0)
	s_setprio 1
	s_barrier
	v_mfma_f32_16x16x32_bf16 v[94:97], v[102:105], v[162:165], v[94:97]
	v_mfma_f32_16x16x32_bf16 v[90:93], v[110:113], v[162:165], v[90:93]
	v_mfma_f32_16x16x32_bf16 v[86:89], v[102:105], v[170:173], v[86:89]
	v_mfma_f32_16x16x32_bf16 v[82:85], v[110:113], v[170:173], v[82:85]
	v_mfma_f32_16x16x32_bf16 v[78:81], v[102:105], v[192:195], v[78:81]
	v_mfma_f32_16x16x32_bf16 v[74:77], v[110:113], v[192:195], v[74:77]
	v_mfma_f32_16x16x32_bf16 v[70:73], v[102:105], v[200:203], v[70:73]
	v_mfma_f32_16x16x32_bf16 v[66:69], v[110:113], v[200:203], v[66:69]
	v_mfma_f32_16x16x32_bf16 v[94:97], v[106:109], v[166:169], v[94:97]
	v_mfma_f32_16x16x32_bf16 v[90:93], v[114:117], v[166:169], v[90:93]
	v_mfma_f32_16x16x32_bf16 v[86:89], v[106:109], v[188:191], v[86:89]
	v_mfma_f32_16x16x32_bf16 v[82:85], v[114:117], v[188:191], v[82:85]
	v_mfma_f32_16x16x32_bf16 v[78:81], v[106:109], v[196:199], v[78:81]
	v_mfma_f32_16x16x32_bf16 v[74:77], v[114:117], v[196:199], v[74:77]
	v_mfma_f32_16x16x32_bf16 v[70:73], v[106:109], v[212:215], v[70:73]
	v_mfma_f32_16x16x32_bf16 v[66:69], v[114:117], v[212:215], v[66:69]
	s_setprio 0
	s_setprio 1
	v_mfma_f32_16x16x32_bf16 v[30:33], v[118:121], v[162:165], v[30:33]
	v_mfma_f32_16x16x32_bf16 v[26:29], v[126:129], v[162:165], v[26:29]
	v_mfma_f32_16x16x32_bf16 v[22:25], v[118:121], v[170:173], v[22:25]
	v_mfma_f32_16x16x32_bf16 v[14:17], v[126:129], v[170:173], v[14:17]
	v_mfma_f32_16x16x32_bf16 v[18:21], v[118:121], v[192:195], v[18:21]
	v_mfma_f32_16x16x32_bf16 v[10:13], v[126:129], v[192:195], v[10:13]
	v_mfma_f32_16x16x32_bf16 v[6:9], v[118:121], v[200:203], v[6:9]
	v_mfma_f32_16x16x32_bf16 v[2:5], v[126:129], v[200:203], v[2:5]
	v_mfma_f32_16x16x32_bf16 v[30:33], v[122:125], v[166:169], v[30:33]
	v_mfma_f32_16x16x32_bf16 v[26:29], v[130:133], v[166:169], v[26:29]
	v_mfma_f32_16x16x32_bf16 v[22:25], v[122:125], v[188:191], v[22:25]
	v_mfma_f32_16x16x32_bf16 v[14:17], v[130:133], v[188:191], v[14:17]
	v_mfma_f32_16x16x32_bf16 v[18:21], v[122:125], v[196:199], v[18:21]
	v_mfma_f32_16x16x32_bf16 v[10:13], v[130:133], v[196:199], v[10:13]
	v_mfma_f32_16x16x32_bf16 v[6:9], v[122:125], v[212:215], v[6:9]
	v_mfma_f32_16x16x32_bf16 v[2:5], v[130:133], v[212:215], v[2:5]
	s_setprio 0
	s_barrier
	s_add_i32 s67, s67, 2
	s_add_u32 s4, s4, 0x100
	s_addc_u32 s5, s5, 0
	s_add_u32 s65, s65, 0x100
	s_addc_u32 s66, s66, 0
	s_cmp_gt_u32 s67, 29
	s_cbranch_scc0 .LBB0_545
	s_and_b64 vcc, exec, s[18:19]
	s_cbranch_vccz .LBB0_548
	s_barrier

; #define PG8_STAGE(bufoff, gbase, VO) do { _Pragma("unroll") for (int _i = 0; _i < 2; ++_i) \
;         __builtin_amdgcn_global_load_lds((const unsigned*)((const char*)(gbase) + VO[_i]), (LAS unsigned*)(lds + (bufoff) + ldsw + _i * 8192), 16, 0, 0); } while (0)
; #define PG8_LDA(dst, b, h) do { _Pragma("unroll") for (int m = 0; m < 4; ++m) _Pragma("unroll") for (int k = 0; k < 2; ++k) dst[m][k] = *(const LAS bf16x8*)(lds + PG8_SA(b, h) + aoff + m * 2048 + k * 1024); } while (0)
; #define PG8_LDB(dst, b, h) do { _Pragma("unroll") for (int n = 0; n < 2; ++n) _Pragma("unroll") for (int k = 0; k < 2; ++k) dst[n][k] = *(const LAS bf16x8*)(lds + PG8_SB(b, h) + boff + n * 2048 + k * 1024); } while (0)
; #define PG8_MMA(ai, bj, At, Bt) do { __builtin_amdgcn_s_setprio(1); _Pragma("unroll") for (int m = 0; m < 4; ++m) _Pragma("unroll") for (int n = 0; n < 2; ++n) _Pragma("unroll") for (int k = 0; k < 2; ++k) \
;         acc[ai][bj][m][n] = __builtin_amdgcn_mfma_f32_16x16x32_bf16(Bt[n][k], At[m][k], acc[ai][bj][m][n], 0, 0, 0); __builtin_amdgcn_s_setprio(0); } while (0)
; #define PG8_BAR __builtin_amdgcn_s_barrier()
; template <int NSEG, class Epi, bool ALIGN_EPI = PG8_ALIGN, bool SP2 = PG8_SP2>
; DI void gemm_phase(LAS unsigned char* lds, const Gemm g, const StaticOrder& S, const Epi& E) {
;     ...
;         for (int t = 0; t < nt; t += 2) {
;             const bool last = (t == nt - 2);
;             const char* a1 = cA + (size_t)(t + 1) * kstep;
;             const char* a2 = last ? nA : cA + (size_t)(t + 2) * kstep; const char* b2 = last ? nB : cB + (size_t)(t + 2) * kstep;
;             const char* a3 = a2 + kstep; const char* b3 = b2 + kstep;
;             unsigned v2[2]; v2[0] = (NSEG > 1 && last) ? voffN[0] : voffC[0]; v2[1] = (NSEG > 1 && last) ? voffN[1] : voffC[1];
;             const size_t h2 = (NSEG > 1 && last) ? hstepN : hstepC;
;             if constexpr (SP2) {
;             PG8_LDB(B0, 0, 0); PG8_LDB(B1, 0, 1); PG8_SCHED; PG8_LDA(At, 0, 0); PG8_STAGE(PG8_SA(1, 1), a1 + hstepC, voffC);
;             PG8_WAIT_V(8); PG8_WAIT_L(0); PG8_BAR; PG8_MMA(0, 0, At, B0); PG8_MMA(0, 1, At, B1); PG8_BAR; PG8_SCHED;
;             PG8_LDA(At, 0, 1); PG8_STAGE(PG8_SB(0, 0), b2, v2); PG8_STAGE(PG8_SB(0, 1), b2 + h2, v2); PG8_STAGE(PG8_SA(0, 0), a2, v2);
;             PG8_WAIT_V(8); PG8_WAIT_L(0); PG8_BAR; PG8_MMA(1, 0, At, B0); PG8_MMA(1, 1, At, B1); PG8_BAR; PG8_SCHED;
.LBB0_599:
	ds_read_b128 v[146:149], v143
	ds_read_b128 v[150:153], v143 offset:1024
	ds_read_b128 v[154:157], v143 offset:2048
	ds_read_b128 v[158:161], v143 offset:3072
	ds_read_b128 v[162:165], v144
	ds_read_b128 v[166:169], v144 offset:1024
	ds_read_b128 v[170:173], v144 offset:2048
	ds_read_b128 v[174:177], v144 offset:3072
	s_add_i32 m0, s45, 0xc000
	ds_read_b128 v[178:181], v145
	ds_read_b128 v[182:185], v145 offset:1024
	ds_read_b128 v[186:189], v145 offset:2048
	ds_read_b128 v[190:193], v145 offset:3072
	ds_read_b128 v[194:197], v145 offset:4096
	ds_read_b128 v[198:201], v145 offset:5120
	ds_read_b128 v[202:205], v145 offset:6144
	ds_read_b128 v[206:209], v145 offset:7168
	global_load_lds_dwordx4 v134, s[26:27]
	s_add_i32 m0, s45, 0xe000
	s_nop 0
	global_load_lds_dwordx4 v136, s[26:27]
	s_waitcnt vmcnt(8)
	s_waitcnt lgkmcnt(0)
	s_setprio 1
	s_barrier
	v_mfma_f32_16x16x32_bf16 v[126:129], v[146:149], v[178:181], v[126:129]
	v_mfma_f32_16x16x32_bf16 v[122:125], v[154:157], v[178:181], v[122:125]
	s_add_u32 s34, s26, 0xffea0080
	s_addc_u32 s35, s27, -1
	v_mfma_f32_16x16x32_bf16 v[118:121], v[146:149], v[186:189], v[118:121]
	v_mfma_f32_16x16x32_bf16 v[114:117], v[154:157], v[186:189], v[114:117]
	s_cmpk_eq_i32 s64, 0x54
	s_cselect_b32 s37, s23, s35
	v_mfma_f32_16x16x32_bf16 v[102:105], v[146:149], v[194:197], v[102:105]
	v_mfma_f32_16x16x32_bf16 v[98:101], v[154:157], v[194:197], v[98:101]
	s_cselect_b32 s36, s22, s34
	s_cselect_b32 s35, s25, s63
	v_mfma_f32_16x16x32_bf16 v[86:89], v[146:149], v[202:205], v[86:89]
	v_mfma_f32_16x16x32_bf16 v[82:85], v[154:157], v[202:205], v[82:85]
	s_cselect_b32 s34, s24, s62
	v_mfma_f32_16x16x32_bf16 v[126:129], v[150:153], v[182:185], v[126:129]
	v_mfma_f32_16x16x32_bf16 v[122:125], v[158:161], v[182:185], v[122:125]
	v_mfma_f32_16x16x32_bf16 v[118:121], v[150:153], v[190:193], v[118:121]
	v_mfma_f32_16x16x32_bf16 v[114:117], v[158:161], v[190:193], v[114:117]
	v_mfma_f32_16x16x32_bf16 v[102:105], v[150:153], v[198:201], v[102:105]
	v_mfma_f32_16x16x32_bf16 v[98:101], v[158:161], v[198:201], v[98:101]
	v_mfma_f32_16x16x32_bf16 v[86:89], v[150:153], v[206:209], v[86:89]
	v_mfma_f32_16x16x32_bf16 v[82:85], v[158:161], v[206:209], v[82:85]
	s_setprio 0
	s_setprio 1
	v_mfma_f32_16x16x32_bf16 v[110:113], v[162:165], v[178:181], v[110:113]
	v_mfma_f32_16x16x32_bf16 v[106:109], v[170:173], v[178:181], v[106:109]
	v_mfma_f32_16x16x32_bf16 v[94:97], v[162:165], v[186:189], v[94:97]
	v_mfma_f32_16x16x32_bf16 v[90:93], v[170:173], v[186:189], v[90:93]
	v_mfma_f32_16x16x32_bf16 v[78:81], v[162:165], v[194:197], v[78:81]
	v_mfma_f32_16x16x32_bf16 v[74:77], v[170:173], v[194:197], v[74:77]
	v_mfma_f32_16x16x32_bf16 v[70:73], v[162:165], v[202:205], v[70:73]
	v_mfma_f32_16x16x32_bf16 v[66:69], v[170:173], v[202:205], v[66:69]
	v_mfma_f32_16x16x32_bf16 v[110:113], v[166:169], v[182:185], v[110:113]
	v_mfma_f32_16x16x32_bf16 v[106:109], v[174:177], v[182:185], v[106:109]
	v_mfma_f32_16x16x32_bf16 v[94:97], v[166:169], v[190:193], v[94:97]
	v_mfma_f32_16x16x32_bf16 v[90:93], v[174:177], v[190:193], v[90:93]
	v_mfma_f32_16x16x32_bf16 v[78:81], v[166:169], v[198:201], v[78:81]
	v_mfma_f32_16x16x32_bf16 v[74:77], v[174:177], v[198:201], v[74:77]
	v_mfma_f32_16x16x32_bf16 v[70:73], v[166:169], v[206:209], v[70:73]
	v_mfma_f32_16x16x32_bf16 v[66:69], v[174:177], v[206:209], v[66:69]
	s_setprio 0
	s_barrier
	s_add_i32 s65, s52, s44
	v_lshl_add_u64 v[210:211], s[34:35], 0, v[130:131]
	s_mov_b32 m0, s65
	ds_read_b128 v[178:181], v145 offset:16384
	ds_read_b128 v[182:185], v145 offset:17408
	ds_read_b128 v[186:189], v145 offset:18432
	ds_read_b128 v[190:193], v145 offset:19456
	ds_read_b128 v[194:197], v145 offset:20480
	ds_read_b128 v[198:201], v145 offset:21504
	ds_read_b128 v[202:205], v145 offset:22528
	ds_read_b128 v[206:209], v145 offset:23552
	global_load_lds_dwordx4 v[210:211], off
	s_add_i32 m0, s65, 0x2000
	s_add_u32 s66, s34, 0x160000
	v_lshl_add_u64 v[212:213], s[34:35], 0, v[132:133]
	s_addc_u32 s67, s35, 0
	s_add_i32 s65, s53, s44
	global_load_lds_dwordx4 v[212:213], off
	v_lshl_add_u64 v[214:215], s[66:67], 0, v[130:131]
	s_mov_b32 m0, s65
	v_lshl_add_u64 v[216:217], s[36:37], 0, v[132:133]
	global_load_lds_dwordx4 v[214:215], off
	v_lshl_add_u64 v[214:215], s[66:67], 0, v[132:133]
	s_add_i32 m0, s65, 0x2000
	s_nop 0
	global_load_lds_dwordx4 v[214:215], off
	v_lshl_add_u64 v[214:215], s[36:37], 0, v[130:131]
	s_mov_b32 m0, s45
	s_nop 0
	global_load_lds_dwordx4 v[214:215], off
	s_mov_b32 m0, s46
	s_nop 0
	global_load_lds_dwordx4 v[216:217], off
	s_waitcnt vmcnt(8)
	s_waitcnt lgkmcnt(0)
	s_setprio 1
	s_barrier
; #define PG8_STAGE(bufoff, gbase, VO) do { _Pragma("unroll") for (int _i = 0; _i < 2; ++_i) \
;         __builtin_amdgcn_global_load_lds((const unsigned*)((const char*)(gbase) + VO[_i]), (LAS unsigned*)(lds + (bufoff) + ldsw + _i * 8192), 16, 0, 0); } while (0)
; #define PG8_LDA(dst, b, h) do { _Pragma("unroll") for (int m = 0; m < 4; ++m) _Pragma("unroll") for (int k = 0; k < 2; ++k) dst[m][k] = *(const LAS bf16x8*)(lds + PG8_SA(b, h) + aoff + m * 2048 + k * 1024); } while (0)
; #define PG8_LDB(dst, b, h) do { _Pragma("unroll") for (int n = 0; n < 2; ++n) _Pragma("unroll") for (int k = 0; k < 2; ++k) dst[n][k] = *(const LAS bf16x8*)(lds + PG8_SB(b, h) + boff + n * 2048 + k * 1024); } while (0)
; #define PG8_MMA(ai, bj, At, Bt) do { __builtin_amdgcn_s_setprio(1); _Pragma("unroll") for (int m = 0; m < 4; ++m) _Pragma("unroll") for (int n = 0; n < 2; ++n) _Pragma("unroll") for (int k = 0; k < 2; ++k) \
;         acc[ai][bj][m][n] = __builtin_amdgcn_mfma_f32_16x16x32_bf16(Bt[n][k], At[m][k], acc[ai][bj][m][n], 0, 0, 0); __builtin_amdgcn_s_setprio(0); } while (0)
; #define PG8_WAIT_V(n) asm volatile("s_waitcnt vmcnt(" #n ")" ::: "memory")
; #define PG8_WAIT_L(n) asm volatile("s_waitcnt lgkmcnt(" #n ")" ::: "memory")
; #define PG8_BAR __builtin_amdgcn_s_barrier()
; #define PG8_SCHED __builtin_amdgcn_sched_barrier(0)
; template <int NSEG, class Epi, bool ALIGN_EPI = PG8_ALIGN, bool SP2 = PG8_SP2>
; DI void gemm_phase(LAS unsigned char* lds, const Gemm g, const StaticOrder& S, const Epi& E) {
;     ...
;             PG8_WAIT_V(8); PG8_WAIT_L(0); PG8_BAR; PG8_MMA(1, 0, At, B0); PG8_MMA(1, 1, At, B1); PG8_BAR; PG8_SCHED;
;             PG8_LDB(B0, 1, 0); PG8_LDB(B1, 1, 1); PG8_SCHED; PG8_LDA(At, 1, 0); PG8_STAGE(PG8_SA(0, 1), a2 + h2, v2);
;             PG8_WAIT_V(8); PG8_WAIT_L(0); PG8_BAR; PG8_MMA(0, 0, At, B0); PG8_MMA(0, 1, At, B1); PG8_BAR; PG8_SCHED;
	v_mfma_f32_16x16x32_bf16 v[54:57], v[146:149], v[178:181], v[54:57]
	v_mfma_f32_16x16x32_bf16 v[46:49], v[154:157], v[178:181], v[46:49]
	v_mfma_f32_16x16x32_bf16 v[38:41], v[146:149], v[186:189], v[38:41]
	v_mfma_f32_16x16x32_bf16 v[34:37], v[154:157], v[186:189], v[34:37]
	v_mfma_f32_16x16x32_bf16 v[22:25], v[146:149], v[194:197], v[22:25]
	v_mfma_f32_16x16x32_bf16 v[18:21], v[154:157], v[194:197], v[18:21]
	v_mfma_f32_16x16x32_bf16 v[6:9], v[146:149], v[202:205], v[6:9]
	v_mfma_f32_16x16x32_bf16 v[2:5], v[154:157], v[202:205], v[2:5]
	v_mfma_f32_16x16x32_bf16 v[54:57], v[150:153], v[182:185], v[54:57]
	v_mfma_f32_16x16x32_bf16 v[46:49], v[158:161], v[182:185], v[46:49]
	v_mfma_f32_16x16x32_bf16 v[38:41], v[150:153], v[190:193], v[38:41]
	v_mfma_f32_16x16x32_bf16 v[34:37], v[158:161], v[190:193], v[34:37]
	v_mfma_f32_16x16x32_bf16 v[22:25], v[150:153], v[198:201], v[22:25]
	v_mfma_f32_16x16x32_bf16 v[18:21], v[158:161], v[198:201], v[18:21]
	v_mfma_f32_16x16x32_bf16 v[6:9], v[150:153], v[206:209], v[6:9]
	v_mfma_f32_16x16x32_bf16 v[2:5], v[158:161], v[206:209], v[2:5]
	s_setprio 0
	s_setprio 1
	v_mfma_f32_16x16x32_bf16 v[30:33], v[162:165], v[178:181], v[30:33]
	v_mfma_f32_16x16x32_bf16 v[26:29], v[170:173], v[178:181], v[26:29]
	v_mfma_f32_16x16x32_bf16 v[14:17], v[162:165], v[186:189], v[14:17]
	v_mfma_f32_16x16x32_bf16 v[10:13], v[170:173], v[186:189], v[10:13]
	v_mfma_f32_16x16x32_bf16 v[58:61], v[162:165], v[194:197], v[58:61]
	v_mfma_f32_16x16x32_bf16 v[62:65], v[170:173], v[194:197], v[62:65]
	v_mfma_f32_16x16x32_bf16 v[42:45], v[162:165], v[202:205], v[42:45]
	v_mfma_f32_16x16x32_bf16 v[50:53], v[170:173], v[202:205], v[50:53]
	v_mfma_f32_16x16x32_bf16 v[30:33], v[166:169], v[182:185], v[30:33]
	v_mfma_f32_16x16x32_bf16 v[26:29], v[174:177], v[182:185], v[26:29]
	v_mfma_f32_16x16x32_bf16 v[14:17], v[166:169], v[190:193], v[14:17]
	v_mfma_f32_16x16x32_bf16 v[10:13], v[174:177], v[190:193], v[10:13]
	v_mfma_f32_16x16x32_bf16 v[58:61], v[166:169], v[198:201], v[58:61]
	v_mfma_f32_16x16x32_bf16 v[62:65], v[174:177], v[198:201], v[62:65]
	v_mfma_f32_16x16x32_bf16 v[42:45], v[166:169], v[206:209], v[42:45]
	v_mfma_f32_16x16x32_bf16 v[50:53], v[174:177], v[206:209], v[50:53]
	s_setprio 0
	s_barrier
	s_add_i32 s65, 0, 0x18000
	s_add_i32 s66, 0, 0x1c000
	v_add_u32_e32 v158, s65, v141
	v_add_u32_e32 v174, s66, v141
	ds_read_b128 v[146:149], v158
	ds_read_b128 v[150:153], v158 offset:1024
	ds_read_b128 v[154:157], v158 offset:2048
	ds_read_b128 v[158:161], v158 offset:3072
	ds_read_b128 v[162:165], v174
	ds_read_b128 v[166:169], v174 offset:1024
	ds_read_b128 v[170:173], v174 offset:2048
	ds_read_b128 v[174:177], v174 offset:3072
	s_add_u32 s36, s36, 0x160000
	s_addc_u32 s37, s37, 0
	s_mov_b32 m0, s47
	v_lshl_add_u64 v[218:219], s[36:37], 0, v[130:131]
	ds_read_b128 v[178:181], v145 offset:32768
	ds_read_b128 v[182:185], v145 offset:33792
	ds_read_b128 v[186:189], v145 offset:34816
	ds_read_b128 v[190:193], v145 offset:35840
	ds_read_b128 v[194:197], v145 offset:36864
	ds_read_b128 v[198:201], v145 offset:37888
	ds_read_b128 v[202:205], v145 offset:38912
	ds_read_b128 v[206:209], v145 offset:39936
	global_load_lds_dwordx4 v[218:219], off
	v_lshl_add_u64 v[218:219], s[36:37], 0, v[132:133]
	s_mov_b32 m0, s48
	s_nop 0
	global_load_lds_dwordx4 v[218:219], off
	s_waitcnt vmcnt(8)
	s_waitcnt lgkmcnt(0)
	s_setprio 1
	s_barrier
	v_mfma_f32_16x16x32_bf16 v[126:129], v[146:149], v[178:181], v[126:129]
	v_mfma_f32_16x16x32_bf16 v[122:125], v[154:157], v[178:181], v[122:125]
	v_mfma_f32_16x16x32_bf16 v[118:121], v[146:149], v[186:189], v[118:121]
	v_mfma_f32_16x16x32_bf16 v[114:117], v[154:157], v[186:189], v[114:117]
	v_mfma_f32_16x16x32_bf16 v[102:105], v[146:149], v[194:197], v[102:105]
	v_mfma_f32_16x16x32_bf16 v[98:101], v[154:157], v[194:197], v[98:101]
	v_mfma_f32_16x16x32_bf16 v[86:89], v[146:149], v[202:205], v[86:89]
	v_mfma_f32_16x16x32_bf16 v[82:85], v[154:157], v[202:205], v[82:85]
	v_mfma_f32_16x16x32_bf16 v[126:129], v[150:153], v[182:185], v[126:129]
	v_mfma_f32_16x16x32_bf16 v[122:125], v[158:161], v[182:185], v[122:125]
	v_mfma_f32_16x16x32_bf16 v[118:121], v[150:153], v[190:193], v[118:121]
	v_mfma_f32_16x16x32_bf16 v[114:117], v[158:161], v[190:193], v[114:117]
	v_mfma_f32_16x16x32_bf16 v[102:105], v[150:153], v[198:201], v[102:105]
	v_mfma_f32_16x16x32_bf16 v[98:101], v[158:161], v[198:201], v[98:101]
	v_mfma_f32_16x16x32_bf16 v[86:89], v[150:153], v[206:209], v[86:89]
	v_mfma_f32_16x16x32_bf16 v[82:85], v[158:161], v[206:209], v[82:85]
	s_setprio 0
	s_setprio 1
	v_mfma_f32_16x16x32_bf16 v[110:113], v[162:165], v[178:181], v[110:113]
	v_mfma_f32_16x16x32_bf16 v[106:109], v[170:173], v[178:181], v[106:109]
	v_mfma_f32_16x16x32_bf16 v[94:97], v[162:165], v[186:189], v[94:97]
	v_mfma_f32_16x16x32_bf16 v[90:93], v[170:173], v[186:189], v[90:93]
	v_mfma_f32_16x16x32_bf16 v[78:81], v[162:165], v[194:197], v[78:81]
	v_mfma_f32_16x16x32_bf16 v[74:77], v[170:173], v[194:197], v[74:77]
	v_mfma_f32_16x16x32_bf16 v[70:73], v[162:165], v[202:205], v[70:73]
	v_mfma_f32_16x16x32_bf16 v[66:69], v[170:173], v[202:205], v[66:69]
	v_mfma_f32_16x16x32_bf16 v[110:113], v[166:169], v[182:185], v[110:113]
	v_mfma_f32_16x16x32_bf16 v[106:109], v[174:177], v[182:185], v[106:109]
	v_mfma_f32_16x16x32_bf16 v[94:97], v[166:169], v[190:193], v[94:97]
	v_mfma_f32_16x16x32_bf16 v[90:93], v[174:177], v[190:193], v[90:93]
	v_mfma_f32_16x16x32_bf16 v[78:81], v[166:169], v[198:201], v[78:81]
	v_mfma_f32_16x16x32_bf16 v[74:77], v[174:177], v[198:201], v[74:77]
	v_mfma_f32_16x16x32_bf16 v[70:73], v[166:169], v[206:209], v[70:73]
	v_mfma_f32_16x16x32_bf16 v[66:69], v[174:177], v[206:209], v[66:69]
	s_setprio 0
	s_barrier
; #define PG8_STAGE(bufoff, gbase, VO) do { _Pragma("unroll") for (int _i = 0; _i < 2; ++_i) \
;         __builtin_amdgcn_global_load_lds((const unsigned*)((const char*)(gbase) + VO[_i]), (LAS unsigned*)(lds + (bufoff) + ldsw + _i * 8192), 16, 0, 0); } while (0)
; #define PG8_LDA(dst, b, h) do { _Pragma("unroll") for (int m = 0; m < 4; ++m) _Pragma("unroll") for (int k = 0; k < 2; ++k) dst[m][k] = *(const LAS bf16x8*)(lds + PG8_SA(b, h) + aoff + m * 2048 + k * 1024); } while (0)
; #define PG8_MMA(ai, bj, At, Bt) do { __builtin_amdgcn_s_setprio(1); _Pragma("unroll") for (int m = 0; m < 4; ++m) _Pragma("unroll") for (int n = 0; n < 2; ++n) _Pragma("unroll") for (int k = 0; k < 2; ++k) \
;         acc[ai][bj][m][n] = __builtin_amdgcn_mfma_f32_16x16x32_bf16(Bt[n][k], At[m][k], acc[ai][bj][m][n], 0, 0, 0); __builtin_amdgcn_s_setprio(0); } while (0)
; #define PG8_WAIT_V(n) asm volatile("s_waitcnt vmcnt(" #n ")" ::: "memory")
; #define PG8_WAIT_L(n) asm volatile("s_waitcnt lgkmcnt(" #n ")" ::: "memory")
; #define PG8_BAR __builtin_amdgcn_s_barrier()
; #define PG8_SCHED __builtin_amdgcn_sched_barrier(0)
; template <int NSEG, class Epi, bool ALIGN_EPI = PG8_ALIGN, bool SP2 = PG8_SP2>
; DI void gemm_phase(LAS unsigned char* lds, const Gemm g, const StaticOrder& S, const Epi& E) {
;     ...
;             PG8_LDA(At, 1, 1); PG8_STAGE(PG8_SB(1, 0), b3, v2); PG8_STAGE(PG8_SB(1, 1), b3 + h2, v2); PG8_STAGE(PG8_SA(1, 0), a3, v2);
;             PG8_WAIT_V(8); PG8_WAIT_L(0); PG8_BAR; PG8_MMA(1, 0, At, B0); PG8_MMA(1, 1, At, B1); PG8_BAR; PG8_SCHED;
;     ...
;         if constexpr (ALIGN_EPI) { if (wr == 0) PG8_BAR; }
	s_add_i32 s36, s65, s44
	v_lshl_add_u64 v[210:211], v[210:211], 0, s[10:11]
	s_mov_b32 m0, s36
	ds_read_b128 v[178:181], v145 offset:49152
	ds_read_b128 v[182:185], v145 offset:50176
	ds_read_b128 v[186:189], v145 offset:51200
	ds_read_b128 v[190:193], v145 offset:52224
	ds_read_b128 v[194:197], v145 offset:53248
	ds_read_b128 v[198:201], v145 offset:54272
	ds_read_b128 v[202:205], v145 offset:55296
	ds_read_b128 v[206:209], v145 offset:56320
	global_load_lds_dwordx4 v[210:211], off
	s_add_i32 m0, s36, 0x2000
	s_add_u32 s34, s34, 0x160080
	v_lshl_add_u64 v[210:211], v[212:213], 0, s[10:11]
	s_addc_u32 s35, s35, 0
	s_add_i32 s36, s66, s44
	global_load_lds_dwordx4 v[210:211], off
	v_lshl_add_u64 v[210:211], s[34:35], 0, v[130:131]
	s_mov_b32 m0, s36
	s_nop 0
	global_load_lds_dwordx4 v[210:211], off
	v_lshl_add_u64 v[210:211], s[34:35], 0, v[132:133]
	s_add_i32 m0, s36, 0x2000
	s_nop 0
	global_load_lds_dwordx4 v[210:211], off
	v_lshl_add_u64 v[210:211], v[214:215], 0, s[10:11]
	s_mov_b32 m0, s49
	s_nop 0
	global_load_lds_dwordx4 v[210:211], off
	v_lshl_add_u64 v[210:211], v[216:217], 0, s[10:11]
	s_mov_b32 m0, s50
	s_nop 0
	global_load_lds_dwordx4 v[210:211], off
	s_waitcnt vmcnt(8)
	s_waitcnt lgkmcnt(0)
	s_setprio 1
	s_barrier
	v_mfma_f32_16x16x32_bf16 v[54:57], v[146:149], v[178:181], v[54:57]
	v_mfma_f32_16x16x32_bf16 v[46:49], v[154:157], v[178:181], v[46:49]
	v_mfma_f32_16x16x32_bf16 v[38:41], v[146:149], v[186:189], v[38:41]
	v_mfma_f32_16x16x32_bf16 v[34:37], v[154:157], v[186:189], v[34:37]
	v_mfma_f32_16x16x32_bf16 v[22:25], v[146:149], v[194:197], v[22:25]
	v_mfma_f32_16x16x32_bf16 v[18:21], v[154:157], v[194:197], v[18:21]
	v_mfma_f32_16x16x32_bf16 v[6:9], v[146:149], v[202:205], v[6:9]
	v_mfma_f32_16x16x32_bf16 v[2:5], v[154:157], v[202:205], v[2:5]
	v_mfma_f32_16x16x32_bf16 v[54:57], v[150:153], v[182:185], v[54:57]
	v_mfma_f32_16x16x32_bf16 v[46:49], v[158:161], v[182:185], v[46:49]
	v_mfma_f32_16x16x32_bf16 v[38:41], v[150:153], v[190:193], v[38:41]
	v_mfma_f32_16x16x32_bf16 v[34:37], v[158:161], v[190:193], v[34:37]
	v_mfma_f32_16x16x32_bf16 v[22:25], v[150:153], v[198:201], v[22:25]
	v_mfma_f32_16x16x32_bf16 v[18:21], v[158:161], v[198:201], v[18:21]
	v_mfma_f32_16x16x32_bf16 v[6:9], v[150:153], v[206:209], v[6:9]
	v_mfma_f32_16x16x32_bf16 v[2:5], v[158:161], v[206:209], v[2:5]
	s_setprio 0
	s_setprio 1
	v_mfma_f32_16x16x32_bf16 v[30:33], v[162:165], v[178:181], v[30:33]
	v_mfma_f32_16x16x32_bf16 v[26:29], v[170:173], v[178:181], v[26:29]
	v_mfma_f32_16x16x32_bf16 v[14:17], v[162:165], v[186:189], v[14:17]
	v_mfma_f32_16x16x32_bf16 v[10:13], v[170:173], v[186:189], v[10:13]
	v_mfma_f32_16x16x32_bf16 v[58:61], v[162:165], v[194:197], v[58:61]
	v_mfma_f32_16x16x32_bf16 v[62:65], v[170:173], v[194:197], v[62:65]
	v_mfma_f32_16x16x32_bf16 v[42:45], v[162:165], v[202:205], v[42:45]
	v_mfma_f32_16x16x32_bf16 v[50:53], v[170:173], v[202:205], v[50:53]
	v_mfma_f32_16x16x32_bf16 v[30:33], v[166:169], v[182:185], v[30:33]
	v_mfma_f32_16x16x32_bf16 v[26:29], v[174:177], v[182:185], v[26:29]
	v_mfma_f32_16x16x32_bf16 v[14:17], v[166:169], v[190:193], v[14:17]
	v_mfma_f32_16x16x32_bf16 v[10:13], v[174:177], v[190:193], v[10:13]
	v_mfma_f32_16x16x32_bf16 v[58:61], v[166:169], v[198:201], v[58:61]
	v_mfma_f32_16x16x32_bf16 v[62:65], v[174:177], v[198:201], v[62:65]
	v_mfma_f32_16x16x32_bf16 v[42:45], v[166:169], v[206:209], v[42:45]
	v_mfma_f32_16x16x32_bf16 v[50:53], v[174:177], v[206:209], v[50:53]
	s_setprio 0
	s_barrier
	s_add_i32 s64, s64, 2
	s_add_u32 s26, s26, 0x100
	s_addc_u32 s27, s27, 0
	s_add_u32 s62, s62, 0x100
	s_addc_u32 s63, s63, 0
	s_cmpk_gt_u32 s64, 0x55
	s_cbranch_scc0 .LBB0_599
	s_and_b64 vcc, exec, s[12:13]
	s_cbranch_vccz .LBB0_602
	s_barrier
